# P1: the transposed V column tiles 43-46 also run as 256x256 pair blocks; pairs on 7 XCDs (3 column pairs each), singles on XCD 7 plus one tile on the workgroups with slack
# baseline (speedup 1.0000x reference)
; template <bool SWAP, class Epi>
; DI void gemm_tile(const u16* __restrict__ A, int lda, const u16* __restrict__ Bw, int ldb, int K, char* lds, Epi epi) {
;     ...
;   const int lrow = tid >> 3, lkc = tid & 7;
;   u32x4 ra0[4], rb0[2], ra1[4], rb1[2];
;   const u16* ap = A + (size_t)lrow * lda + lkc * 8;
;   const u16* bp = Bw + (size_t)lrow * ldb + lkc * 8;
;   const int nk = K >> 6;
;   auto gload = [&](int kt, u32x4* ra, u32x4* rb) {
; #pragma unroll
;     for (int j = 0; j < 4; ++j) ra[j] = *(const u32x4*)(ap + (size_t)(64 * j) * lda + kt * 64);
; #pragma unroll
;     for (int j = 0; j < 2; ++j) rb[j] = *(const u32x4*)(bp + (size_t)(64 * j) * ldb + kt * 64);
;   };
;   auto lstore = [&](int st, const u32x4* ra, const u32x4* rb) {
;     char* base = lds + st * GEMM_STAGE;
; #pragma unroll
;     for (int j = 0; j < 4; ++j) *(u32x4*)(base + ((lrow + 64 * j) * 72 + lkc * 8) * 2) = ra[j];
; #pragma unroll
;     for (int j = 0; j < 2; ++j) *(u32x4*)(base + 36864 + ((lrow + 64 * j) * 72 + lkc * 8) * 2) = rb[j];
;   };
;   auto compute = [&](int st) {
;     const char* as = lds + st * GEMM_STAGE;
;     const char* bs = as + 36864;
; #pragma unroll
;     for (int ks = 0; ks < 4; ++ks) {
;       bf16x8 af[2], bfr[2];
; #pragma unroll
;       for (int mi = 0; mi < 2; ++mi) af[mi] = *(const bf16x8*)(as + ((wm * 64 + mi * 32 + r) * 72 + ks * 16 + 8 * h) * 2);
; #pragma unroll
;       for (int ni = 0; ni < 2; ++ni) bfr[ni] = *(const bf16x8*)(bs + ((wn * 64 + ni * 32 + r) * 72 + ks * 16 + 8 * h) * 2);
; #pragma unroll
;       for (int mi = 0; mi < 2; ++mi)
; #pragma unroll
;         for (int ni = 0; ni < 2; ++ni) {
;           if (SWAP) acc[mi][ni] = MFMA32(bfr[ni], af[mi], acc[mi][ni]);
;           else acc[mi][ni] = MFMA32(af[mi], bfr[ni], acc[mi][ni]);
;         }
;     }
;   };
;   gload(0, ra0, rb0);
;   lstore(0, ra0, rb0);
;   gload(1, ra1, rb1);
;   __syncthreads();
;   for (int kt = 0; kt < nk; kt += 2) {
;     if (kt + 2 < nk) gload(kt + 2, ra0, rb0);
;     compute(0);
; DI void inproj_tile(const Params& p, int l, int mt, int nt, char* lds) {
;   const int tid = opaque_tid(), lane = tid & 63, w = tid >> 6, r = lane & 31, h = lane >> 5;
;   const int wm = w & 3, wn = w >> 2;
;   const int m0 = mt * 256;
;   const u16* A = p.Xb + (size_t)m0 * DM;
;   const u16* Bw = p.Wt_in + (size_t)(l & 1) * NIN * DM + (size_t)nt * 128 * DM;
;   if (nt < 42) {
;     float ssq = 0.f;
.LBB0_320:
	v_readlane_b32 s0, v240, 17
	v_readlane_b32 s1, v240, 18
	s_andn2_b64 vcc, exec, s[0:1]
	s_lshl_b32 s0, s38, 4
	s_lshl_b32 s50, s38, 3
	v_writelane_b32 v238, s0, 45
	s_nop 1
	v_writelane_b32 v238, s1, 46
	s_cbranch_vccnz .LBB0_370
	s_bitcmp1_b32 s38, 0
	v_readlane_b32 s4, v241, 16
	s_cselect_b32 s0, 0xc00000, 0
	s_add_u32 s18, s4, s0
	v_readlane_b32 s0, v238, 45
	v_readlane_b32 s5, v241, 17
	s_addc_u32 s19, s5, 0
	s_mov_b32 s1, s61
	s_mov_b32 s2, s0
	v_writelane_b32 v238, s2, 45
	s_lshl_b64 s[0:1], s[0:1], 2
	v_readlane_b32 s6, v241, 42
	v_writelane_b32 v238, s3, 46
	v_readlane_b32 s7, v241, 43
	v_readlane_b32 s10, v241, 46
	s_add_u32 s20, s6, s0
	s_addc_u32 s21, s7, s1
	s_lshl_b32 s22, s10, 7
	v_readlane_b32 s23, v238, 17
	v_readlane_b32 s0, v238, 16
	s_and_b32 s41, s0, 7
	s_lshr_b32 s101, s0, 3
	s_cmp_gt_u32 s41, 6
	s_cbranch_scc1 .Lpp_done
.Lpp_loop:
	s_cmpk_ge_u32 s101, 0xc6
	s_cbranch_scc1 .Lpp_done
	s_mul_i32 s0, s101, 0x5556
	s_lshr_b32 s26, s0, 16
	s_mul_i32 s0, s26, 3
	s_sub_i32 s0, s101, s0
	s_mul_i32 s0, s0, 7
	s_add_i32 s42, s0, s41
	s_lshl_b32 s1, s42, 1
	s_cmp_gt_u32 s42, 1
	s_cselect_b32 s2, 4, 0
	s_add_i32 s2, s1, s2
	s_cmp_gt_u32 s42, 18
	s_cselect_b32 s0, 1, 0
	s_add_i32 s2, s2, s0
	v_readlane_b32 s4, v241, 26
	v_readlane_b32 s5, v241, 27
	v_lshrrev_b32_e32 v0, 6, v152
	v_and_b32_e32 v1, 63, v152
	s_lshl_b32 s0, s26, 19
	s_add_u32 s4, s4, s0
	s_addc_u32 s5, s5, 0
	s_lshl_b32 s0, s2, 18
	s_add_u32 s6, s18, s0
	s_addc_u32 s7, s19, 0
	v_readfirstlane_b32 s3, v0
	s_lshl_b32 s0, s3, 16
	s_add_u32 s68, s4, s0
	s_addc_u32 s69, s5, 0
	s_add_u32 s70, s68, 0x3c00
	s_addc_u32 s71, s69, 0
	s_add_u32 s72, s70, 0x3c00
	s_addc_u32 s73, s71, 0
	s_add_u32 s74, s72, 0x3c00
	s_addc_u32 s75, s73, 0
	s_add_u32 s76, s6, s0
	s_addc_u32 s77, s7, 0
	s_add_u32 s78, s76, 0x3c00
	s_addc_u32 s79, s77, 0
	s_add_u32 s80, s78, 0x3c00
	s_addc_u32 s81, s79, 0
	s_add_u32 s82, s80, 0x3c00
	s_addc_u32 s83, s81, 0
	s_lshl_b32 s40, s3, 12
	s_add_i32 s44, s40, 0
	s_add_i32 s45, s40, 0x8000
	s_add_i32 s46, s40, 0x10000
	s_add_i32 s47, s40, 0x18000
	v_lshrrev_b32_e32 v2, 4, v1
	v_and_b32_e32 v0, 7, v1
	v_xor_b32_e32 v2, v2, v0
	v_lshlrev_b32_e32 v2, 4, v2
	v_lshrrev_b32_e32 v0, 3, v1
	v_lshlrev_b32_e32 v0, 11, v0
	v_add_u32_e32 v208, v2, v0
	v_xor_b32_e32 v209, 64, v208
	s_mov_b32 m0, s44
	s_nop 0
	global_load_lds_dwordx4 v208, s[68:69]
	global_load_lds_dwordx4 v209, s[70:71] offset:1024
	global_load_lds_dwordx4 v208, s[72:73] offset:2048
	global_load_lds_dwordx4 v209, s[74:75] offset:3072
	s_mov_b32 m0, s46
	s_nop 0
	global_load_lds_dwordx4 v208, s[76:77]
	global_load_lds_dwordx4 v209, s[78:79] offset:1024
	global_load_lds_dwordx4 v208, s[80:81] offset:2048
	global_load_lds_dwordx4 v209, s[82:83] offset:3072
	v_add_u32_e32 v208, 0x80, v208
	v_add_u32_e32 v209, 0x80, v209
	v_and_b32_e32 v0, 31, v1
	v_lshrrev_b32_e32 v2, 1, v0
	v_and_b32_e32 v2, 7, v2
	v_lshrrev_b32_e32 v1, 5, v1
	v_xor_b32_e32 v2, v2, v1
	v_lshlrev_b32_e32 v0, 7, v0
	s_and_b32 s0, s3, 3
	s_lshr_b32 s1, s3, 2
	s_lshl_b32 s10, s0, 13
	s_lshl_b32 s11, s1, 13
	s_add_i32 s11, s11, 0x10000
	v_xor_b32_e32 v214, 0, v2
	v_lshl_add_u32 v214, v214, 4, v0
	v_add_u32_e32 v210, s10, v214
	v_add_u32_e32 v214, s11, v214
	v_xor_b32_e32 v215, 2, v2
	v_lshl_add_u32 v215, v215, 4, v0
	v_add_u32_e32 v211, s10, v215
	v_add_u32_e32 v215, s11, v215
	v_xor_b32_e32 v216, 4, v2
	v_lshl_add_u32 v216, v216, 4, v0
	v_add_u32_e32 v212, s10, v216
	v_add_u32_e32 v216, s11, v216
	v_xor_b32_e32 v217, 6, v2
	v_lshl_add_u32 v217, v217, 4, v0
	v_add_u32_e32 v213, s10, v217
	v_add_u32_e32 v217, s11, v217
	v_lshrrev_b32_e32 v0, 7, v0
	s_cmp_gt_u32 s42, 18
	s_cbranch_scc1 .Lpp_T
	v_readlane_b32 s8, v241, 24
	v_readlane_b32 s9, v241, 25
	s_lshl_b32 s12, s26, 8
	s_lshl_b32 s0, s0, 6
	s_add_i32 s12, s12, s0
	v_add_u32_e32 v0, s12, v0
	v_mul_u32_u24_e32 v0, 0x2a00, v0
	s_lshl_b32 s12, s2, 8
	s_lshl_b32 s1, s1, 7
	s_add_i32 s12, s12, s1
	v_lshlrev_b32_e32 v1, 4, v1
	v_add3_u32 v218, v0, v1, s12
	v_add_u32_e32 v219, 0x54000, v218
	s_waitcnt vmcnt(0) lgkmcnt(0)
	s_barrier
	ds_read_b128 v[132:135], v210 offset:0
	ds_read_b128 v[136:139], v210 offset:4096
	ds_read_b128 v[140:143], v214 offset:0
	ds_read_b128 v[144:147], v214 offset:4096
	ds_read_b128 v[148:151], v214 offset:16384
	ds_read_b128 v[158:161], v214 offset:20480
	s_mov_b32 m0, s45
	s_nop 0
	global_load_lds_dwordx4 v208, s[68:69]
	global_load_lds_dwordx4 v209, s[70:71] offset:1024
	global_load_lds_dwordx4 v208, s[72:73] offset:2048
	global_load_lds_dwordx4 v209, s[74:75] offset:3072
	ds_read_b128 v[162:165], v211 offset:0
	ds_read_b128 v[168:171], v211 offset:4096
	ds_read_b128 v[172:175], v215 offset:0
	ds_read_b128 v[176:179], v215 offset:4096
	ds_read_b128 v[180:183], v215 offset:16384
	ds_read_b128 v[184:187], v215 offset:20480
	s_waitcnt lgkmcnt(6)
	v_mfma_f32_32x32x16_bf16 v[4:19], v[140:143], v[132:135], 0
	v_mfma_f32_32x32x16_bf16 v[68:83], v[140:143], v[136:139], 0
	v_mfma_f32_32x32x16_bf16 v[20:35], v[144:147], v[132:135], 0
	v_mfma_f32_32x32x16_bf16 v[84:99], v[144:147], v[136:139], 0
	v_mfma_f32_32x32x16_bf16 v[36:51], v[148:151], v[132:135], 0
	v_mfma_f32_32x32x16_bf16 v[100:115], v[148:151], v[136:139], 0
	v_mfma_f32_32x32x16_bf16 v[52:67], v[158:161], v[132:135], 0
	v_mfma_f32_32x32x16_bf16 v[116:131], v[158:161], v[136:139], 0
	s_mov_b32 m0, s47
	s_nop 0
	global_load_lds_dwordx4 v208, s[76:77]
	global_load_lds_dwordx4 v209, s[78:79] offset:1024
	global_load_lds_dwordx4 v208, s[80:81] offset:2048
	global_load_lds_dwordx4 v209, s[82:83] offset:3072
	v_add_u32_e32 v208, 0x80, v208
	v_add_u32_e32 v209, 0x80, v209
	ds_read_b128 v[132:135], v212 offset:0
	ds_read_b128 v[136:139], v212 offset:4096
	ds_read_b128 v[140:143], v216 offset:0
	ds_read_b128 v[144:147], v216 offset:4096
	ds_read_b128 v[148:151], v216 offset:16384
	ds_read_b128 v[158:161], v216 offset:20480
	s_waitcnt lgkmcnt(6)
; #define MFMA32(a, b, c) __builtin_amdgcn_mfma_f32_32x32x16_bf16((a), (b), (c), 0, 0, 0)
; template <bool SWAP, class Epi>
; DI void gemm_tile(const u16* __restrict__ A, int lda, const u16* __restrict__ Bw, int ldb, int K, char* lds, Epi epi) {
;     ...
;   auto compute = [&](int st) {
;     const char* as = lds + st * GEMM_STAGE;
;     const char* bs = as + 36864;
; #pragma unroll
;     for (int ks = 0; ks < 4; ++ks) {
;       bf16x8 af[2], bfr[2];
; #pragma unroll
;       for (int mi = 0; mi < 2; ++mi) af[mi] = *(const bf16x8*)(as + ((wm * 64 + mi * 32 + r) * 72 + ks * 16 + 8 * h) * 2);
; #pragma unroll
;       for (int ni = 0; ni < 2; ++ni) bfr[ni] = *(const bf16x8*)(bs + ((wn * 64 + ni * 32 + r) * 72 + ks * 16 + 8 * h) * 2);
; #pragma unroll
;       for (int mi = 0; mi < 2; ++mi)
; #pragma unroll
;         for (int ni = 0; ni < 2; ++ni) {
;           if (SWAP) acc[mi][ni] = MFMA32(bfr[ni], af[mi], acc[mi][ni]);
;           else acc[mi][ni] = MFMA32(af[mi], bfr[ni], acc[mi][ni]);
;         }
;     }
;   };
;   gload(0, ra0, rb0);
;   lstore(0, ra0, rb0);
;   gload(1, ra1, rb1);
;   __syncthreads();
;   for (int kt = 0; kt < nk; kt += 2) {
;     if (kt + 2 < nk) gload(kt + 2, ra0, rb0);
;     compute(0);
;     lstore(1, ra1, rb1);
;     __syncthreads();
;     if (kt + 3 < nk) gload(kt + 3, ra1, rb1);
;     compute(1);
;     if (kt + 2 < nk) lstore(0, ra0, rb0);
;     __syncthreads();
	v_mfma_f32_32x32x16_bf16 v[4:19], v[172:175], v[162:165], v[4:19]
	v_mfma_f32_32x32x16_bf16 v[68:83], v[172:175], v[168:171], v[68:83]
	v_mfma_f32_32x32x16_bf16 v[20:35], v[176:179], v[162:165], v[20:35]
	v_mfma_f32_32x32x16_bf16 v[84:99], v[176:179], v[168:171], v[84:99]
	v_mfma_f32_32x32x16_bf16 v[36:51], v[180:183], v[162:165], v[36:51]
	v_mfma_f32_32x32x16_bf16 v[100:115], v[180:183], v[168:171], v[100:115]
	v_mfma_f32_32x32x16_bf16 v[52:67], v[184:187], v[162:165], v[52:67]
	v_mfma_f32_32x32x16_bf16 v[116:131], v[184:187], v[168:171], v[116:131]
	ds_read_b128 v[162:165], v213 offset:0
	ds_read_b128 v[168:171], v213 offset:4096
	ds_read_b128 v[172:175], v217 offset:0
	ds_read_b128 v[176:179], v217 offset:4096
	ds_read_b128 v[180:183], v217 offset:16384
	ds_read_b128 v[184:187], v217 offset:20480
	s_waitcnt lgkmcnt(6)
	v_mfma_f32_32x32x16_bf16 v[4:19], v[140:143], v[132:135], v[4:19]
	v_mfma_f32_32x32x16_bf16 v[68:83], v[140:143], v[136:139], v[68:83]
	v_mfma_f32_32x32x16_bf16 v[20:35], v[144:147], v[132:135], v[20:35]
	v_mfma_f32_32x32x16_bf16 v[84:99], v[144:147], v[136:139], v[84:99]
	v_mfma_f32_32x32x16_bf16 v[36:51], v[148:151], v[132:135], v[36:51]
	v_mfma_f32_32x32x16_bf16 v[100:115], v[148:151], v[136:139], v[100:115]
	v_mfma_f32_32x32x16_bf16 v[52:67], v[158:161], v[132:135], v[52:67]
	v_mfma_f32_32x32x16_bf16 v[116:131], v[158:161], v[136:139], v[116:131]
	s_waitcnt lgkmcnt(0)
	v_mfma_f32_32x32x16_bf16 v[4:19], v[172:175], v[162:165], v[4:19]
	v_mfma_f32_32x32x16_bf16 v[68:83], v[172:175], v[168:171], v[68:83]
	v_mfma_f32_32x32x16_bf16 v[20:35], v[176:179], v[162:165], v[20:35]
	v_mfma_f32_32x32x16_bf16 v[84:99], v[176:179], v[168:171], v[84:99]
	v_mfma_f32_32x32x16_bf16 v[36:51], v[180:183], v[162:165], v[36:51]
	v_mfma_f32_32x32x16_bf16 v[100:115], v[180:183], v[168:171], v[100:115]
	v_mfma_f32_32x32x16_bf16 v[52:67], v[184:187], v[162:165], v[52:67]
	v_mfma_f32_32x32x16_bf16 v[116:131], v[184:187], v[168:171], v[116:131]
	s_waitcnt vmcnt(0) lgkmcnt(0)
	s_barrier
	ds_read_b128 v[132:135], v210 offset:32768
	ds_read_b128 v[136:139], v210 offset:36864
	ds_read_b128 v[140:143], v214 offset:32768
	ds_read_b128 v[144:147], v214 offset:36864
	ds_read_b128 v[148:151], v214 offset:49152
	ds_read_b128 v[158:161], v214 offset:53248
	s_mov_b32 m0, s44
	s_nop 0
	global_load_lds_dwordx4 v208, s[68:69]
	global_load_lds_dwordx4 v209, s[70:71] offset:1024
	global_load_lds_dwordx4 v208, s[72:73] offset:2048
	global_load_lds_dwordx4 v209, s[74:75] offset:3072
	ds_read_b128 v[162:165], v211 offset:32768
	ds_read_b128 v[168:171], v211 offset:36864
	ds_read_b128 v[172:175], v215 offset:32768
	ds_read_b128 v[176:179], v215 offset:36864
	ds_read_b128 v[180:183], v215 offset:49152
	ds_read_b128 v[184:187], v215 offset:53248
	s_waitcnt lgkmcnt(6)
	v_mfma_f32_32x32x16_bf16 v[4:19], v[140:143], v[132:135], v[4:19]
	v_mfma_f32_32x32x16_bf16 v[68:83], v[140:143], v[136:139], v[68:83]
	v_mfma_f32_32x32x16_bf16 v[20:35], v[144:147], v[132:135], v[20:35]
	v_mfma_f32_32x32x16_bf16 v[84:99], v[144:147], v[136:139], v[84:99]
	v_mfma_f32_32x32x16_bf16 v[36:51], v[148:151], v[132:135], v[36:51]
	v_mfma_f32_32x32x16_bf16 v[100:115], v[148:151], v[136:139], v[100:115]
	v_mfma_f32_32x32x16_bf16 v[52:67], v[158:161], v[132:135], v[52:67]
	v_mfma_f32_32x32x16_bf16 v[116:131], v[158:161], v[136:139], v[116:131]
	s_mov_b32 m0, s46
	s_nop 0
	global_load_lds_dwordx4 v208, s[76:77]
	global_load_lds_dwordx4 v209, s[78:79] offset:1024
	global_load_lds_dwordx4 v208, s[80:81] offset:2048
	global_load_lds_dwordx4 v209, s[82:83] offset:3072
	v_add_u32_e32 v208, 0x80, v208
	v_add_u32_e32 v209, 0x80, v209
	ds_read_b128 v[132:135], v212 offset:32768
	ds_read_b128 v[136:139], v212 offset:36864
	ds_read_b128 v[140:143], v216 offset:32768
	ds_read_b128 v[144:147], v216 offset:36864
	ds_read_b128 v[148:151], v216 offset:49152
	ds_read_b128 v[158:161], v216 offset:53248
	s_waitcnt lgkmcnt(6)
	v_mfma_f32_32x32x16_bf16 v[4:19], v[172:175], v[162:165], v[4:19]
	v_mfma_f32_32x32x16_bf16 v[68:83], v[172:175], v[168:171], v[68:83]
	v_mfma_f32_32x32x16_bf16 v[20:35], v[176:179], v[162:165], v[20:35]
	v_mfma_f32_32x32x16_bf16 v[84:99], v[176:179], v[168:171], v[84:99]
	v_mfma_f32_32x32x16_bf16 v[36:51], v[180:183], v[162:165], v[36:51]
	v_mfma_f32_32x32x16_bf16 v[100:115], v[180:183], v[168:171], v[100:115]
	v_mfma_f32_32x32x16_bf16 v[52:67], v[184:187], v[162:165], v[52:67]
	v_mfma_f32_32x32x16_bf16 v[116:131], v[184:187], v[168:171], v[116:131]
	ds_read_b128 v[162:165], v213 offset:32768
	ds_read_b128 v[168:171], v213 offset:36864
	ds_read_b128 v[172:175], v217 offset:32768
	ds_read_b128 v[176:179], v217 offset:36864
	ds_read_b128 v[180:183], v217 offset:49152
	ds_read_b128 v[184:187], v217 offset:53248
	s_waitcnt lgkmcnt(6)
	v_mfma_f32_32x32x16_bf16 v[4:19], v[140:143], v[132:135], v[4:19]
	v_mfma_f32_32x32x16_bf16 v[68:83], v[140:143], v[136:139], v[68:83]
	v_mfma_f32_32x32x16_bf16 v[20:35], v[144:147], v[132:135], v[20:35]
	v_mfma_f32_32x32x16_bf16 v[84:99], v[144:147], v[136:139], v[84:99]
	v_mfma_f32_32x32x16_bf16 v[36:51], v[148:151], v[132:135], v[36:51]
	v_mfma_f32_32x32x16_bf16 v[100:115], v[148:151], v[136:139], v[100:115]
	v_mfma_f32_32x32x16_bf16 v[52:67], v[158:161], v[132:135], v[52:67]
	v_mfma_f32_32x32x16_bf16 v[116:131], v[158:161], v[136:139], v[116:131]
	s_waitcnt lgkmcnt(0)
	v_mfma_f32_32x32x16_bf16 v[4:19], v[172:175], v[162:165], v[4:19]
	v_mfma_f32_32x32x16_bf16 v[68:83], v[172:175], v[168:171], v[68:83]
	v_mfma_f32_32x32x16_bf16 v[20:35], v[176:179], v[162:165], v[20:35]
	v_mfma_f32_32x32x16_bf16 v[84:99], v[176:179], v[168:171], v[84:99]
	v_mfma_f32_32x32x16_bf16 v[36:51], v[180:183], v[162:165], v[36:51]
	v_mfma_f32_32x32x16_bf16 v[100:115], v[180:183], v[168:171], v[100:115]
	v_mfma_f32_32x32x16_bf16 v[52:67], v[184:187], v[162:165], v[52:67]
	v_mfma_f32_32x32x16_bf16 v[116:131], v[184:187], v[168:171], v[116:131]
	s_waitcnt vmcnt(0) lgkmcnt(0)
	s_barrier
; #define MFMA32(a, b, c) __builtin_amdgcn_mfma_f32_32x32x16_bf16((a), (b), (c), 0, 0, 0)
; template <bool SWAP, class Epi>
; DI void gemm_tile(const u16* __restrict__ A, int lda, const u16* __restrict__ Bw, int ldb, int K, char* lds, Epi epi) {
;     ...
;   auto compute = [&](int st) {
;     const char* as = lds + st * GEMM_STAGE;
;     const char* bs = as + 36864;
; #pragma unroll
;     for (int ks = 0; ks < 4; ++ks) {
;       bf16x8 af[2], bfr[2];
; #pragma unroll
;       for (int mi = 0; mi < 2; ++mi) af[mi] = *(const bf16x8*)(as + ((wm * 64 + mi * 32 + r) * 72 + ks * 16 + 8 * h) * 2);
; #pragma unroll
;       for (int ni = 0; ni < 2; ++ni) bfr[ni] = *(const bf16x8*)(bs + ((wn * 64 + ni * 32 + r) * 72 + ks * 16 + 8 * h) * 2);
; #pragma unroll
;       for (int mi = 0; mi < 2; ++mi)
; #pragma unroll
;         for (int ni = 0; ni < 2; ++ni) {
;           if (SWAP) acc[mi][ni] = MFMA32(bfr[ni], af[mi], acc[mi][ni]);
;           else acc[mi][ni] = MFMA32(af[mi], bfr[ni], acc[mi][ni]);
;         }
;     }
;   };
;   gload(0, ra0, rb0);
;   lstore(0, ra0, rb0);
;   gload(1, ra1, rb1);
;   __syncthreads();
;   for (int kt = 0; kt < nk; kt += 2) {
;     if (kt + 2 < nk) gload(kt + 2, ra0, rb0);
;     compute(0);
;     lstore(1, ra1, rb1);
;     __syncthreads();
;     if (kt + 3 < nk) gload(kt + 3, ra1, rb1);
;     compute(1);
;     if (kt + 2 < nk) lstore(0, ra0, rb0);
;     __syncthreads();
	ds_read_b128 v[132:135], v210 offset:0
	ds_read_b128 v[136:139], v210 offset:4096
	ds_read_b128 v[140:143], v214 offset:0
	ds_read_b128 v[144:147], v214 offset:4096
	ds_read_b128 v[148:151], v214 offset:16384
	ds_read_b128 v[158:161], v214 offset:20480
	s_mov_b32 m0, s45
	s_nop 0
	global_load_lds_dwordx4 v208, s[68:69]
	global_load_lds_dwordx4 v209, s[70:71] offset:1024
	global_load_lds_dwordx4 v208, s[72:73] offset:2048
	global_load_lds_dwordx4 v209, s[74:75] offset:3072
	ds_read_b128 v[162:165], v211 offset:0
	ds_read_b128 v[168:171], v211 offset:4096
	ds_read_b128 v[172:175], v215 offset:0
	ds_read_b128 v[176:179], v215 offset:4096
	ds_read_b128 v[180:183], v215 offset:16384
	ds_read_b128 v[184:187], v215 offset:20480
	s_waitcnt lgkmcnt(6)
	v_mfma_f32_32x32x16_bf16 v[4:19], v[140:143], v[132:135], v[4:19]
	v_mfma_f32_32x32x16_bf16 v[68:83], v[140:143], v[136:139], v[68:83]
	v_mfma_f32_32x32x16_bf16 v[20:35], v[144:147], v[132:135], v[20:35]
	v_mfma_f32_32x32x16_bf16 v[84:99], v[144:147], v[136:139], v[84:99]
	v_mfma_f32_32x32x16_bf16 v[36:51], v[148:151], v[132:135], v[36:51]
	v_mfma_f32_32x32x16_bf16 v[100:115], v[148:151], v[136:139], v[100:115]
	v_mfma_f32_32x32x16_bf16 v[52:67], v[158:161], v[132:135], v[52:67]
	v_mfma_f32_32x32x16_bf16 v[116:131], v[158:161], v[136:139], v[116:131]
	s_mov_b32 m0, s47
	s_nop 0
	global_load_lds_dwordx4 v208, s[76:77]
	global_load_lds_dwordx4 v209, s[78:79] offset:1024
	global_load_lds_dwordx4 v208, s[80:81] offset:2048
	global_load_lds_dwordx4 v209, s[82:83] offset:3072
	v_add_u32_e32 v208, 0x80, v208
	v_add_u32_e32 v209, 0x80, v209
	ds_read_b128 v[132:135], v212 offset:0
	ds_read_b128 v[136:139], v212 offset:4096
	ds_read_b128 v[140:143], v216 offset:0
	ds_read_b128 v[144:147], v216 offset:4096
	ds_read_b128 v[148:151], v216 offset:16384
	ds_read_b128 v[158:161], v216 offset:20480
	s_waitcnt lgkmcnt(6)
	v_mfma_f32_32x32x16_bf16 v[4:19], v[172:175], v[162:165], v[4:19]
	v_mfma_f32_32x32x16_bf16 v[68:83], v[172:175], v[168:171], v[68:83]
	v_mfma_f32_32x32x16_bf16 v[20:35], v[176:179], v[162:165], v[20:35]
	v_mfma_f32_32x32x16_bf16 v[84:99], v[176:179], v[168:171], v[84:99]
	v_mfma_f32_32x32x16_bf16 v[36:51], v[180:183], v[162:165], v[36:51]
	v_mfma_f32_32x32x16_bf16 v[100:115], v[180:183], v[168:171], v[100:115]
	v_mfma_f32_32x32x16_bf16 v[52:67], v[184:187], v[162:165], v[52:67]
	v_mfma_f32_32x32x16_bf16 v[116:131], v[184:187], v[168:171], v[116:131]
	ds_read_b128 v[162:165], v213 offset:0
	ds_read_b128 v[168:171], v213 offset:4096
	ds_read_b128 v[172:175], v217 offset:0
	ds_read_b128 v[176:179], v217 offset:4096
	ds_read_b128 v[180:183], v217 offset:16384
	ds_read_b128 v[184:187], v217 offset:20480
	s_waitcnt lgkmcnt(6)
	v_mfma_f32_32x32x16_bf16 v[4:19], v[140:143], v[132:135], v[4:19]
	v_mfma_f32_32x32x16_bf16 v[68:83], v[140:143], v[136:139], v[68:83]
	v_mfma_f32_32x32x16_bf16 v[20:35], v[144:147], v[132:135], v[20:35]
	v_mfma_f32_32x32x16_bf16 v[84:99], v[144:147], v[136:139], v[84:99]
	v_mfma_f32_32x32x16_bf16 v[36:51], v[148:151], v[132:135], v[36:51]
	v_mfma_f32_32x32x16_bf16 v[100:115], v[148:151], v[136:139], v[100:115]
	v_mfma_f32_32x32x16_bf16 v[52:67], v[158:161], v[132:135], v[52:67]
	v_mfma_f32_32x32x16_bf16 v[116:131], v[158:161], v[136:139], v[116:131]
	s_waitcnt lgkmcnt(0)
	v_mfma_f32_32x32x16_bf16 v[4:19], v[172:175], v[162:165], v[4:19]
	v_mfma_f32_32x32x16_bf16 v[68:83], v[172:175], v[168:171], v[68:83]
	v_mfma_f32_32x32x16_bf16 v[20:35], v[176:179], v[162:165], v[20:35]
	v_mfma_f32_32x32x16_bf16 v[84:99], v[176:179], v[168:171], v[84:99]
	v_mfma_f32_32x32x16_bf16 v[36:51], v[180:183], v[162:165], v[36:51]
	v_mfma_f32_32x32x16_bf16 v[100:115], v[180:183], v[168:171], v[100:115]
	v_mfma_f32_32x32x16_bf16 v[52:67], v[184:187], v[162:165], v[52:67]
	v_mfma_f32_32x32x16_bf16 v[116:131], v[184:187], v[168:171], v[116:131]
	s_waitcnt vmcnt(0) lgkmcnt(0)
	s_barrier
	ds_read_b128 v[132:135], v210 offset:32768
	ds_read_b128 v[136:139], v210 offset:36864
	ds_read_b128 v[140:143], v214 offset:32768
	ds_read_b128 v[144:147], v214 offset:36864
	ds_read_b128 v[148:151], v214 offset:49152
	ds_read_b128 v[158:161], v214 offset:53248
	s_mov_b32 m0, s44
	s_nop 0
	global_load_lds_dwordx4 v208, s[68:69]
	global_load_lds_dwordx4 v209, s[70:71] offset:1024
	global_load_lds_dwordx4 v208, s[72:73] offset:2048
	global_load_lds_dwordx4 v209, s[74:75] offset:3072
	ds_read_b128 v[162:165], v211 offset:32768
	ds_read_b128 v[168:171], v211 offset:36864
	ds_read_b128 v[172:175], v215 offset:32768
	ds_read_b128 v[176:179], v215 offset:36864
	ds_read_b128 v[180:183], v215 offset:49152
	ds_read_b128 v[184:187], v215 offset:53248
	s_waitcnt lgkmcnt(6)
	v_mfma_f32_32x32x16_bf16 v[4:19], v[140:143], v[132:135], v[4:19]
	v_mfma_f32_32x32x16_bf16 v[68:83], v[140:143], v[136:139], v[68:83]
	v_mfma_f32_32x32x16_bf16 v[20:35], v[144:147], v[132:135], v[20:35]
	v_mfma_f32_32x32x16_bf16 v[84:99], v[144:147], v[136:139], v[84:99]
	v_mfma_f32_32x32x16_bf16 v[36:51], v[148:151], v[132:135], v[36:51]
	v_mfma_f32_32x32x16_bf16 v[100:115], v[148:151], v[136:139], v[100:115]
	v_mfma_f32_32x32x16_bf16 v[52:67], v[158:161], v[132:135], v[52:67]
	v_mfma_f32_32x32x16_bf16 v[116:131], v[158:161], v[136:139], v[116:131]
	s_mov_b32 m0, s46
	s_nop 0
	global_load_lds_dwordx4 v208, s[76:77]
	global_load_lds_dwordx4 v209, s[78:79] offset:1024
	global_load_lds_dwordx4 v208, s[80:81] offset:2048
	global_load_lds_dwordx4 v209, s[82:83] offset:3072
	v_add_u32_e32 v208, 0x80, v208
	v_add_u32_e32 v209, 0x80, v209
	ds_read_b128 v[132:135], v212 offset:32768
	ds_read_b128 v[136:139], v212 offset:36864
	ds_read_b128 v[140:143], v216 offset:32768
	ds_read_b128 v[144:147], v216 offset:36864
	ds_read_b128 v[148:151], v216 offset:49152
	ds_read_b128 v[158:161], v216 offset:53248
	s_waitcnt lgkmcnt(6)
; #define MFMA32(a, b, c) __builtin_amdgcn_mfma_f32_32x32x16_bf16((a), (b), (c), 0, 0, 0)
; template <bool SWAP, class Epi>
; DI void gemm_tile(const u16* __restrict__ A, int lda, const u16* __restrict__ Bw, int ldb, int K, char* lds, Epi epi) {
;     ...
;   auto compute = [&](int st) {
;     const char* as = lds + st * GEMM_STAGE;
;     const char* bs = as + 36864;
; #pragma unroll
;     for (int ks = 0; ks < 4; ++ks) {
;       bf16x8 af[2], bfr[2];
; #pragma unroll
;       for (int mi = 0; mi < 2; ++mi) af[mi] = *(const bf16x8*)(as + ((wm * 64 + mi * 32 + r) * 72 + ks * 16 + 8 * h) * 2);
; #pragma unroll
;       for (int ni = 0; ni < 2; ++ni) bfr[ni] = *(const bf16x8*)(bs + ((wn * 64 + ni * 32 + r) * 72 + ks * 16 + 8 * h) * 2);
; #pragma unroll
;       for (int mi = 0; mi < 2; ++mi)
; #pragma unroll
;         for (int ni = 0; ni < 2; ++ni) {
;           if (SWAP) acc[mi][ni] = MFMA32(bfr[ni], af[mi], acc[mi][ni]);
;           else acc[mi][ni] = MFMA32(af[mi], bfr[ni], acc[mi][ni]);
;         }
;     }
;   };
;   gload(0, ra0, rb0);
;   lstore(0, ra0, rb0);
;   gload(1, ra1, rb1);
;   __syncthreads();
;   for (int kt = 0; kt < nk; kt += 2) {
;     if (kt + 2 < nk) gload(kt + 2, ra0, rb0);
;     compute(0);
;     lstore(1, ra1, rb1);
;     __syncthreads();
;     if (kt + 3 < nk) gload(kt + 3, ra1, rb1);
;     compute(1);
;     if (kt + 2 < nk) lstore(0, ra0, rb0);
;     __syncthreads();
	v_mfma_f32_32x32x16_bf16 v[4:19], v[172:175], v[162:165], v[4:19]
	v_mfma_f32_32x32x16_bf16 v[68:83], v[172:175], v[168:171], v[68:83]
	v_mfma_f32_32x32x16_bf16 v[20:35], v[176:179], v[162:165], v[20:35]
	v_mfma_f32_32x32x16_bf16 v[84:99], v[176:179], v[168:171], v[84:99]
	v_mfma_f32_32x32x16_bf16 v[36:51], v[180:183], v[162:165], v[36:51]
	v_mfma_f32_32x32x16_bf16 v[100:115], v[180:183], v[168:171], v[100:115]
	v_mfma_f32_32x32x16_bf16 v[52:67], v[184:187], v[162:165], v[52:67]
	v_mfma_f32_32x32x16_bf16 v[116:131], v[184:187], v[168:171], v[116:131]
	ds_read_b128 v[162:165], v213 offset:32768
	ds_read_b128 v[168:171], v213 offset:36864
	ds_read_b128 v[172:175], v217 offset:32768
	ds_read_b128 v[176:179], v217 offset:36864
	ds_read_b128 v[180:183], v217 offset:49152
	ds_read_b128 v[184:187], v217 offset:53248
	s_waitcnt lgkmcnt(6)
	v_mfma_f32_32x32x16_bf16 v[4:19], v[140:143], v[132:135], v[4:19]
	v_mfma_f32_32x32x16_bf16 v[68:83], v[140:143], v[136:139], v[68:83]
	v_mfma_f32_32x32x16_bf16 v[20:35], v[144:147], v[132:135], v[20:35]
	v_mfma_f32_32x32x16_bf16 v[84:99], v[144:147], v[136:139], v[84:99]
	v_mfma_f32_32x32x16_bf16 v[36:51], v[148:151], v[132:135], v[36:51]
	v_mfma_f32_32x32x16_bf16 v[100:115], v[148:151], v[136:139], v[100:115]
	v_mfma_f32_32x32x16_bf16 v[52:67], v[158:161], v[132:135], v[52:67]
	v_mfma_f32_32x32x16_bf16 v[116:131], v[158:161], v[136:139], v[116:131]
	s_waitcnt lgkmcnt(0)
	v_mfma_f32_32x32x16_bf16 v[4:19], v[172:175], v[162:165], v[4:19]
	v_mfma_f32_32x32x16_bf16 v[68:83], v[172:175], v[168:171], v[68:83]
	v_mfma_f32_32x32x16_bf16 v[20:35], v[176:179], v[162:165], v[20:35]
	v_mfma_f32_32x32x16_bf16 v[84:99], v[176:179], v[168:171], v[84:99]
	v_mfma_f32_32x32x16_bf16 v[36:51], v[180:183], v[162:165], v[36:51]
	v_mfma_f32_32x32x16_bf16 v[100:115], v[180:183], v[168:171], v[100:115]
	v_mfma_f32_32x32x16_bf16 v[52:67], v[184:187], v[162:165], v[52:67]
	v_mfma_f32_32x32x16_bf16 v[116:131], v[184:187], v[168:171], v[116:131]
	s_waitcnt vmcnt(0) lgkmcnt(0)
	s_barrier
	ds_read_b128 v[132:135], v210 offset:0
	ds_read_b128 v[136:139], v210 offset:4096
	ds_read_b128 v[140:143], v214 offset:0
	ds_read_b128 v[144:147], v214 offset:4096
	ds_read_b128 v[148:151], v214 offset:16384
	ds_read_b128 v[158:161], v214 offset:20480
	s_mov_b32 m0, s45
	s_nop 0
	global_load_lds_dwordx4 v208, s[68:69]
	global_load_lds_dwordx4 v209, s[70:71] offset:1024
	global_load_lds_dwordx4 v208, s[72:73] offset:2048
	global_load_lds_dwordx4 v209, s[74:75] offset:3072
	ds_read_b128 v[162:165], v211 offset:0
	ds_read_b128 v[168:171], v211 offset:4096
	ds_read_b128 v[172:175], v215 offset:0
	ds_read_b128 v[176:179], v215 offset:4096
	ds_read_b128 v[180:183], v215 offset:16384
	ds_read_b128 v[184:187], v215 offset:20480
	s_waitcnt lgkmcnt(6)
	v_mfma_f32_32x32x16_bf16 v[4:19], v[140:143], v[132:135], v[4:19]
	v_mfma_f32_32x32x16_bf16 v[68:83], v[140:143], v[136:139], v[68:83]
	v_mfma_f32_32x32x16_bf16 v[20:35], v[144:147], v[132:135], v[20:35]
	v_mfma_f32_32x32x16_bf16 v[84:99], v[144:147], v[136:139], v[84:99]
	v_mfma_f32_32x32x16_bf16 v[36:51], v[148:151], v[132:135], v[36:51]
	v_mfma_f32_32x32x16_bf16 v[100:115], v[148:151], v[136:139], v[100:115]
	v_mfma_f32_32x32x16_bf16 v[52:67], v[158:161], v[132:135], v[52:67]
	v_mfma_f32_32x32x16_bf16 v[116:131], v[158:161], v[136:139], v[116:131]
	s_mov_b32 m0, s47
	s_nop 0
	global_load_lds_dwordx4 v208, s[76:77]
	global_load_lds_dwordx4 v209, s[78:79] offset:1024
	global_load_lds_dwordx4 v208, s[80:81] offset:2048
	global_load_lds_dwordx4 v209, s[82:83] offset:3072
	v_add_u32_e32 v208, 0x80, v208
	v_add_u32_e32 v209, 0x80, v209
	ds_read_b128 v[132:135], v212 offset:0
	ds_read_b128 v[136:139], v212 offset:4096
	ds_read_b128 v[140:143], v216 offset:0
	ds_read_b128 v[144:147], v216 offset:4096
	ds_read_b128 v[148:151], v216 offset:16384
	ds_read_b128 v[158:161], v216 offset:20480
	s_waitcnt lgkmcnt(6)
	v_mfma_f32_32x32x16_bf16 v[4:19], v[172:175], v[162:165], v[4:19]
	v_mfma_f32_32x32x16_bf16 v[68:83], v[172:175], v[168:171], v[68:83]
	v_mfma_f32_32x32x16_bf16 v[20:35], v[176:179], v[162:165], v[20:35]
	v_mfma_f32_32x32x16_bf16 v[84:99], v[176:179], v[168:171], v[84:99]
	v_mfma_f32_32x32x16_bf16 v[36:51], v[180:183], v[162:165], v[36:51]
	v_mfma_f32_32x32x16_bf16 v[100:115], v[180:183], v[168:171], v[100:115]
	v_mfma_f32_32x32x16_bf16 v[52:67], v[184:187], v[162:165], v[52:67]
	v_mfma_f32_32x32x16_bf16 v[116:131], v[184:187], v[168:171], v[116:131]
	ds_read_b128 v[162:165], v213 offset:0
	ds_read_b128 v[168:171], v213 offset:4096
	ds_read_b128 v[172:175], v217 offset:0
	ds_read_b128 v[176:179], v217 offset:4096
	ds_read_b128 v[180:183], v217 offset:16384
	ds_read_b128 v[184:187], v217 offset:20480
	s_waitcnt lgkmcnt(6)
	v_mfma_f32_32x32x16_bf16 v[4:19], v[140:143], v[132:135], v[4:19]
	v_mfma_f32_32x32x16_bf16 v[68:83], v[140:143], v[136:139], v[68:83]
	v_mfma_f32_32x32x16_bf16 v[20:35], v[144:147], v[132:135], v[20:35]
	v_mfma_f32_32x32x16_bf16 v[84:99], v[144:147], v[136:139], v[84:99]
	v_mfma_f32_32x32x16_bf16 v[36:51], v[148:151], v[132:135], v[36:51]
	v_mfma_f32_32x32x16_bf16 v[100:115], v[148:151], v[136:139], v[100:115]
	v_mfma_f32_32x32x16_bf16 v[52:67], v[158:161], v[132:135], v[52:67]
	v_mfma_f32_32x32x16_bf16 v[116:131], v[158:161], v[136:139], v[116:131]
	s_waitcnt lgkmcnt(0)
	v_mfma_f32_32x32x16_bf16 v[4:19], v[172:175], v[162:165], v[4:19]
	v_mfma_f32_32x32x16_bf16 v[68:83], v[172:175], v[168:171], v[68:83]
	v_mfma_f32_32x32x16_bf16 v[20:35], v[176:179], v[162:165], v[20:35]
	v_mfma_f32_32x32x16_bf16 v[84:99], v[176:179], v[168:171], v[84:99]
	v_mfma_f32_32x32x16_bf16 v[36:51], v[180:183], v[162:165], v[36:51]
	v_mfma_f32_32x32x16_bf16 v[100:115], v[180:183], v[168:171], v[100:115]
	v_mfma_f32_32x32x16_bf16 v[52:67], v[184:187], v[162:165], v[52:67]
	v_mfma_f32_32x32x16_bf16 v[116:131], v[184:187], v[168:171], v[116:131]
	s_waitcnt vmcnt(0) lgkmcnt(0)
	s_barrier
; #define MFMA32(a, b, c) __builtin_amdgcn_mfma_f32_32x32x16_bf16((a), (b), (c), 0, 0, 0)
; template <bool SWAP, class Epi>
; DI void gemm_tile(const u16* __restrict__ A, int lda, const u16* __restrict__ Bw, int ldb, int K, char* lds, Epi epi) {
;     ...
;   auto compute = [&](int st) {
;     const char* as = lds + st * GEMM_STAGE;
;     const char* bs = as + 36864;
; #pragma unroll
;     for (int ks = 0; ks < 4; ++ks) {
;       bf16x8 af[2], bfr[2];
; #pragma unroll
;       for (int mi = 0; mi < 2; ++mi) af[mi] = *(const bf16x8*)(as + ((wm * 64 + mi * 32 + r) * 72 + ks * 16 + 8 * h) * 2);
; #pragma unroll
;       for (int ni = 0; ni < 2; ++ni) bfr[ni] = *(const bf16x8*)(bs + ((wn * 64 + ni * 32 + r) * 72 + ks * 16 + 8 * h) * 2);
; #pragma unroll
;       for (int mi = 0; mi < 2; ++mi)
; #pragma unroll
;         for (int ni = 0; ni < 2; ++ni) {
;           if (SWAP) acc[mi][ni] = MFMA32(bfr[ni], af[mi], acc[mi][ni]);
;           else acc[mi][ni] = MFMA32(af[mi], bfr[ni], acc[mi][ni]);
;         }
;     }
;   };
;   gload(0, ra0, rb0);
;   lstore(0, ra0, rb0);
;   gload(1, ra1, rb1);
;   __syncthreads();
;   for (int kt = 0; kt < nk; kt += 2) {
;     if (kt + 2 < nk) gload(kt + 2, ra0, rb0);
;     compute(0);
;     lstore(1, ra1, rb1);
;     __syncthreads();
;     if (kt + 3 < nk) gload(kt + 3, ra1, rb1);
;     compute(1);
;     if (kt + 2 < nk) lstore(0, ra0, rb0);
;     __syncthreads();
	ds_read_b128 v[132:135], v210 offset:32768
	ds_read_b128 v[136:139], v210 offset:36864
	ds_read_b128 v[140:143], v214 offset:32768
	ds_read_b128 v[144:147], v214 offset:36864
	ds_read_b128 v[148:151], v214 offset:49152
	ds_read_b128 v[158:161], v214 offset:53248
	s_mov_b32 m0, s44
	s_nop 0
	global_load_lds_dwordx4 v208, s[68:69]
	global_load_lds_dwordx4 v209, s[70:71] offset:1024
	global_load_lds_dwordx4 v208, s[72:73] offset:2048
	global_load_lds_dwordx4 v209, s[74:75] offset:3072
	ds_read_b128 v[162:165], v211 offset:32768
	ds_read_b128 v[168:171], v211 offset:36864
	ds_read_b128 v[172:175], v215 offset:32768
	ds_read_b128 v[176:179], v215 offset:36864
	ds_read_b128 v[180:183], v215 offset:49152
	ds_read_b128 v[184:187], v215 offset:53248
	s_waitcnt lgkmcnt(6)
	v_mfma_f32_32x32x16_bf16 v[4:19], v[140:143], v[132:135], v[4:19]
	v_mfma_f32_32x32x16_bf16 v[68:83], v[140:143], v[136:139], v[68:83]
	v_mfma_f32_32x32x16_bf16 v[20:35], v[144:147], v[132:135], v[20:35]
	v_mfma_f32_32x32x16_bf16 v[84:99], v[144:147], v[136:139], v[84:99]
	v_mfma_f32_32x32x16_bf16 v[36:51], v[148:151], v[132:135], v[36:51]
	v_mfma_f32_32x32x16_bf16 v[100:115], v[148:151], v[136:139], v[100:115]
	v_mfma_f32_32x32x16_bf16 v[52:67], v[158:161], v[132:135], v[52:67]
	v_mfma_f32_32x32x16_bf16 v[116:131], v[158:161], v[136:139], v[116:131]
	s_mov_b32 m0, s46
	s_nop 0
	global_load_lds_dwordx4 v208, s[76:77]
	global_load_lds_dwordx4 v209, s[78:79] offset:1024
	global_load_lds_dwordx4 v208, s[80:81] offset:2048
	global_load_lds_dwordx4 v209, s[82:83] offset:3072
	v_add_u32_e32 v208, 0x80, v208
	v_add_u32_e32 v209, 0x80, v209
	ds_read_b128 v[132:135], v212 offset:32768
	ds_read_b128 v[136:139], v212 offset:36864
	ds_read_b128 v[140:143], v216 offset:32768
	ds_read_b128 v[144:147], v216 offset:36864
	ds_read_b128 v[148:151], v216 offset:49152
	ds_read_b128 v[158:161], v216 offset:53248
	s_waitcnt lgkmcnt(6)
	v_mfma_f32_32x32x16_bf16 v[4:19], v[172:175], v[162:165], v[4:19]
	v_mfma_f32_32x32x16_bf16 v[68:83], v[172:175], v[168:171], v[68:83]
	v_mfma_f32_32x32x16_bf16 v[20:35], v[176:179], v[162:165], v[20:35]
	v_mfma_f32_32x32x16_bf16 v[84:99], v[176:179], v[168:171], v[84:99]
	v_mfma_f32_32x32x16_bf16 v[36:51], v[180:183], v[162:165], v[36:51]
	v_mfma_f32_32x32x16_bf16 v[100:115], v[180:183], v[168:171], v[100:115]
	v_mfma_f32_32x32x16_bf16 v[52:67], v[184:187], v[162:165], v[52:67]
	v_mfma_f32_32x32x16_bf16 v[116:131], v[184:187], v[168:171], v[116:131]
	ds_read_b128 v[162:165], v213 offset:32768
	ds_read_b128 v[168:171], v213 offset:36864
	ds_read_b128 v[172:175], v217 offset:32768
	ds_read_b128 v[176:179], v217 offset:36864
	ds_read_b128 v[180:183], v217 offset:49152
	ds_read_b128 v[184:187], v217 offset:53248
	s_waitcnt lgkmcnt(6)
	v_mfma_f32_32x32x16_bf16 v[4:19], v[140:143], v[132:135], v[4:19]
	v_mfma_f32_32x32x16_bf16 v[68:83], v[140:143], v[136:139], v[68:83]
	v_mfma_f32_32x32x16_bf16 v[20:35], v[144:147], v[132:135], v[20:35]
	v_mfma_f32_32x32x16_bf16 v[84:99], v[144:147], v[136:139], v[84:99]
	v_mfma_f32_32x32x16_bf16 v[36:51], v[148:151], v[132:135], v[36:51]
	v_mfma_f32_32x32x16_bf16 v[100:115], v[148:151], v[136:139], v[100:115]
	v_mfma_f32_32x32x16_bf16 v[52:67], v[158:161], v[132:135], v[52:67]
	v_mfma_f32_32x32x16_bf16 v[116:131], v[158:161], v[136:139], v[116:131]
	s_waitcnt lgkmcnt(0)
	v_mfma_f32_32x32x16_bf16 v[4:19], v[172:175], v[162:165], v[4:19]
	v_mfma_f32_32x32x16_bf16 v[68:83], v[172:175], v[168:171], v[68:83]
	v_mfma_f32_32x32x16_bf16 v[20:35], v[176:179], v[162:165], v[20:35]
	v_mfma_f32_32x32x16_bf16 v[84:99], v[176:179], v[168:171], v[84:99]
	v_mfma_f32_32x32x16_bf16 v[36:51], v[180:183], v[162:165], v[36:51]
	v_mfma_f32_32x32x16_bf16 v[100:115], v[180:183], v[168:171], v[100:115]
	v_mfma_f32_32x32x16_bf16 v[52:67], v[184:187], v[162:165], v[52:67]
	v_mfma_f32_32x32x16_bf16 v[116:131], v[184:187], v[168:171], v[116:131]
	s_waitcnt vmcnt(0) lgkmcnt(0)
	s_barrier
	ds_read_b128 v[132:135], v210 offset:0
	ds_read_b128 v[136:139], v210 offset:4096
	ds_read_b128 v[140:143], v214 offset:0
	ds_read_b128 v[144:147], v214 offset:4096
	ds_read_b128 v[148:151], v214 offset:16384
	ds_read_b128 v[158:161], v214 offset:20480
	s_mov_b32 m0, s45
	s_nop 0
	global_load_lds_dwordx4 v208, s[68:69]
	global_load_lds_dwordx4 v209, s[70:71] offset:1024
	global_load_lds_dwordx4 v208, s[72:73] offset:2048
	global_load_lds_dwordx4 v209, s[74:75] offset:3072
	ds_read_b128 v[162:165], v211 offset:0
	ds_read_b128 v[168:171], v211 offset:4096
	ds_read_b128 v[172:175], v215 offset:0
	ds_read_b128 v[176:179], v215 offset:4096
	ds_read_b128 v[180:183], v215 offset:16384
	ds_read_b128 v[184:187], v215 offset:20480
	s_waitcnt lgkmcnt(6)
	v_mfma_f32_32x32x16_bf16 v[4:19], v[140:143], v[132:135], v[4:19]
	v_mfma_f32_32x32x16_bf16 v[68:83], v[140:143], v[136:139], v[68:83]
	v_mfma_f32_32x32x16_bf16 v[20:35], v[144:147], v[132:135], v[20:35]
	v_mfma_f32_32x32x16_bf16 v[84:99], v[144:147], v[136:139], v[84:99]
	v_mfma_f32_32x32x16_bf16 v[36:51], v[148:151], v[132:135], v[36:51]
	v_mfma_f32_32x32x16_bf16 v[100:115], v[148:151], v[136:139], v[100:115]
	v_mfma_f32_32x32x16_bf16 v[52:67], v[158:161], v[132:135], v[52:67]
	v_mfma_f32_32x32x16_bf16 v[116:131], v[158:161], v[136:139], v[116:131]
	s_mov_b32 m0, s47
	s_nop 0
	global_load_lds_dwordx4 v208, s[76:77]
	global_load_lds_dwordx4 v209, s[78:79] offset:1024
	global_load_lds_dwordx4 v208, s[80:81] offset:2048
	global_load_lds_dwordx4 v209, s[82:83] offset:3072
	v_add_u32_e32 v208, 0x80, v208
	v_add_u32_e32 v209, 0x80, v209
	ds_read_b128 v[132:135], v212 offset:0
	ds_read_b128 v[136:139], v212 offset:4096
	ds_read_b128 v[140:143], v216 offset:0
	ds_read_b128 v[144:147], v216 offset:4096
	ds_read_b128 v[148:151], v216 offset:16384
	ds_read_b128 v[158:161], v216 offset:20480
	s_waitcnt lgkmcnt(6)
; #define MFMA32(a, b, c) __builtin_amdgcn_mfma_f32_32x32x16_bf16((a), (b), (c), 0, 0, 0)
; template <bool SWAP, class Epi>
; DI void gemm_tile(const u16* __restrict__ A, int lda, const u16* __restrict__ Bw, int ldb, int K, char* lds, Epi epi) {
;     ...
;   auto compute = [&](int st) {
;     const char* as = lds + st * GEMM_STAGE;
;     const char* bs = as + 36864;
; #pragma unroll
;     for (int ks = 0; ks < 4; ++ks) {
;       bf16x8 af[2], bfr[2];
; #pragma unroll
;       for (int mi = 0; mi < 2; ++mi) af[mi] = *(const bf16x8*)(as + ((wm * 64 + mi * 32 + r) * 72 + ks * 16 + 8 * h) * 2);
; #pragma unroll
;       for (int ni = 0; ni < 2; ++ni) bfr[ni] = *(const bf16x8*)(bs + ((wn * 64 + ni * 32 + r) * 72 + ks * 16 + 8 * h) * 2);
; #pragma unroll
;       for (int mi = 0; mi < 2; ++mi)
; #pragma unroll
;         for (int ni = 0; ni < 2; ++ni) {
;           if (SWAP) acc[mi][ni] = MFMA32(bfr[ni], af[mi], acc[mi][ni]);
;           else acc[mi][ni] = MFMA32(af[mi], bfr[ni], acc[mi][ni]);
;         }
;     }
;   };
;   gload(0, ra0, rb0);
;   lstore(0, ra0, rb0);
;   gload(1, ra1, rb1);
;   __syncthreads();
;   for (int kt = 0; kt < nk; kt += 2) {
;     if (kt + 2 < nk) gload(kt + 2, ra0, rb0);
;     compute(0);
;     lstore(1, ra1, rb1);
;     __syncthreads();
;     if (kt + 3 < nk) gload(kt + 3, ra1, rb1);
;     compute(1);
;     if (kt + 2 < nk) lstore(0, ra0, rb0);
;     __syncthreads();
	v_mfma_f32_32x32x16_bf16 v[4:19], v[172:175], v[162:165], v[4:19]
	v_mfma_f32_32x32x16_bf16 v[68:83], v[172:175], v[168:171], v[68:83]
	v_mfma_f32_32x32x16_bf16 v[20:35], v[176:179], v[162:165], v[20:35]
	v_mfma_f32_32x32x16_bf16 v[84:99], v[176:179], v[168:171], v[84:99]
	v_mfma_f32_32x32x16_bf16 v[36:51], v[180:183], v[162:165], v[36:51]
	v_mfma_f32_32x32x16_bf16 v[100:115], v[180:183], v[168:171], v[100:115]
	v_mfma_f32_32x32x16_bf16 v[52:67], v[184:187], v[162:165], v[52:67]
	v_mfma_f32_32x32x16_bf16 v[116:131], v[184:187], v[168:171], v[116:131]
	ds_read_b128 v[162:165], v213 offset:0
	ds_read_b128 v[168:171], v213 offset:4096
	ds_read_b128 v[172:175], v217 offset:0
	ds_read_b128 v[176:179], v217 offset:4096
	ds_read_b128 v[180:183], v217 offset:16384
	ds_read_b128 v[184:187], v217 offset:20480
	s_waitcnt lgkmcnt(6)
	v_mfma_f32_32x32x16_bf16 v[4:19], v[140:143], v[132:135], v[4:19]
	v_mfma_f32_32x32x16_bf16 v[68:83], v[140:143], v[136:139], v[68:83]
	v_mfma_f32_32x32x16_bf16 v[20:35], v[144:147], v[132:135], v[20:35]
	v_mfma_f32_32x32x16_bf16 v[84:99], v[144:147], v[136:139], v[84:99]
	v_mfma_f32_32x32x16_bf16 v[36:51], v[148:151], v[132:135], v[36:51]
	v_mfma_f32_32x32x16_bf16 v[100:115], v[148:151], v[136:139], v[100:115]
	v_mfma_f32_32x32x16_bf16 v[52:67], v[158:161], v[132:135], v[52:67]
	v_mfma_f32_32x32x16_bf16 v[116:131], v[158:161], v[136:139], v[116:131]
	s_waitcnt lgkmcnt(0)
	v_mfma_f32_32x32x16_bf16 v[4:19], v[172:175], v[162:165], v[4:19]
	v_mfma_f32_32x32x16_bf16 v[68:83], v[172:175], v[168:171], v[68:83]
	v_mfma_f32_32x32x16_bf16 v[20:35], v[176:179], v[162:165], v[20:35]
	v_mfma_f32_32x32x16_bf16 v[84:99], v[176:179], v[168:171], v[84:99]
	v_mfma_f32_32x32x16_bf16 v[36:51], v[180:183], v[162:165], v[36:51]
	v_mfma_f32_32x32x16_bf16 v[100:115], v[180:183], v[168:171], v[100:115]
	v_mfma_f32_32x32x16_bf16 v[52:67], v[184:187], v[162:165], v[52:67]
	v_mfma_f32_32x32x16_bf16 v[116:131], v[184:187], v[168:171], v[116:131]
	s_waitcnt vmcnt(0) lgkmcnt(0)
	s_barrier
	ds_read_b128 v[132:135], v210 offset:32768
	ds_read_b128 v[136:139], v210 offset:36864
	ds_read_b128 v[140:143], v214 offset:32768
	ds_read_b128 v[144:147], v214 offset:36864
	ds_read_b128 v[148:151], v214 offset:49152
	ds_read_b128 v[158:161], v214 offset:53248
	s_mov_b32 m0, s44
	s_nop 0
	global_load_lds_dwordx4 v208, s[68:69]
	global_load_lds_dwordx4 v209, s[70:71] offset:1024
	global_load_lds_dwordx4 v208, s[72:73] offset:2048
	global_load_lds_dwordx4 v209, s[74:75] offset:3072
	ds_read_b128 v[162:165], v211 offset:32768
	ds_read_b128 v[168:171], v211 offset:36864
	ds_read_b128 v[172:175], v215 offset:32768
	ds_read_b128 v[176:179], v215 offset:36864
	ds_read_b128 v[180:183], v215 offset:49152
	ds_read_b128 v[184:187], v215 offset:53248
	s_waitcnt lgkmcnt(6)
	v_mfma_f32_32x32x16_bf16 v[4:19], v[140:143], v[132:135], v[4:19]
	v_mfma_f32_32x32x16_bf16 v[68:83], v[140:143], v[136:139], v[68:83]
	v_mfma_f32_32x32x16_bf16 v[20:35], v[144:147], v[132:135], v[20:35]
	v_mfma_f32_32x32x16_bf16 v[84:99], v[144:147], v[136:139], v[84:99]
	v_mfma_f32_32x32x16_bf16 v[36:51], v[148:151], v[132:135], v[36:51]
	v_mfma_f32_32x32x16_bf16 v[100:115], v[148:151], v[136:139], v[100:115]
	v_mfma_f32_32x32x16_bf16 v[52:67], v[158:161], v[132:135], v[52:67]
	v_mfma_f32_32x32x16_bf16 v[116:131], v[158:161], v[136:139], v[116:131]
	s_mov_b32 m0, s46
	s_nop 0
	global_load_lds_dwordx4 v208, s[76:77]
	global_load_lds_dwordx4 v209, s[78:79] offset:1024
	global_load_lds_dwordx4 v208, s[80:81] offset:2048
	global_load_lds_dwordx4 v209, s[82:83] offset:3072
	v_add_u32_e32 v208, 0x80, v208
	v_add_u32_e32 v209, 0x80, v209
	ds_read_b128 v[132:135], v212 offset:32768
	ds_read_b128 v[136:139], v212 offset:36864
	ds_read_b128 v[140:143], v216 offset:32768
	ds_read_b128 v[144:147], v216 offset:36864
	ds_read_b128 v[148:151], v216 offset:49152
	ds_read_b128 v[158:161], v216 offset:53248
	s_waitcnt lgkmcnt(6)
	v_mfma_f32_32x32x16_bf16 v[4:19], v[172:175], v[162:165], v[4:19]
	v_mfma_f32_32x32x16_bf16 v[68:83], v[172:175], v[168:171], v[68:83]
	v_mfma_f32_32x32x16_bf16 v[20:35], v[176:179], v[162:165], v[20:35]
	v_mfma_f32_32x32x16_bf16 v[84:99], v[176:179], v[168:171], v[84:99]
	v_mfma_f32_32x32x16_bf16 v[36:51], v[180:183], v[162:165], v[36:51]
	v_mfma_f32_32x32x16_bf16 v[100:115], v[180:183], v[168:171], v[100:115]
	v_mfma_f32_32x32x16_bf16 v[52:67], v[184:187], v[162:165], v[52:67]
	v_mfma_f32_32x32x16_bf16 v[116:131], v[184:187], v[168:171], v[116:131]
	ds_read_b128 v[162:165], v213 offset:32768
	ds_read_b128 v[168:171], v213 offset:36864
	ds_read_b128 v[172:175], v217 offset:32768
	ds_read_b128 v[176:179], v217 offset:36864
	ds_read_b128 v[180:183], v217 offset:49152
	ds_read_b128 v[184:187], v217 offset:53248
	s_waitcnt lgkmcnt(6)
	v_mfma_f32_32x32x16_bf16 v[4:19], v[140:143], v[132:135], v[4:19]
	v_mfma_f32_32x32x16_bf16 v[68:83], v[140:143], v[136:139], v[68:83]
	v_mfma_f32_32x32x16_bf16 v[20:35], v[144:147], v[132:135], v[20:35]
	v_mfma_f32_32x32x16_bf16 v[84:99], v[144:147], v[136:139], v[84:99]
	v_mfma_f32_32x32x16_bf16 v[36:51], v[148:151], v[132:135], v[36:51]
	v_mfma_f32_32x32x16_bf16 v[100:115], v[148:151], v[136:139], v[100:115]
	v_mfma_f32_32x32x16_bf16 v[52:67], v[158:161], v[132:135], v[52:67]
	v_mfma_f32_32x32x16_bf16 v[116:131], v[158:161], v[136:139], v[116:131]
	s_waitcnt lgkmcnt(0)
	v_mfma_f32_32x32x16_bf16 v[4:19], v[172:175], v[162:165], v[4:19]
	v_mfma_f32_32x32x16_bf16 v[68:83], v[172:175], v[168:171], v[68:83]
	v_mfma_f32_32x32x16_bf16 v[20:35], v[176:179], v[162:165], v[20:35]
	v_mfma_f32_32x32x16_bf16 v[84:99], v[176:179], v[168:171], v[84:99]
	v_mfma_f32_32x32x16_bf16 v[36:51], v[180:183], v[162:165], v[36:51]
	v_mfma_f32_32x32x16_bf16 v[100:115], v[180:183], v[168:171], v[100:115]
	v_mfma_f32_32x32x16_bf16 v[52:67], v[184:187], v[162:165], v[52:67]
	v_mfma_f32_32x32x16_bf16 v[116:131], v[184:187], v[168:171], v[116:131]
	s_waitcnt vmcnt(0) lgkmcnt(0)
	s_barrier
; #define MFMA32(a, b, c) __builtin_amdgcn_mfma_f32_32x32x16_bf16((a), (b), (c), 0, 0, 0)
; template <bool SWAP, class Epi>
; DI void gemm_tile(const u16* __restrict__ A, int lda, const u16* __restrict__ Bw, int ldb, int K, char* lds, Epi epi) {
;     ...
;   auto compute = [&](int st) {
;     const char* as = lds + st * GEMM_STAGE;
;     const char* bs = as + 36864;
; #pragma unroll
;     for (int ks = 0; ks < 4; ++ks) {
;       bf16x8 af[2], bfr[2];
; #pragma unroll
;       for (int mi = 0; mi < 2; ++mi) af[mi] = *(const bf16x8*)(as + ((wm * 64 + mi * 32 + r) * 72 + ks * 16 + 8 * h) * 2);
; #pragma unroll
;       for (int ni = 0; ni < 2; ++ni) bfr[ni] = *(const bf16x8*)(bs + ((wn * 64 + ni * 32 + r) * 72 + ks * 16 + 8 * h) * 2);
; #pragma unroll
;       for (int mi = 0; mi < 2; ++mi)
; #pragma unroll
;         for (int ni = 0; ni < 2; ++ni) {
;           if (SWAP) acc[mi][ni] = MFMA32(bfr[ni], af[mi], acc[mi][ni]);
;           else acc[mi][ni] = MFMA32(af[mi], bfr[ni], acc[mi][ni]);
;         }
;     }
;   };
;   gload(0, ra0, rb0);
;   lstore(0, ra0, rb0);
;   gload(1, ra1, rb1);
;   __syncthreads();
;   for (int kt = 0; kt < nk; kt += 2) {
;     if (kt + 2 < nk) gload(kt + 2, ra0, rb0);
;     compute(0);
;     lstore(1, ra1, rb1);
;     __syncthreads();
;     if (kt + 3 < nk) gload(kt + 3, ra1, rb1);
;     compute(1);
;     if (kt + 2 < nk) lstore(0, ra0, rb0);
;     __syncthreads();
	ds_read_b128 v[132:135], v210 offset:0
	ds_read_b128 v[136:139], v210 offset:4096
	ds_read_b128 v[140:143], v214 offset:0
	ds_read_b128 v[144:147], v214 offset:4096
	ds_read_b128 v[148:151], v214 offset:16384
	ds_read_b128 v[158:161], v214 offset:20480
	s_mov_b32 m0, s45
	s_nop 0
	global_load_lds_dwordx4 v208, s[68:69]
	global_load_lds_dwordx4 v209, s[70:71] offset:1024
	global_load_lds_dwordx4 v208, s[72:73] offset:2048
	global_load_lds_dwordx4 v209, s[74:75] offset:3072
	ds_read_b128 v[162:165], v211 offset:0
	ds_read_b128 v[168:171], v211 offset:4096
	ds_read_b128 v[172:175], v215 offset:0
	ds_read_b128 v[176:179], v215 offset:4096
	ds_read_b128 v[180:183], v215 offset:16384
	ds_read_b128 v[184:187], v215 offset:20480
	s_waitcnt lgkmcnt(6)
	v_mfma_f32_32x32x16_bf16 v[4:19], v[140:143], v[132:135], v[4:19]
	v_mfma_f32_32x32x16_bf16 v[68:83], v[140:143], v[136:139], v[68:83]
	v_mfma_f32_32x32x16_bf16 v[20:35], v[144:147], v[132:135], v[20:35]
	v_mfma_f32_32x32x16_bf16 v[84:99], v[144:147], v[136:139], v[84:99]
	v_mfma_f32_32x32x16_bf16 v[36:51], v[148:151], v[132:135], v[36:51]
	v_mfma_f32_32x32x16_bf16 v[100:115], v[148:151], v[136:139], v[100:115]
	v_mfma_f32_32x32x16_bf16 v[52:67], v[158:161], v[132:135], v[52:67]
	v_mfma_f32_32x32x16_bf16 v[116:131], v[158:161], v[136:139], v[116:131]
	s_mov_b32 m0, s47
	s_nop 0
	global_load_lds_dwordx4 v208, s[76:77]
	global_load_lds_dwordx4 v209, s[78:79] offset:1024
	global_load_lds_dwordx4 v208, s[80:81] offset:2048
	global_load_lds_dwordx4 v209, s[82:83] offset:3072
	v_add_u32_e32 v208, 0x80, v208
	v_add_u32_e32 v209, 0x80, v209
	ds_read_b128 v[132:135], v212 offset:0
	ds_read_b128 v[136:139], v212 offset:4096
	ds_read_b128 v[140:143], v216 offset:0
	ds_read_b128 v[144:147], v216 offset:4096
	ds_read_b128 v[148:151], v216 offset:16384
	ds_read_b128 v[158:161], v216 offset:20480
	s_waitcnt lgkmcnt(6)
	v_mfma_f32_32x32x16_bf16 v[4:19], v[172:175], v[162:165], v[4:19]
	v_mfma_f32_32x32x16_bf16 v[68:83], v[172:175], v[168:171], v[68:83]
	v_mfma_f32_32x32x16_bf16 v[20:35], v[176:179], v[162:165], v[20:35]
	v_mfma_f32_32x32x16_bf16 v[84:99], v[176:179], v[168:171], v[84:99]
	v_mfma_f32_32x32x16_bf16 v[36:51], v[180:183], v[162:165], v[36:51]
	v_mfma_f32_32x32x16_bf16 v[100:115], v[180:183], v[168:171], v[100:115]
	v_mfma_f32_32x32x16_bf16 v[52:67], v[184:187], v[162:165], v[52:67]
	v_mfma_f32_32x32x16_bf16 v[116:131], v[184:187], v[168:171], v[116:131]
	ds_read_b128 v[162:165], v213 offset:0
	ds_read_b128 v[168:171], v213 offset:4096
	ds_read_b128 v[172:175], v217 offset:0
	ds_read_b128 v[176:179], v217 offset:4096
	ds_read_b128 v[180:183], v217 offset:16384
	ds_read_b128 v[184:187], v217 offset:20480
	s_waitcnt lgkmcnt(6)
	v_mfma_f32_32x32x16_bf16 v[4:19], v[140:143], v[132:135], v[4:19]
	v_mfma_f32_32x32x16_bf16 v[68:83], v[140:143], v[136:139], v[68:83]
	v_mfma_f32_32x32x16_bf16 v[20:35], v[144:147], v[132:135], v[20:35]
	v_mfma_f32_32x32x16_bf16 v[84:99], v[144:147], v[136:139], v[84:99]
	v_mfma_f32_32x32x16_bf16 v[36:51], v[148:151], v[132:135], v[36:51]
	v_mfma_f32_32x32x16_bf16 v[100:115], v[148:151], v[136:139], v[100:115]
	v_mfma_f32_32x32x16_bf16 v[52:67], v[158:161], v[132:135], v[52:67]
	v_mfma_f32_32x32x16_bf16 v[116:131], v[158:161], v[136:139], v[116:131]
	s_waitcnt lgkmcnt(0)
	v_mfma_f32_32x32x16_bf16 v[4:19], v[172:175], v[162:165], v[4:19]
	v_mfma_f32_32x32x16_bf16 v[68:83], v[172:175], v[168:171], v[68:83]
	v_mfma_f32_32x32x16_bf16 v[20:35], v[176:179], v[162:165], v[20:35]
	v_mfma_f32_32x32x16_bf16 v[84:99], v[176:179], v[168:171], v[84:99]
	v_mfma_f32_32x32x16_bf16 v[36:51], v[180:183], v[162:165], v[36:51]
	v_mfma_f32_32x32x16_bf16 v[100:115], v[180:183], v[168:171], v[100:115]
	v_mfma_f32_32x32x16_bf16 v[52:67], v[184:187], v[162:165], v[52:67]
	v_mfma_f32_32x32x16_bf16 v[116:131], v[184:187], v[168:171], v[116:131]
	s_waitcnt vmcnt(0) lgkmcnt(0)
	s_barrier
	ds_read_b128 v[132:135], v210 offset:32768
	ds_read_b128 v[136:139], v210 offset:36864
	ds_read_b128 v[140:143], v214 offset:32768
	ds_read_b128 v[144:147], v214 offset:36864
	ds_read_b128 v[148:151], v214 offset:49152
	ds_read_b128 v[158:161], v214 offset:53248
	s_mov_b32 m0, s44
	s_nop 0
	global_load_lds_dwordx4 v208, s[68:69]
	global_load_lds_dwordx4 v209, s[70:71] offset:1024
	global_load_lds_dwordx4 v208, s[72:73] offset:2048
	global_load_lds_dwordx4 v209, s[74:75] offset:3072
	ds_read_b128 v[162:165], v211 offset:32768
	ds_read_b128 v[168:171], v211 offset:36864
	ds_read_b128 v[172:175], v215 offset:32768
	ds_read_b128 v[176:179], v215 offset:36864
	ds_read_b128 v[180:183], v215 offset:49152
	ds_read_b128 v[184:187], v215 offset:53248
	s_waitcnt lgkmcnt(6)
	v_mfma_f32_32x32x16_bf16 v[4:19], v[140:143], v[132:135], v[4:19]
	v_mfma_f32_32x32x16_bf16 v[68:83], v[140:143], v[136:139], v[68:83]
	v_mfma_f32_32x32x16_bf16 v[20:35], v[144:147], v[132:135], v[20:35]
	v_mfma_f32_32x32x16_bf16 v[84:99], v[144:147], v[136:139], v[84:99]
	v_mfma_f32_32x32x16_bf16 v[36:51], v[148:151], v[132:135], v[36:51]
	v_mfma_f32_32x32x16_bf16 v[100:115], v[148:151], v[136:139], v[100:115]
	v_mfma_f32_32x32x16_bf16 v[52:67], v[158:161], v[132:135], v[52:67]
	v_mfma_f32_32x32x16_bf16 v[116:131], v[158:161], v[136:139], v[116:131]
	s_mov_b32 m0, s46
	s_nop 0
	global_load_lds_dwordx4 v208, s[76:77]
	global_load_lds_dwordx4 v209, s[78:79] offset:1024
	global_load_lds_dwordx4 v208, s[80:81] offset:2048
	global_load_lds_dwordx4 v209, s[82:83] offset:3072
	v_add_u32_e32 v208, 0x80, v208
	v_add_u32_e32 v209, 0x80, v209
	ds_read_b128 v[132:135], v212 offset:32768
	ds_read_b128 v[136:139], v212 offset:36864
	ds_read_b128 v[140:143], v216 offset:32768
	ds_read_b128 v[144:147], v216 offset:36864
	ds_read_b128 v[148:151], v216 offset:49152
	ds_read_b128 v[158:161], v216 offset:53248
	s_waitcnt lgkmcnt(6)
; #define MFMA32(a, b, c) __builtin_amdgcn_mfma_f32_32x32x16_bf16((a), (b), (c), 0, 0, 0)
; template <bool SWAP, class Epi>
; DI void gemm_tile(const u16* __restrict__ A, int lda, const u16* __restrict__ Bw, int ldb, int K, char* lds, Epi epi) {
;     ...
;   auto compute = [&](int st) {
;     const char* as = lds + st * GEMM_STAGE;
;     const char* bs = as + 36864;
; #pragma unroll
;     for (int ks = 0; ks < 4; ++ks) {
;       bf16x8 af[2], bfr[2];
; #pragma unroll
;       for (int mi = 0; mi < 2; ++mi) af[mi] = *(const bf16x8*)(as + ((wm * 64 + mi * 32 + r) * 72 + ks * 16 + 8 * h) * 2);
; #pragma unroll
;       for (int ni = 0; ni < 2; ++ni) bfr[ni] = *(const bf16x8*)(bs + ((wn * 64 + ni * 32 + r) * 72 + ks * 16 + 8 * h) * 2);
; #pragma unroll
;       for (int mi = 0; mi < 2; ++mi)
; #pragma unroll
;         for (int ni = 0; ni < 2; ++ni) {
;           if (SWAP) acc[mi][ni] = MFMA32(bfr[ni], af[mi], acc[mi][ni]);
;           else acc[mi][ni] = MFMA32(af[mi], bfr[ni], acc[mi][ni]);
;         }
;     }
;   };
;   gload(0, ra0, rb0);
;   lstore(0, ra0, rb0);
;   gload(1, ra1, rb1);
;   __syncthreads();
;   for (int kt = 0; kt < nk; kt += 2) {
;     if (kt + 2 < nk) gload(kt + 2, ra0, rb0);
;     compute(0);
;     lstore(1, ra1, rb1);
;     __syncthreads();
;     if (kt + 3 < nk) gload(kt + 3, ra1, rb1);
;     compute(1);
;     if (kt + 2 < nk) lstore(0, ra0, rb0);
;     __syncthreads();
	v_mfma_f32_32x32x16_bf16 v[4:19], v[172:175], v[162:165], v[4:19]
	v_mfma_f32_32x32x16_bf16 v[68:83], v[172:175], v[168:171], v[68:83]
	v_mfma_f32_32x32x16_bf16 v[20:35], v[176:179], v[162:165], v[20:35]
	v_mfma_f32_32x32x16_bf16 v[84:99], v[176:179], v[168:171], v[84:99]
	v_mfma_f32_32x32x16_bf16 v[36:51], v[180:183], v[162:165], v[36:51]
	v_mfma_f32_32x32x16_bf16 v[100:115], v[180:183], v[168:171], v[100:115]
	v_mfma_f32_32x32x16_bf16 v[52:67], v[184:187], v[162:165], v[52:67]
	v_mfma_f32_32x32x16_bf16 v[116:131], v[184:187], v[168:171], v[116:131]
	ds_read_b128 v[162:165], v213 offset:32768
	ds_read_b128 v[168:171], v213 offset:36864
	ds_read_b128 v[172:175], v217 offset:32768
	ds_read_b128 v[176:179], v217 offset:36864
	ds_read_b128 v[180:183], v217 offset:49152
	ds_read_b128 v[184:187], v217 offset:53248
	s_waitcnt lgkmcnt(6)
	v_mfma_f32_32x32x16_bf16 v[4:19], v[140:143], v[132:135], v[4:19]
	v_mfma_f32_32x32x16_bf16 v[68:83], v[140:143], v[136:139], v[68:83]
	v_mfma_f32_32x32x16_bf16 v[20:35], v[144:147], v[132:135], v[20:35]
	v_mfma_f32_32x32x16_bf16 v[84:99], v[144:147], v[136:139], v[84:99]
	v_mfma_f32_32x32x16_bf16 v[36:51], v[148:151], v[132:135], v[36:51]
	v_mfma_f32_32x32x16_bf16 v[100:115], v[148:151], v[136:139], v[100:115]
	v_mfma_f32_32x32x16_bf16 v[52:67], v[158:161], v[132:135], v[52:67]
	v_mfma_f32_32x32x16_bf16 v[116:131], v[158:161], v[136:139], v[116:131]
	s_waitcnt lgkmcnt(0)
	v_mfma_f32_32x32x16_bf16 v[4:19], v[172:175], v[162:165], v[4:19]
	v_mfma_f32_32x32x16_bf16 v[68:83], v[172:175], v[168:171], v[68:83]
	v_mfma_f32_32x32x16_bf16 v[20:35], v[176:179], v[162:165], v[20:35]
	v_mfma_f32_32x32x16_bf16 v[84:99], v[176:179], v[168:171], v[84:99]
	v_mfma_f32_32x32x16_bf16 v[36:51], v[180:183], v[162:165], v[36:51]
	v_mfma_f32_32x32x16_bf16 v[100:115], v[180:183], v[168:171], v[100:115]
	v_mfma_f32_32x32x16_bf16 v[52:67], v[184:187], v[162:165], v[52:67]
	v_mfma_f32_32x32x16_bf16 v[116:131], v[184:187], v[168:171], v[116:131]
	s_waitcnt vmcnt(0) lgkmcnt(0)
	s_barrier
	ds_read_b128 v[132:135], v210 offset:0
	ds_read_b128 v[136:139], v210 offset:4096
	ds_read_b128 v[140:143], v214 offset:0
	ds_read_b128 v[144:147], v214 offset:4096
	ds_read_b128 v[148:151], v214 offset:16384
	ds_read_b128 v[158:161], v214 offset:20480
	s_mov_b32 m0, s45
	s_nop 0
	global_load_lds_dwordx4 v208, s[68:69]
	global_load_lds_dwordx4 v209, s[70:71] offset:1024
	global_load_lds_dwordx4 v208, s[72:73] offset:2048
	global_load_lds_dwordx4 v209, s[74:75] offset:3072
	ds_read_b128 v[162:165], v211 offset:0
	ds_read_b128 v[168:171], v211 offset:4096
	ds_read_b128 v[172:175], v215 offset:0
	ds_read_b128 v[176:179], v215 offset:4096
	ds_read_b128 v[180:183], v215 offset:16384
	ds_read_b128 v[184:187], v215 offset:20480
	s_waitcnt lgkmcnt(6)
	v_mfma_f32_32x32x16_bf16 v[4:19], v[140:143], v[132:135], v[4:19]
	v_mfma_f32_32x32x16_bf16 v[68:83], v[140:143], v[136:139], v[68:83]
	v_mfma_f32_32x32x16_bf16 v[20:35], v[144:147], v[132:135], v[20:35]
	v_mfma_f32_32x32x16_bf16 v[84:99], v[144:147], v[136:139], v[84:99]
	v_mfma_f32_32x32x16_bf16 v[36:51], v[148:151], v[132:135], v[36:51]
	v_mfma_f32_32x32x16_bf16 v[100:115], v[148:151], v[136:139], v[100:115]
	v_mfma_f32_32x32x16_bf16 v[52:67], v[158:161], v[132:135], v[52:67]
	v_mfma_f32_32x32x16_bf16 v[116:131], v[158:161], v[136:139], v[116:131]
	s_mov_b32 m0, s47
	s_nop 0
	global_load_lds_dwordx4 v208, s[76:77]
	global_load_lds_dwordx4 v209, s[78:79] offset:1024
	global_load_lds_dwordx4 v208, s[80:81] offset:2048
	global_load_lds_dwordx4 v209, s[82:83] offset:3072
	v_add_u32_e32 v208, 0x80, v208
	v_add_u32_e32 v209, 0x80, v209
	ds_read_b128 v[132:135], v212 offset:0
	ds_read_b128 v[136:139], v212 offset:4096
	ds_read_b128 v[140:143], v216 offset:0
	ds_read_b128 v[144:147], v216 offset:4096
	ds_read_b128 v[148:151], v216 offset:16384
	ds_read_b128 v[158:161], v216 offset:20480
	s_waitcnt lgkmcnt(6)
	v_mfma_f32_32x32x16_bf16 v[4:19], v[172:175], v[162:165], v[4:19]
	v_mfma_f32_32x32x16_bf16 v[68:83], v[172:175], v[168:171], v[68:83]
	v_mfma_f32_32x32x16_bf16 v[20:35], v[176:179], v[162:165], v[20:35]
	v_mfma_f32_32x32x16_bf16 v[84:99], v[176:179], v[168:171], v[84:99]
	v_mfma_f32_32x32x16_bf16 v[36:51], v[180:183], v[162:165], v[36:51]
	v_mfma_f32_32x32x16_bf16 v[100:115], v[180:183], v[168:171], v[100:115]
	v_mfma_f32_32x32x16_bf16 v[52:67], v[184:187], v[162:165], v[52:67]
	v_mfma_f32_32x32x16_bf16 v[116:131], v[184:187], v[168:171], v[116:131]
	ds_read_b128 v[162:165], v213 offset:0
	ds_read_b128 v[168:171], v213 offset:4096
	ds_read_b128 v[172:175], v217 offset:0
	ds_read_b128 v[176:179], v217 offset:4096
	ds_read_b128 v[180:183], v217 offset:16384
	ds_read_b128 v[184:187], v217 offset:20480
	s_waitcnt lgkmcnt(6)
	v_mfma_f32_32x32x16_bf16 v[4:19], v[140:143], v[132:135], v[4:19]
	v_mfma_f32_32x32x16_bf16 v[68:83], v[140:143], v[136:139], v[68:83]
	v_mfma_f32_32x32x16_bf16 v[20:35], v[144:147], v[132:135], v[20:35]
	v_mfma_f32_32x32x16_bf16 v[84:99], v[144:147], v[136:139], v[84:99]
	v_mfma_f32_32x32x16_bf16 v[36:51], v[148:151], v[132:135], v[36:51]
	v_mfma_f32_32x32x16_bf16 v[100:115], v[148:151], v[136:139], v[100:115]
	v_mfma_f32_32x32x16_bf16 v[52:67], v[158:161], v[132:135], v[52:67]
	v_mfma_f32_32x32x16_bf16 v[116:131], v[158:161], v[136:139], v[116:131]
	s_waitcnt lgkmcnt(0)
	v_mfma_f32_32x32x16_bf16 v[4:19], v[172:175], v[162:165], v[4:19]
	v_mfma_f32_32x32x16_bf16 v[68:83], v[172:175], v[168:171], v[68:83]
	v_mfma_f32_32x32x16_bf16 v[20:35], v[176:179], v[162:165], v[20:35]
	v_mfma_f32_32x32x16_bf16 v[84:99], v[176:179], v[168:171], v[84:99]
	v_mfma_f32_32x32x16_bf16 v[36:51], v[180:183], v[162:165], v[36:51]
	v_mfma_f32_32x32x16_bf16 v[100:115], v[180:183], v[168:171], v[100:115]
	v_mfma_f32_32x32x16_bf16 v[52:67], v[184:187], v[162:165], v[52:67]
	v_mfma_f32_32x32x16_bf16 v[116:131], v[184:187], v[168:171], v[116:131]
	s_waitcnt vmcnt(0) lgkmcnt(0)
	s_barrier
; #define MFMA32(a, b, c) __builtin_amdgcn_mfma_f32_32x32x16_bf16((a), (b), (c), 0, 0, 0)
; template <bool SWAP, class Epi>
; DI void gemm_tile(const u16* __restrict__ A, int lda, const u16* __restrict__ Bw, int ldb, int K, char* lds, Epi epi) {
;     ...
;   auto compute = [&](int st) {
;     const char* as = lds + st * GEMM_STAGE;
;     const char* bs = as + 36864;
; #pragma unroll
;     for (int ks = 0; ks < 4; ++ks) {
;       bf16x8 af[2], bfr[2];
; #pragma unroll
;       for (int mi = 0; mi < 2; ++mi) af[mi] = *(const bf16x8*)(as + ((wm * 64 + mi * 32 + r) * 72 + ks * 16 + 8 * h) * 2);
; #pragma unroll
;       for (int ni = 0; ni < 2; ++ni) bfr[ni] = *(const bf16x8*)(bs + ((wn * 64 + ni * 32 + r) * 72 + ks * 16 + 8 * h) * 2);
; #pragma unroll
;       for (int mi = 0; mi < 2; ++mi)
; #pragma unroll
;         for (int ni = 0; ni < 2; ++ni) {
;           if (SWAP) acc[mi][ni] = MFMA32(bfr[ni], af[mi], acc[mi][ni]);
;           else acc[mi][ni] = MFMA32(af[mi], bfr[ni], acc[mi][ni]);
;         }
;     }
;   };
;   gload(0, ra0, rb0);
;   lstore(0, ra0, rb0);
;   gload(1, ra1, rb1);
;   __syncthreads();
;   for (int kt = 0; kt < nk; kt += 2) {
;     if (kt + 2 < nk) gload(kt + 2, ra0, rb0);
;     compute(0);
;     lstore(1, ra1, rb1);
;     __syncthreads();
;     if (kt + 3 < nk) gload(kt + 3, ra1, rb1);
;     compute(1);
;     if (kt + 2 < nk) lstore(0, ra0, rb0);
;     __syncthreads();
	ds_read_b128 v[132:135], v210 offset:32768
	ds_read_b128 v[136:139], v210 offset:36864
	ds_read_b128 v[140:143], v214 offset:32768
	ds_read_b128 v[144:147], v214 offset:36864
	ds_read_b128 v[148:151], v214 offset:49152
	ds_read_b128 v[158:161], v214 offset:53248
	s_mov_b32 m0, s44
	s_nop 0
	global_load_lds_dwordx4 v208, s[68:69]
	global_load_lds_dwordx4 v209, s[70:71] offset:1024
	global_load_lds_dwordx4 v208, s[72:73] offset:2048
	global_load_lds_dwordx4 v209, s[74:75] offset:3072
	ds_read_b128 v[162:165], v211 offset:32768
	ds_read_b128 v[168:171], v211 offset:36864
	ds_read_b128 v[172:175], v215 offset:32768
	ds_read_b128 v[176:179], v215 offset:36864
	ds_read_b128 v[180:183], v215 offset:49152
	ds_read_b128 v[184:187], v215 offset:53248
	s_waitcnt lgkmcnt(6)
	v_mfma_f32_32x32x16_bf16 v[4:19], v[140:143], v[132:135], v[4:19]
	v_mfma_f32_32x32x16_bf16 v[68:83], v[140:143], v[136:139], v[68:83]
	v_mfma_f32_32x32x16_bf16 v[20:35], v[144:147], v[132:135], v[20:35]
	v_mfma_f32_32x32x16_bf16 v[84:99], v[144:147], v[136:139], v[84:99]
	v_mfma_f32_32x32x16_bf16 v[36:51], v[148:151], v[132:135], v[36:51]
	v_mfma_f32_32x32x16_bf16 v[100:115], v[148:151], v[136:139], v[100:115]
	v_mfma_f32_32x32x16_bf16 v[52:67], v[158:161], v[132:135], v[52:67]
	v_mfma_f32_32x32x16_bf16 v[116:131], v[158:161], v[136:139], v[116:131]
	s_mov_b32 m0, s46
	s_nop 0
	global_load_lds_dwordx4 v208, s[76:77]
	global_load_lds_dwordx4 v209, s[78:79] offset:1024
	global_load_lds_dwordx4 v208, s[80:81] offset:2048
	global_load_lds_dwordx4 v209, s[82:83] offset:3072
	v_add_u32_e32 v208, 0x80, v208
	v_add_u32_e32 v209, 0x80, v209
	ds_read_b128 v[132:135], v212 offset:32768
	ds_read_b128 v[136:139], v212 offset:36864
	ds_read_b128 v[140:143], v216 offset:32768
	ds_read_b128 v[144:147], v216 offset:36864
	ds_read_b128 v[148:151], v216 offset:49152
	ds_read_b128 v[158:161], v216 offset:53248
	s_waitcnt lgkmcnt(6)
	v_mfma_f32_32x32x16_bf16 v[4:19], v[172:175], v[162:165], v[4:19]
	v_mfma_f32_32x32x16_bf16 v[68:83], v[172:175], v[168:171], v[68:83]
	v_mfma_f32_32x32x16_bf16 v[20:35], v[176:179], v[162:165], v[20:35]
	v_mfma_f32_32x32x16_bf16 v[84:99], v[176:179], v[168:171], v[84:99]
	v_mfma_f32_32x32x16_bf16 v[36:51], v[180:183], v[162:165], v[36:51]
	v_mfma_f32_32x32x16_bf16 v[100:115], v[180:183], v[168:171], v[100:115]
	v_mfma_f32_32x32x16_bf16 v[52:67], v[184:187], v[162:165], v[52:67]
	v_mfma_f32_32x32x16_bf16 v[116:131], v[184:187], v[168:171], v[116:131]
	ds_read_b128 v[162:165], v213 offset:32768
	ds_read_b128 v[168:171], v213 offset:36864
	ds_read_b128 v[172:175], v217 offset:32768
	ds_read_b128 v[176:179], v217 offset:36864
	ds_read_b128 v[180:183], v217 offset:49152
	ds_read_b128 v[184:187], v217 offset:53248
	s_waitcnt lgkmcnt(6)
	v_mfma_f32_32x32x16_bf16 v[4:19], v[140:143], v[132:135], v[4:19]
	v_mfma_f32_32x32x16_bf16 v[68:83], v[140:143], v[136:139], v[68:83]
	v_mfma_f32_32x32x16_bf16 v[20:35], v[144:147], v[132:135], v[20:35]
	v_mfma_f32_32x32x16_bf16 v[84:99], v[144:147], v[136:139], v[84:99]
	v_mfma_f32_32x32x16_bf16 v[36:51], v[148:151], v[132:135], v[36:51]
	v_mfma_f32_32x32x16_bf16 v[100:115], v[148:151], v[136:139], v[100:115]
	v_mfma_f32_32x32x16_bf16 v[52:67], v[158:161], v[132:135], v[52:67]
	v_mfma_f32_32x32x16_bf16 v[116:131], v[158:161], v[136:139], v[116:131]
	s_waitcnt lgkmcnt(0)
	v_mfma_f32_32x32x16_bf16 v[4:19], v[172:175], v[162:165], v[4:19]
	v_mfma_f32_32x32x16_bf16 v[68:83], v[172:175], v[168:171], v[68:83]
	v_mfma_f32_32x32x16_bf16 v[20:35], v[176:179], v[162:165], v[20:35]
	v_mfma_f32_32x32x16_bf16 v[84:99], v[176:179], v[168:171], v[84:99]
	v_mfma_f32_32x32x16_bf16 v[36:51], v[180:183], v[162:165], v[36:51]
	v_mfma_f32_32x32x16_bf16 v[100:115], v[180:183], v[168:171], v[100:115]
	v_mfma_f32_32x32x16_bf16 v[52:67], v[184:187], v[162:165], v[52:67]
	v_mfma_f32_32x32x16_bf16 v[116:131], v[184:187], v[168:171], v[116:131]
	s_waitcnt vmcnt(0) lgkmcnt(0)
	s_barrier
	ds_read_b128 v[132:135], v210 offset:0
	ds_read_b128 v[136:139], v210 offset:4096
	ds_read_b128 v[140:143], v214 offset:0
	ds_read_b128 v[144:147], v214 offset:4096
	ds_read_b128 v[148:151], v214 offset:16384
	ds_read_b128 v[158:161], v214 offset:20480
	s_mov_b32 m0, s45
	s_nop 0
	global_load_lds_dwordx4 v208, s[68:69]
	global_load_lds_dwordx4 v209, s[70:71] offset:1024
	global_load_lds_dwordx4 v208, s[72:73] offset:2048
	global_load_lds_dwordx4 v209, s[74:75] offset:3072
	ds_read_b128 v[162:165], v211 offset:0
	ds_read_b128 v[168:171], v211 offset:4096
	ds_read_b128 v[172:175], v215 offset:0
	ds_read_b128 v[176:179], v215 offset:4096
	ds_read_b128 v[180:183], v215 offset:16384
	ds_read_b128 v[184:187], v215 offset:20480
	s_waitcnt lgkmcnt(6)
	v_mfma_f32_32x32x16_bf16 v[4:19], v[140:143], v[132:135], v[4:19]
	v_mfma_f32_32x32x16_bf16 v[68:83], v[140:143], v[136:139], v[68:83]
	v_mfma_f32_32x32x16_bf16 v[20:35], v[144:147], v[132:135], v[20:35]
	v_mfma_f32_32x32x16_bf16 v[84:99], v[144:147], v[136:139], v[84:99]
	v_mfma_f32_32x32x16_bf16 v[36:51], v[148:151], v[132:135], v[36:51]
	v_mfma_f32_32x32x16_bf16 v[100:115], v[148:151], v[136:139], v[100:115]
	v_mfma_f32_32x32x16_bf16 v[52:67], v[158:161], v[132:135], v[52:67]
	v_mfma_f32_32x32x16_bf16 v[116:131], v[158:161], v[136:139], v[116:131]
	s_mov_b32 m0, s47
	s_nop 0
	global_load_lds_dwordx4 v208, s[76:77]
	global_load_lds_dwordx4 v209, s[78:79] offset:1024
	global_load_lds_dwordx4 v208, s[80:81] offset:2048
	global_load_lds_dwordx4 v209, s[82:83] offset:3072
	v_add_u32_e32 v208, 0x80, v208
	v_add_u32_e32 v209, 0x80, v209
	ds_read_b128 v[132:135], v212 offset:0
	ds_read_b128 v[136:139], v212 offset:4096
	ds_read_b128 v[140:143], v216 offset:0
	ds_read_b128 v[144:147], v216 offset:4096
	ds_read_b128 v[148:151], v216 offset:16384
	ds_read_b128 v[158:161], v216 offset:20480
	s_waitcnt lgkmcnt(6)
; #define MFMA32(a, b, c) __builtin_amdgcn_mfma_f32_32x32x16_bf16((a), (b), (c), 0, 0, 0)
; template <bool SWAP, class Epi>
; DI void gemm_tile(const u16* __restrict__ A, int lda, const u16* __restrict__ Bw, int ldb, int K, char* lds, Epi epi) {
;     ...
;   auto compute = [&](int st) {
;     const char* as = lds + st * GEMM_STAGE;
;     const char* bs = as + 36864;
; #pragma unroll
;     for (int ks = 0; ks < 4; ++ks) {
;       bf16x8 af[2], bfr[2];
; #pragma unroll
;       for (int mi = 0; mi < 2; ++mi) af[mi] = *(const bf16x8*)(as + ((wm * 64 + mi * 32 + r) * 72 + ks * 16 + 8 * h) * 2);
; #pragma unroll
;       for (int ni = 0; ni < 2; ++ni) bfr[ni] = *(const bf16x8*)(bs + ((wn * 64 + ni * 32 + r) * 72 + ks * 16 + 8 * h) * 2);
; #pragma unroll
;       for (int mi = 0; mi < 2; ++mi)
; #pragma unroll
;         for (int ni = 0; ni < 2; ++ni) {
;           if (SWAP) acc[mi][ni] = MFMA32(bfr[ni], af[mi], acc[mi][ni]);
;           else acc[mi][ni] = MFMA32(af[mi], bfr[ni], acc[mi][ni]);
;         }
;     }
;   };
;   gload(0, ra0, rb0);
;   lstore(0, ra0, rb0);
;   gload(1, ra1, rb1);
;   __syncthreads();
;   for (int kt = 0; kt < nk; kt += 2) {
;     if (kt + 2 < nk) gload(kt + 2, ra0, rb0);
;     compute(0);
;     lstore(1, ra1, rb1);
;     __syncthreads();
;     if (kt + 3 < nk) gload(kt + 3, ra1, rb1);
;     compute(1);
;     if (kt + 2 < nk) lstore(0, ra0, rb0);
;     __syncthreads();
	v_mfma_f32_32x32x16_bf16 v[4:19], v[172:175], v[162:165], v[4:19]
	v_mfma_f32_32x32x16_bf16 v[68:83], v[172:175], v[168:171], v[68:83]
	v_mfma_f32_32x32x16_bf16 v[20:35], v[176:179], v[162:165], v[20:35]
	v_mfma_f32_32x32x16_bf16 v[84:99], v[176:179], v[168:171], v[84:99]
	v_mfma_f32_32x32x16_bf16 v[36:51], v[180:183], v[162:165], v[36:51]
	v_mfma_f32_32x32x16_bf16 v[100:115], v[180:183], v[168:171], v[100:115]
	v_mfma_f32_32x32x16_bf16 v[52:67], v[184:187], v[162:165], v[52:67]
	v_mfma_f32_32x32x16_bf16 v[116:131], v[184:187], v[168:171], v[116:131]
	ds_read_b128 v[162:165], v213 offset:0
	ds_read_b128 v[168:171], v213 offset:4096
	ds_read_b128 v[172:175], v217 offset:0
	ds_read_b128 v[176:179], v217 offset:4096
	ds_read_b128 v[180:183], v217 offset:16384
	ds_read_b128 v[184:187], v217 offset:20480
	s_waitcnt lgkmcnt(6)
	v_mfma_f32_32x32x16_bf16 v[4:19], v[140:143], v[132:135], v[4:19]
	v_mfma_f32_32x32x16_bf16 v[68:83], v[140:143], v[136:139], v[68:83]
	v_mfma_f32_32x32x16_bf16 v[20:35], v[144:147], v[132:135], v[20:35]
	v_mfma_f32_32x32x16_bf16 v[84:99], v[144:147], v[136:139], v[84:99]
	v_mfma_f32_32x32x16_bf16 v[36:51], v[148:151], v[132:135], v[36:51]
	v_mfma_f32_32x32x16_bf16 v[100:115], v[148:151], v[136:139], v[100:115]
	v_mfma_f32_32x32x16_bf16 v[52:67], v[158:161], v[132:135], v[52:67]
	v_mfma_f32_32x32x16_bf16 v[116:131], v[158:161], v[136:139], v[116:131]
	s_waitcnt lgkmcnt(0)
	v_mfma_f32_32x32x16_bf16 v[4:19], v[172:175], v[162:165], v[4:19]
	v_mfma_f32_32x32x16_bf16 v[68:83], v[172:175], v[168:171], v[68:83]
	v_mfma_f32_32x32x16_bf16 v[20:35], v[176:179], v[162:165], v[20:35]
	v_mfma_f32_32x32x16_bf16 v[84:99], v[176:179], v[168:171], v[84:99]
	v_mfma_f32_32x32x16_bf16 v[36:51], v[180:183], v[162:165], v[36:51]
	v_mfma_f32_32x32x16_bf16 v[100:115], v[180:183], v[168:171], v[100:115]
	v_mfma_f32_32x32x16_bf16 v[52:67], v[184:187], v[162:165], v[52:67]
	v_mfma_f32_32x32x16_bf16 v[116:131], v[184:187], v[168:171], v[116:131]
	s_waitcnt vmcnt(0) lgkmcnt(0)
	s_barrier
	ds_read_b128 v[132:135], v210 offset:32768
	ds_read_b128 v[136:139], v210 offset:36864
	ds_read_b128 v[140:143], v214 offset:32768
	ds_read_b128 v[144:147], v214 offset:36864
	ds_read_b128 v[148:151], v214 offset:49152
	ds_read_b128 v[158:161], v214 offset:53248
	s_mov_b32 m0, s44
	s_nop 0
	global_load_lds_dwordx4 v208, s[68:69]
	global_load_lds_dwordx4 v209, s[70:71] offset:1024
	global_load_lds_dwordx4 v208, s[72:73] offset:2048
	global_load_lds_dwordx4 v209, s[74:75] offset:3072
	ds_read_b128 v[162:165], v211 offset:32768
	ds_read_b128 v[168:171], v211 offset:36864
	ds_read_b128 v[172:175], v215 offset:32768
	ds_read_b128 v[176:179], v215 offset:36864
	ds_read_b128 v[180:183], v215 offset:49152
	ds_read_b128 v[184:187], v215 offset:53248
	s_waitcnt lgkmcnt(6)
	v_mfma_f32_32x32x16_bf16 v[4:19], v[140:143], v[132:135], v[4:19]
	v_mfma_f32_32x32x16_bf16 v[68:83], v[140:143], v[136:139], v[68:83]
	v_mfma_f32_32x32x16_bf16 v[20:35], v[144:147], v[132:135], v[20:35]
	v_mfma_f32_32x32x16_bf16 v[84:99], v[144:147], v[136:139], v[84:99]
	v_mfma_f32_32x32x16_bf16 v[36:51], v[148:151], v[132:135], v[36:51]
	v_mfma_f32_32x32x16_bf16 v[100:115], v[148:151], v[136:139], v[100:115]
	v_mfma_f32_32x32x16_bf16 v[52:67], v[158:161], v[132:135], v[52:67]
	v_mfma_f32_32x32x16_bf16 v[116:131], v[158:161], v[136:139], v[116:131]
	s_mov_b32 m0, s46
	s_nop 0
	global_load_lds_dwordx4 v208, s[76:77]
	global_load_lds_dwordx4 v209, s[78:79] offset:1024
	global_load_lds_dwordx4 v208, s[80:81] offset:2048
	global_load_lds_dwordx4 v209, s[82:83] offset:3072
	v_add_u32_e32 v208, 0x80, v208
	v_add_u32_e32 v209, 0x80, v209
	ds_read_b128 v[132:135], v212 offset:32768
	ds_read_b128 v[136:139], v212 offset:36864
	ds_read_b128 v[140:143], v216 offset:32768
	ds_read_b128 v[144:147], v216 offset:36864
	ds_read_b128 v[148:151], v216 offset:49152
	ds_read_b128 v[158:161], v216 offset:53248
	s_waitcnt lgkmcnt(6)
	v_mfma_f32_32x32x16_bf16 v[4:19], v[172:175], v[162:165], v[4:19]
	v_mfma_f32_32x32x16_bf16 v[68:83], v[172:175], v[168:171], v[68:83]
	v_mfma_f32_32x32x16_bf16 v[20:35], v[176:179], v[162:165], v[20:35]
	v_mfma_f32_32x32x16_bf16 v[84:99], v[176:179], v[168:171], v[84:99]
	v_mfma_f32_32x32x16_bf16 v[36:51], v[180:183], v[162:165], v[36:51]
	v_mfma_f32_32x32x16_bf16 v[100:115], v[180:183], v[168:171], v[100:115]
	v_mfma_f32_32x32x16_bf16 v[52:67], v[184:187], v[162:165], v[52:67]
	v_mfma_f32_32x32x16_bf16 v[116:131], v[184:187], v[168:171], v[116:131]
	ds_read_b128 v[162:165], v213 offset:32768
	ds_read_b128 v[168:171], v213 offset:36864
	ds_read_b128 v[172:175], v217 offset:32768
	ds_read_b128 v[176:179], v217 offset:36864
	ds_read_b128 v[180:183], v217 offset:49152
	ds_read_b128 v[184:187], v217 offset:53248
	s_waitcnt lgkmcnt(6)
	v_mfma_f32_32x32x16_bf16 v[4:19], v[140:143], v[132:135], v[4:19]
	v_mfma_f32_32x32x16_bf16 v[68:83], v[140:143], v[136:139], v[68:83]
	v_mfma_f32_32x32x16_bf16 v[20:35], v[144:147], v[132:135], v[20:35]
	v_mfma_f32_32x32x16_bf16 v[84:99], v[144:147], v[136:139], v[84:99]
	v_mfma_f32_32x32x16_bf16 v[36:51], v[148:151], v[132:135], v[36:51]
	v_mfma_f32_32x32x16_bf16 v[100:115], v[148:151], v[136:139], v[100:115]
	v_mfma_f32_32x32x16_bf16 v[52:67], v[158:161], v[132:135], v[52:67]
	v_mfma_f32_32x32x16_bf16 v[116:131], v[158:161], v[136:139], v[116:131]
	s_waitcnt lgkmcnt(0)
	v_mfma_f32_32x32x16_bf16 v[4:19], v[172:175], v[162:165], v[4:19]
	v_mfma_f32_32x32x16_bf16 v[68:83], v[172:175], v[168:171], v[68:83]
	v_mfma_f32_32x32x16_bf16 v[20:35], v[176:179], v[162:165], v[20:35]
	v_mfma_f32_32x32x16_bf16 v[84:99], v[176:179], v[168:171], v[84:99]
	v_mfma_f32_32x32x16_bf16 v[36:51], v[180:183], v[162:165], v[36:51]
	v_mfma_f32_32x32x16_bf16 v[100:115], v[180:183], v[168:171], v[100:115]
	v_mfma_f32_32x32x16_bf16 v[52:67], v[184:187], v[162:165], v[52:67]
	v_mfma_f32_32x32x16_bf16 v[116:131], v[184:187], v[168:171], v[116:131]
	s_waitcnt vmcnt(0) lgkmcnt(0)
	s_barrier
; #define MFMA32(a, b, c) __builtin_amdgcn_mfma_f32_32x32x16_bf16((a), (b), (c), 0, 0, 0)
; template <bool SWAP, class Epi>
; DI void gemm_tile(const u16* __restrict__ A, int lda, const u16* __restrict__ Bw, int ldb, int K, char* lds, Epi epi) {
;     ...
;   auto compute = [&](int st) {
;     const char* as = lds + st * GEMM_STAGE;
;     const char* bs = as + 36864;
; #pragma unroll
;     for (int ks = 0; ks < 4; ++ks) {
;       bf16x8 af[2], bfr[2];
; #pragma unroll
;       for (int mi = 0; mi < 2; ++mi) af[mi] = *(const bf16x8*)(as + ((wm * 64 + mi * 32 + r) * 72 + ks * 16 + 8 * h) * 2);
; #pragma unroll
;       for (int ni = 0; ni < 2; ++ni) bfr[ni] = *(const bf16x8*)(bs + ((wn * 64 + ni * 32 + r) * 72 + ks * 16 + 8 * h) * 2);
; #pragma unroll
;       for (int mi = 0; mi < 2; ++mi)
; #pragma unroll
;         for (int ni = 0; ni < 2; ++ni) {
;           if (SWAP) acc[mi][ni] = MFMA32(bfr[ni], af[mi], acc[mi][ni]);
;           else acc[mi][ni] = MFMA32(af[mi], bfr[ni], acc[mi][ni]);
;         }
;     }
;   };
;   gload(0, ra0, rb0);
;   lstore(0, ra0, rb0);
;   gload(1, ra1, rb1);
;   __syncthreads();
;   for (int kt = 0; kt < nk; kt += 2) {
;     if (kt + 2 < nk) gload(kt + 2, ra0, rb0);
;     compute(0);
;     lstore(1, ra1, rb1);
;     __syncthreads();
;     if (kt + 3 < nk) gload(kt + 3, ra1, rb1);
;     compute(1);
;     if (kt + 2 < nk) lstore(0, ra0, rb0);
;     __syncthreads();
	ds_read_b128 v[132:135], v210 offset:0
	ds_read_b128 v[136:139], v210 offset:4096
	ds_read_b128 v[140:143], v214 offset:0
	ds_read_b128 v[144:147], v214 offset:4096
	ds_read_b128 v[148:151], v214 offset:16384
	ds_read_b128 v[158:161], v214 offset:20480
	s_mov_b32 m0, s45
	s_nop 0
	global_load_lds_dwordx4 v208, s[68:69]
	global_load_lds_dwordx4 v209, s[70:71] offset:1024
	global_load_lds_dwordx4 v208, s[72:73] offset:2048
	global_load_lds_dwordx4 v209, s[74:75] offset:3072
	ds_read_b128 v[162:165], v211 offset:0
	ds_read_b128 v[168:171], v211 offset:4096
	ds_read_b128 v[172:175], v215 offset:0
	ds_read_b128 v[176:179], v215 offset:4096
	ds_read_b128 v[180:183], v215 offset:16384
	ds_read_b128 v[184:187], v215 offset:20480
	s_waitcnt lgkmcnt(6)
	v_mfma_f32_32x32x16_bf16 v[4:19], v[140:143], v[132:135], v[4:19]
	v_mfma_f32_32x32x16_bf16 v[68:83], v[140:143], v[136:139], v[68:83]
	v_mfma_f32_32x32x16_bf16 v[20:35], v[144:147], v[132:135], v[20:35]
	v_mfma_f32_32x32x16_bf16 v[84:99], v[144:147], v[136:139], v[84:99]
	v_mfma_f32_32x32x16_bf16 v[36:51], v[148:151], v[132:135], v[36:51]
	v_mfma_f32_32x32x16_bf16 v[100:115], v[148:151], v[136:139], v[100:115]
	v_mfma_f32_32x32x16_bf16 v[52:67], v[158:161], v[132:135], v[52:67]
	v_mfma_f32_32x32x16_bf16 v[116:131], v[158:161], v[136:139], v[116:131]
	s_mov_b32 m0, s47
	s_nop 0
	global_load_lds_dwordx4 v208, s[76:77]
	global_load_lds_dwordx4 v209, s[78:79] offset:1024
	global_load_lds_dwordx4 v208, s[80:81] offset:2048
	global_load_lds_dwordx4 v209, s[82:83] offset:3072
	v_add_u32_e32 v208, 0x80, v208
	v_add_u32_e32 v209, 0x80, v209
	ds_read_b128 v[132:135], v212 offset:0
	ds_read_b128 v[136:139], v212 offset:4096
	ds_read_b128 v[140:143], v216 offset:0
	ds_read_b128 v[144:147], v216 offset:4096
	ds_read_b128 v[148:151], v216 offset:16384
	ds_read_b128 v[158:161], v216 offset:20480
	s_waitcnt lgkmcnt(6)
	v_mfma_f32_32x32x16_bf16 v[4:19], v[172:175], v[162:165], v[4:19]
	v_mfma_f32_32x32x16_bf16 v[68:83], v[172:175], v[168:171], v[68:83]
	v_mfma_f32_32x32x16_bf16 v[20:35], v[176:179], v[162:165], v[20:35]
	v_mfma_f32_32x32x16_bf16 v[84:99], v[176:179], v[168:171], v[84:99]
	v_mfma_f32_32x32x16_bf16 v[36:51], v[180:183], v[162:165], v[36:51]
	v_mfma_f32_32x32x16_bf16 v[100:115], v[180:183], v[168:171], v[100:115]
	v_mfma_f32_32x32x16_bf16 v[52:67], v[184:187], v[162:165], v[52:67]
	v_mfma_f32_32x32x16_bf16 v[116:131], v[184:187], v[168:171], v[116:131]
	ds_read_b128 v[162:165], v213 offset:0
	ds_read_b128 v[168:171], v213 offset:4096
	ds_read_b128 v[172:175], v217 offset:0
	ds_read_b128 v[176:179], v217 offset:4096
	ds_read_b128 v[180:183], v217 offset:16384
	ds_read_b128 v[184:187], v217 offset:20480
	s_waitcnt lgkmcnt(6)
	v_mfma_f32_32x32x16_bf16 v[4:19], v[140:143], v[132:135], v[4:19]
	v_mfma_f32_32x32x16_bf16 v[68:83], v[140:143], v[136:139], v[68:83]
	v_mfma_f32_32x32x16_bf16 v[20:35], v[144:147], v[132:135], v[20:35]
	v_mfma_f32_32x32x16_bf16 v[84:99], v[144:147], v[136:139], v[84:99]
	v_mfma_f32_32x32x16_bf16 v[36:51], v[148:151], v[132:135], v[36:51]
	v_mfma_f32_32x32x16_bf16 v[100:115], v[148:151], v[136:139], v[100:115]
	v_mfma_f32_32x32x16_bf16 v[52:67], v[158:161], v[132:135], v[52:67]
	v_mfma_f32_32x32x16_bf16 v[116:131], v[158:161], v[136:139], v[116:131]
	s_waitcnt lgkmcnt(0)
	v_mfma_f32_32x32x16_bf16 v[4:19], v[172:175], v[162:165], v[4:19]
	v_mfma_f32_32x32x16_bf16 v[68:83], v[172:175], v[168:171], v[68:83]
	v_mfma_f32_32x32x16_bf16 v[20:35], v[176:179], v[162:165], v[20:35]
	v_mfma_f32_32x32x16_bf16 v[84:99], v[176:179], v[168:171], v[84:99]
	v_mfma_f32_32x32x16_bf16 v[36:51], v[180:183], v[162:165], v[36:51]
	v_mfma_f32_32x32x16_bf16 v[100:115], v[180:183], v[168:171], v[100:115]
	v_mfma_f32_32x32x16_bf16 v[52:67], v[184:187], v[162:165], v[52:67]
	v_mfma_f32_32x32x16_bf16 v[116:131], v[184:187], v[168:171], v[116:131]
	s_waitcnt vmcnt(0) lgkmcnt(0)
	s_barrier
	ds_read_b128 v[132:135], v210 offset:32768
	ds_read_b128 v[136:139], v210 offset:36864
	ds_read_b128 v[140:143], v214 offset:32768
	ds_read_b128 v[144:147], v214 offset:36864
	ds_read_b128 v[148:151], v214 offset:49152
	ds_read_b128 v[158:161], v214 offset:53248
	ds_read_b128 v[162:165], v211 offset:32768
	ds_read_b128 v[168:171], v211 offset:36864
	ds_read_b128 v[172:175], v215 offset:32768
	ds_read_b128 v[176:179], v215 offset:36864
	ds_read_b128 v[180:183], v215 offset:49152
	ds_read_b128 v[184:187], v215 offset:53248
	s_waitcnt lgkmcnt(6)
	v_mfma_f32_32x32x16_bf16 v[4:19], v[140:143], v[132:135], v[4:19]
	v_mfma_f32_32x32x16_bf16 v[68:83], v[140:143], v[136:139], v[68:83]
	v_mfma_f32_32x32x16_bf16 v[20:35], v[144:147], v[132:135], v[20:35]
	v_mfma_f32_32x32x16_bf16 v[84:99], v[144:147], v[136:139], v[84:99]
	v_mfma_f32_32x32x16_bf16 v[36:51], v[148:151], v[132:135], v[36:51]
	v_mfma_f32_32x32x16_bf16 v[100:115], v[148:151], v[136:139], v[100:115]
	v_mfma_f32_32x32x16_bf16 v[52:67], v[158:161], v[132:135], v[52:67]
	v_mfma_f32_32x32x16_bf16 v[116:131], v[158:161], v[136:139], v[116:131]
	ds_read_b128 v[132:135], v212 offset:32768
	ds_read_b128 v[136:139], v212 offset:36864
	ds_read_b128 v[140:143], v216 offset:32768
	ds_read_b128 v[144:147], v216 offset:36864
	ds_read_b128 v[148:151], v216 offset:49152
	ds_read_b128 v[158:161], v216 offset:53248
	s_waitcnt lgkmcnt(6)
; DI unsigned pk2(float a, float b) { f32x2 v = {a, b}; return __builtin_bit_cast(unsigned, __builtin_convertvector(v, bf2_t)); }
; template <bool SWAP, class Epi>
; DI void gemm_tile(const u16* __restrict__ A, int lda, const u16* __restrict__ Bw, int ldb, int K, char* lds, Epi epi) {
;     ...
;   for (int mi = 0; mi < 2; ++mi)
; #pragma unroll
;     for (int ni = 0; ni < 2; ++ni) epi(mi, ni, acc[mi][ni]);
; }
; DI void store_rowmajor(u16* dst, const f32x16& a, int h, float sc) {
; #pragma unroll
;   for (int kp = 0; kp < 2; ++kp) {
;     const int g = 2 * kp;
;     unsigned ax = pk2(a[4 * g] * sc, a[4 * g + 1] * sc), ay = pk2(a[4 * g + 2] * sc, a[4 * g + 3] * sc);
;     unsigned bx = pk2(a[4 * g + 4] * sc, a[4 * g + 5] * sc), by = pk2(a[4 * g + 6] * sc, a[4 * g + 7] * sc);
;     const u32x2 rx = __builtin_amdgcn_permlane32_swap(ax, bx, false, false);
;     const u32x2 ry = __builtin_amdgcn_permlane32_swap(ay, by, false, false);
;     const u32x4 v = {rx[0], ry[0], rx[1], ry[1]};
;     *(u32x4*)(dst + 8 * (g + h)) = v;
;   }
; }
; DI void inproj_tile(const Params& p, int l, int mt, int nt, char* lds) {
;     ...
;     gemm_tile<true>(A, DM, Bw, DM, DM, lds, [&](int mi, int ni, const f32x16& a) {
;       const int tok = m0 + wm * 64 + mi * 32 + r;
;       store_rowmajor(p.H + (size_t)tok * LDH + nt * 128 + wn * 64 + ni * 32, a, h, 1.f);
	v_mfma_f32_32x32x16_bf16 v[4:19], v[172:175], v[162:165], v[4:19]
	v_mfma_f32_32x32x16_bf16 v[68:83], v[172:175], v[168:171], v[68:83]
	v_mfma_f32_32x32x16_bf16 v[20:35], v[176:179], v[162:165], v[20:35]
	v_mfma_f32_32x32x16_bf16 v[84:99], v[176:179], v[168:171], v[84:99]
	v_mfma_f32_32x32x16_bf16 v[36:51], v[180:183], v[162:165], v[36:51]
	v_mfma_f32_32x32x16_bf16 v[100:115], v[180:183], v[168:171], v[100:115]
	v_mfma_f32_32x32x16_bf16 v[52:67], v[184:187], v[162:165], v[52:67]
	v_mfma_f32_32x32x16_bf16 v[116:131], v[184:187], v[168:171], v[116:131]
	ds_read_b128 v[162:165], v213 offset:32768
	ds_read_b128 v[168:171], v213 offset:36864
	ds_read_b128 v[172:175], v217 offset:32768
	ds_read_b128 v[176:179], v217 offset:36864
	ds_read_b128 v[180:183], v217 offset:49152
	ds_read_b128 v[184:187], v217 offset:53248
	s_waitcnt lgkmcnt(6)
	v_mfma_f32_32x32x16_bf16 v[4:19], v[140:143], v[132:135], v[4:19]
	v_mfma_f32_32x32x16_bf16 v[68:83], v[140:143], v[136:139], v[68:83]
	v_mfma_f32_32x32x16_bf16 v[20:35], v[144:147], v[132:135], v[20:35]
	v_mfma_f32_32x32x16_bf16 v[84:99], v[144:147], v[136:139], v[84:99]
	v_mfma_f32_32x32x16_bf16 v[36:51], v[148:151], v[132:135], v[36:51]
	v_mfma_f32_32x32x16_bf16 v[100:115], v[148:151], v[136:139], v[100:115]
	v_mfma_f32_32x32x16_bf16 v[52:67], v[158:161], v[132:135], v[52:67]
	v_mfma_f32_32x32x16_bf16 v[116:131], v[158:161], v[136:139], v[116:131]
	s_waitcnt lgkmcnt(0)
	v_mfma_f32_32x32x16_bf16 v[4:19], v[172:175], v[162:165], v[4:19]
	v_mfma_f32_32x32x16_bf16 v[68:83], v[172:175], v[168:171], v[68:83]
	v_mfma_f32_32x32x16_bf16 v[20:35], v[176:179], v[162:165], v[20:35]
	v_mfma_f32_32x32x16_bf16 v[84:99], v[176:179], v[168:171], v[84:99]
	v_mfma_f32_32x32x16_bf16 v[36:51], v[180:183], v[162:165], v[36:51]
	v_mfma_f32_32x32x16_bf16 v[100:115], v[180:183], v[168:171], v[100:115]
	v_mfma_f32_32x32x16_bf16 v[52:67], v[184:187], v[162:165], v[52:67]
	v_mfma_f32_32x32x16_bf16 v[116:131], v[184:187], v[168:171], v[116:131]
	s_waitcnt lgkmcnt(0)
	s_barrier
	s_nop 7
	s_nop 7
	v_cvt_pk_bf16_f32 v224, v4, v5
	v_cvt_pk_bf16_f32 v225, v6, v7
	v_cvt_pk_bf16_f32 v226, v8, v9
	v_cvt_pk_bf16_f32 v227, v10, v11
	s_nop 1
	v_permlane32_swap_b32_e32 v224, v226
	v_permlane32_swap_b32_e32 v225, v227
	s_nop 0
	global_store_dwordx4 v218, v[224:227], s[8:9]
	v_cvt_pk_bf16_f32 v228, v12, v13
	v_cvt_pk_bf16_f32 v229, v14, v15
	v_cvt_pk_bf16_f32 v230, v16, v17
	v_cvt_pk_bf16_f32 v231, v18, v19
	s_nop 1
	v_permlane32_swap_b32_e32 v228, v230
	v_permlane32_swap_b32_e32 v229, v231
	s_nop 0
	global_store_dwordx4 v218, v[228:231], s[8:9] offset:32
	v_cvt_pk_bf16_f32 v224, v68, v69
	v_cvt_pk_bf16_f32 v225, v70, v71
	v_cvt_pk_bf16_f32 v226, v72, v73
	v_cvt_pk_bf16_f32 v227, v74, v75
	s_nop 1
	v_permlane32_swap_b32_e32 v224, v226
	v_permlane32_swap_b32_e32 v225, v227
	s_nop 0
	global_store_dwordx4 v219, v[224:227], s[8:9]
	v_cvt_pk_bf16_f32 v228, v76, v77
	v_cvt_pk_bf16_f32 v229, v78, v79
	v_cvt_pk_bf16_f32 v230, v80, v81
	v_cvt_pk_bf16_f32 v231, v82, v83
	s_nop 1
	v_permlane32_swap_b32_e32 v228, v230
	v_permlane32_swap_b32_e32 v229, v231
	s_nop 0
	global_store_dwordx4 v219, v[228:231], s[8:9] offset:32
	v_cvt_pk_bf16_f32 v224, v20, v21
	v_cvt_pk_bf16_f32 v225, v22, v23
	v_cvt_pk_bf16_f32 v226, v24, v25
	v_cvt_pk_bf16_f32 v227, v26, v27
	s_nop 1
	v_permlane32_swap_b32_e32 v224, v226
	v_permlane32_swap_b32_e32 v225, v227
	s_nop 0
	global_store_dwordx4 v218, v[224:227], s[8:9] offset:64
	v_cvt_pk_bf16_f32 v228, v28, v29
	v_cvt_pk_bf16_f32 v229, v30, v31
	v_cvt_pk_bf16_f32 v230, v32, v33
	v_cvt_pk_bf16_f32 v231, v34, v35
	s_nop 1
	v_permlane32_swap_b32_e32 v228, v230
	v_permlane32_swap_b32_e32 v229, v231
	s_nop 0
	global_store_dwordx4 v218, v[228:231], s[8:9] offset:96
	v_cvt_pk_bf16_f32 v224, v84, v85
	v_cvt_pk_bf16_f32 v225, v86, v87
	v_cvt_pk_bf16_f32 v226, v88, v89
	v_cvt_pk_bf16_f32 v227, v90, v91
	s_nop 1
	v_permlane32_swap_b32_e32 v224, v226
	v_permlane32_swap_b32_e32 v225, v227
	s_nop 0
	global_store_dwordx4 v219, v[224:227], s[8:9] offset:64
	v_cvt_pk_bf16_f32 v228, v92, v93
	v_cvt_pk_bf16_f32 v229, v94, v95
	v_cvt_pk_bf16_f32 v230, v96, v97
	v_cvt_pk_bf16_f32 v231, v98, v99
	s_nop 1
	v_permlane32_swap_b32_e32 v228, v230
	v_permlane32_swap_b32_e32 v229, v231
	s_nop 0
	global_store_dwordx4 v219, v[228:231], s[8:9] offset:96
	v_cvt_pk_bf16_f32 v224, v36, v37
	v_cvt_pk_bf16_f32 v225, v38, v39
	v_cvt_pk_bf16_f32 v226, v40, v41
	v_cvt_pk_bf16_f32 v227, v42, v43
	s_nop 1
	v_permlane32_swap_b32_e32 v224, v226
	v_permlane32_swap_b32_e32 v225, v227
	s_nop 0
	global_store_dwordx4 v218, v[224:227], s[8:9] offset:256
	v_cvt_pk_bf16_f32 v228, v44, v45
	v_cvt_pk_bf16_f32 v229, v46, v47
	v_cvt_pk_bf16_f32 v230, v48, v49
	v_cvt_pk_bf16_f32 v231, v50, v51
	s_nop 1
	v_permlane32_swap_b32_e32 v228, v230
	v_permlane32_swap_b32_e32 v229, v231
	s_nop 0
	global_store_dwordx4 v218, v[228:231], s[8:9] offset:288
	v_cvt_pk_bf16_f32 v224, v100, v101
	v_cvt_pk_bf16_f32 v225, v102, v103
	v_cvt_pk_bf16_f32 v226, v104, v105
	v_cvt_pk_bf16_f32 v227, v106, v107
	s_nop 1
	v_permlane32_swap_b32_e32 v224, v226
	v_permlane32_swap_b32_e32 v225, v227
	s_nop 0
	global_store_dwordx4 v219, v[224:227], s[8:9] offset:256
	v_cvt_pk_bf16_f32 v228, v108, v109
	v_cvt_pk_bf16_f32 v229, v110, v111
	v_cvt_pk_bf16_f32 v230, v112, v113
	v_cvt_pk_bf16_f32 v231, v114, v115
	s_nop 1
	v_permlane32_swap_b32_e32 v228, v230
	v_permlane32_swap_b32_e32 v229, v231
	s_nop 0
	global_store_dwordx4 v219, v[228:231], s[8:9] offset:288
	v_cvt_pk_bf16_f32 v224, v52, v53
	v_cvt_pk_bf16_f32 v225, v54, v55
	v_cvt_pk_bf16_f32 v226, v56, v57
	v_cvt_pk_bf16_f32 v227, v58, v59
	s_nop 1
	v_permlane32_swap_b32_e32 v224, v226
	v_permlane32_swap_b32_e32 v225, v227
	s_nop 0
	global_store_dwordx4 v218, v[224:227], s[8:9] offset:320
	v_cvt_pk_bf16_f32 v228, v60, v61
	v_cvt_pk_bf16_f32 v229, v62, v63
	v_cvt_pk_bf16_f32 v230, v64, v65
	v_cvt_pk_bf16_f32 v231, v66, v67
	s_nop 1
	v_permlane32_swap_b32_e32 v228, v230
	v_permlane32_swap_b32_e32 v229, v231
	s_nop 0
	global_store_dwordx4 v218, v[228:231], s[8:9] offset:352
	v_cvt_pk_bf16_f32 v224, v116, v117
	v_cvt_pk_bf16_f32 v225, v118, v119
	v_cvt_pk_bf16_f32 v226, v120, v121
	v_cvt_pk_bf16_f32 v227, v122, v123
	s_nop 1
	v_permlane32_swap_b32_e32 v224, v226
	v_permlane32_swap_b32_e32 v225, v227
	s_nop 0
	global_store_dwordx4 v219, v[224:227], s[8:9] offset:320
	v_cvt_pk_bf16_f32 v228, v124, v125
	v_cvt_pk_bf16_f32 v229, v126, v127
	v_cvt_pk_bf16_f32 v230, v128, v129
	v_cvt_pk_bf16_f32 v231, v130, v131
	s_nop 1
	v_permlane32_swap_b32_e32 v228, v230
	v_permlane32_swap_b32_e32 v229, v231
	s_nop 0
	global_store_dwordx4 v219, v[228:231], s[8:9] offset:352
	s_branch .Lpp_next
; #define MFMA32(a, b, c) __builtin_amdgcn_mfma_f32_32x32x16_bf16((a), (b), (c), 0, 0, 0)
; template <bool SWAP, class Epi>
; DI void gemm_tile(const u16* __restrict__ A, int lda, const u16* __restrict__ Bw, int ldb, int K, char* lds, Epi epi) {
;     ...
;   auto compute = [&](int st) {
;     const char* as = lds + st * GEMM_STAGE;
;     const char* bs = as + 36864;
; #pragma unroll
;     for (int ks = 0; ks < 4; ++ks) {
;       bf16x8 af[2], bfr[2];
; #pragma unroll
;       for (int mi = 0; mi < 2; ++mi) af[mi] = *(const bf16x8*)(as + ((wm * 64 + mi * 32 + r) * 72 + ks * 16 + 8 * h) * 2);
; #pragma unroll
;       for (int ni = 0; ni < 2; ++ni) bfr[ni] = *(const bf16x8*)(bs + ((wn * 64 + ni * 32 + r) * 72 + ks * 16 + 8 * h) * 2);
; #pragma unroll
;       for (int mi = 0; mi < 2; ++mi)
; #pragma unroll
;         for (int ni = 0; ni < 2; ++ni) {
;           if (SWAP) acc[mi][ni] = MFMA32(bfr[ni], af[mi], acc[mi][ni]);
;           else acc[mi][ni] = MFMA32(af[mi], bfr[ni], acc[mi][ni]);
;         }
;     }
;   };
;   gload(0, ra0, rb0);
;   lstore(0, ra0, rb0);
;   gload(1, ra1, rb1);
;   __syncthreads();
;   for (int kt = 0; kt < nk; kt += 2) {
;     if (kt + 2 < nk) gload(kt + 2, ra0, rb0);
;     compute(0);
; DI void inproj_tile(const Params& p, int l, int mt, int nt, char* lds) {
;     ...
;     u16* vt; int nv, c0;
;     if (nt < 47) { vt = p.VtA; nv = 512; c0 = (nt - 43) * 128; } else { vt = p.VtD; nv = 128; c0 = 0; }
;     gemm_tile<false>(A, DM, Bw, DM, DM, lds, [&](int mi, int ni, const f32x16& a) {
;       const int b = m0 / PP, t0 = m0 - b * PP + wm * 64 + mi * 32;
;       const int col = c0 + wn * 64 + ni * 32 + r;
;       store_transposed(vt + ((size_t)b * nv + col) * PP + t0, a, h, nullptr);
.Lpp_T:
	v_readlane_b32 s8, v241, 30
	v_readlane_b32 s9, v241, 31
	s_cmp_gt_u32 s26, 32
	s_cselect_b32 s12, 1, 0
	s_mul_i32 s13, s12, 33
	s_sub_i32 s13, s26, s13
	s_lshl_b32 s13, s13, 8
	s_lshl_b32 s0, s0, 6
	s_add_i32 s13, s13, s0
	s_lshl_b32 s12, s12, 9
	s_sub_i32 s0, s2, 43
	s_lshl_b32 s0, s0, 7
	s_add_i32 s12, s12, s0
	s_lshl_b32 s1, s1, 6
	s_add_i32 s12, s12, s1
	v_add_u32_e32 v0, s12, v0
	v_mul_u32_u24_e32 v0, 0x2100, v0
	v_add_u32_e32 v0, s13, v0
	v_lshlrev_b32_e32 v0, 1, v0
	v_lshl_add_u32 v218, v1, 3, v0
	v_add_u32_e32 v219, 0x84000, v218
	v_add_u32_e32 v220, 0x210000, v218
	v_add_u32_e32 v221, 0x210000, v219
	s_waitcnt vmcnt(0) lgkmcnt(0)
	s_barrier
	ds_read_b128 v[132:135], v210 offset:0
	ds_read_b128 v[136:139], v210 offset:4096
	ds_read_b128 v[140:143], v214 offset:0
	ds_read_b128 v[144:147], v214 offset:4096
	ds_read_b128 v[148:151], v214 offset:16384
	ds_read_b128 v[158:161], v214 offset:20480
	s_mov_b32 m0, s45
	s_nop 0
	global_load_lds_dwordx4 v208, s[68:69]
	global_load_lds_dwordx4 v209, s[70:71] offset:1024
	global_load_lds_dwordx4 v208, s[72:73] offset:2048
	global_load_lds_dwordx4 v209, s[74:75] offset:3072
	ds_read_b128 v[162:165], v211 offset:0
	ds_read_b128 v[168:171], v211 offset:4096
	ds_read_b128 v[172:175], v215 offset:0
	ds_read_b128 v[176:179], v215 offset:4096
	ds_read_b128 v[180:183], v215 offset:16384
	ds_read_b128 v[184:187], v215 offset:20480
	s_waitcnt lgkmcnt(6)
	v_mfma_f32_32x32x16_bf16 v[4:19], v[132:135], v[140:143], 0
	v_mfma_f32_32x32x16_bf16 v[68:83], v[136:139], v[140:143], 0
	v_mfma_f32_32x32x16_bf16 v[20:35], v[132:135], v[144:147], 0
	v_mfma_f32_32x32x16_bf16 v[84:99], v[136:139], v[144:147], 0
	v_mfma_f32_32x32x16_bf16 v[36:51], v[132:135], v[148:151], 0
	v_mfma_f32_32x32x16_bf16 v[100:115], v[136:139], v[148:151], 0
	v_mfma_f32_32x32x16_bf16 v[52:67], v[132:135], v[158:161], 0
	v_mfma_f32_32x32x16_bf16 v[116:131], v[136:139], v[158:161], 0
	s_mov_b32 m0, s47
	s_nop 0
	global_load_lds_dwordx4 v208, s[76:77]
	global_load_lds_dwordx4 v209, s[78:79] offset:1024
	global_load_lds_dwordx4 v208, s[80:81] offset:2048
	global_load_lds_dwordx4 v209, s[82:83] offset:3072
	v_add_u32_e32 v208, 0x80, v208
	v_add_u32_e32 v209, 0x80, v209
	ds_read_b128 v[132:135], v212 offset:0
	ds_read_b128 v[136:139], v212 offset:4096
	ds_read_b128 v[140:143], v216 offset:0
	ds_read_b128 v[144:147], v216 offset:4096
	ds_read_b128 v[148:151], v216 offset:16384
	ds_read_b128 v[158:161], v216 offset:20480
	s_waitcnt lgkmcnt(6)
	v_mfma_f32_32x32x16_bf16 v[4:19], v[162:165], v[172:175], v[4:19]
	v_mfma_f32_32x32x16_bf16 v[68:83], v[168:171], v[172:175], v[68:83]
	v_mfma_f32_32x32x16_bf16 v[20:35], v[162:165], v[176:179], v[20:35]
	v_mfma_f32_32x32x16_bf16 v[84:99], v[168:171], v[176:179], v[84:99]
	v_mfma_f32_32x32x16_bf16 v[36:51], v[162:165], v[180:183], v[36:51]
	v_mfma_f32_32x32x16_bf16 v[100:115], v[168:171], v[180:183], v[100:115]
	v_mfma_f32_32x32x16_bf16 v[52:67], v[162:165], v[184:187], v[52:67]
	v_mfma_f32_32x32x16_bf16 v[116:131], v[168:171], v[184:187], v[116:131]
	ds_read_b128 v[162:165], v213 offset:0
	ds_read_b128 v[168:171], v213 offset:4096
	ds_read_b128 v[172:175], v217 offset:0
	ds_read_b128 v[176:179], v217 offset:4096
	ds_read_b128 v[180:183], v217 offset:16384
	ds_read_b128 v[184:187], v217 offset:20480
	s_waitcnt lgkmcnt(6)
	v_mfma_f32_32x32x16_bf16 v[4:19], v[132:135], v[140:143], v[4:19]
	v_mfma_f32_32x32x16_bf16 v[68:83], v[136:139], v[140:143], v[68:83]
	v_mfma_f32_32x32x16_bf16 v[20:35], v[132:135], v[144:147], v[20:35]
	v_mfma_f32_32x32x16_bf16 v[84:99], v[136:139], v[144:147], v[84:99]
	v_mfma_f32_32x32x16_bf16 v[36:51], v[132:135], v[148:151], v[36:51]
	v_mfma_f32_32x32x16_bf16 v[100:115], v[136:139], v[148:151], v[100:115]
	v_mfma_f32_32x32x16_bf16 v[52:67], v[132:135], v[158:161], v[52:67]
	v_mfma_f32_32x32x16_bf16 v[116:131], v[136:139], v[158:161], v[116:131]
	s_waitcnt lgkmcnt(0)
	v_mfma_f32_32x32x16_bf16 v[4:19], v[162:165], v[172:175], v[4:19]
	v_mfma_f32_32x32x16_bf16 v[68:83], v[168:171], v[172:175], v[68:83]
	v_mfma_f32_32x32x16_bf16 v[20:35], v[162:165], v[176:179], v[20:35]
	v_mfma_f32_32x32x16_bf16 v[84:99], v[168:171], v[176:179], v[84:99]
	v_mfma_f32_32x32x16_bf16 v[36:51], v[162:165], v[180:183], v[36:51]
	v_mfma_f32_32x32x16_bf16 v[100:115], v[168:171], v[180:183], v[100:115]
	v_mfma_f32_32x32x16_bf16 v[52:67], v[162:165], v[184:187], v[52:67]
	v_mfma_f32_32x32x16_bf16 v[116:131], v[168:171], v[184:187], v[116:131]
	s_waitcnt vmcnt(0) lgkmcnt(0)
	s_barrier
; #define MFMA32(a, b, c) __builtin_amdgcn_mfma_f32_32x32x16_bf16((a), (b), (c), 0, 0, 0)
; template <bool SWAP, class Epi>
; DI void gemm_tile(const u16* __restrict__ A, int lda, const u16* __restrict__ Bw, int ldb, int K, char* lds, Epi epi) {
;     ...
;   auto compute = [&](int st) {
;     const char* as = lds + st * GEMM_STAGE;
;     const char* bs = as + 36864;
; #pragma unroll
;     for (int ks = 0; ks < 4; ++ks) {
;       bf16x8 af[2], bfr[2];
; #pragma unroll
;       for (int mi = 0; mi < 2; ++mi) af[mi] = *(const bf16x8*)(as + ((wm * 64 + mi * 32 + r) * 72 + ks * 16 + 8 * h) * 2);
; #pragma unroll
;       for (int ni = 0; ni < 2; ++ni) bfr[ni] = *(const bf16x8*)(bs + ((wn * 64 + ni * 32 + r) * 72 + ks * 16 + 8 * h) * 2);
; #pragma unroll
;       for (int mi = 0; mi < 2; ++mi)
; #pragma unroll
;         for (int ni = 0; ni < 2; ++ni) {
;           if (SWAP) acc[mi][ni] = MFMA32(bfr[ni], af[mi], acc[mi][ni]);
;           else acc[mi][ni] = MFMA32(af[mi], bfr[ni], acc[mi][ni]);
;         }
;     }
;   };
;   gload(0, ra0, rb0);
;   lstore(0, ra0, rb0);
;   gload(1, ra1, rb1);
;   __syncthreads();
;   for (int kt = 0; kt < nk; kt += 2) {
;     if (kt + 2 < nk) gload(kt + 2, ra0, rb0);
;     compute(0);
;     lstore(1, ra1, rb1);
;     __syncthreads();
;     if (kt + 3 < nk) gload(kt + 3, ra1, rb1);
;     compute(1);
;     if (kt + 2 < nk) lstore(0, ra0, rb0);
;     __syncthreads();
	ds_read_b128 v[132:135], v210 offset:32768
	ds_read_b128 v[136:139], v210 offset:36864
	ds_read_b128 v[140:143], v214 offset:32768
	ds_read_b128 v[144:147], v214 offset:36864
	ds_read_b128 v[148:151], v214 offset:49152
	ds_read_b128 v[158:161], v214 offset:53248
	s_mov_b32 m0, s44
	s_nop 0
	global_load_lds_dwordx4 v208, s[68:69]
	global_load_lds_dwordx4 v209, s[70:71] offset:1024
	global_load_lds_dwordx4 v208, s[72:73] offset:2048
	global_load_lds_dwordx4 v209, s[74:75] offset:3072
	ds_read_b128 v[162:165], v211 offset:32768
	ds_read_b128 v[168:171], v211 offset:36864
	ds_read_b128 v[172:175], v215 offset:32768
	ds_read_b128 v[176:179], v215 offset:36864
	ds_read_b128 v[180:183], v215 offset:49152
	ds_read_b128 v[184:187], v215 offset:53248
	s_waitcnt lgkmcnt(6)
	v_mfma_f32_32x32x16_bf16 v[4:19], v[132:135], v[140:143], v[4:19]
	v_mfma_f32_32x32x16_bf16 v[68:83], v[136:139], v[140:143], v[68:83]
	v_mfma_f32_32x32x16_bf16 v[20:35], v[132:135], v[144:147], v[20:35]
	v_mfma_f32_32x32x16_bf16 v[84:99], v[136:139], v[144:147], v[84:99]
	v_mfma_f32_32x32x16_bf16 v[36:51], v[132:135], v[148:151], v[36:51]
	v_mfma_f32_32x32x16_bf16 v[100:115], v[136:139], v[148:151], v[100:115]
	v_mfma_f32_32x32x16_bf16 v[52:67], v[132:135], v[158:161], v[52:67]
	v_mfma_f32_32x32x16_bf16 v[116:131], v[136:139], v[158:161], v[116:131]
	s_mov_b32 m0, s46
	s_nop 0
	global_load_lds_dwordx4 v208, s[76:77]
	global_load_lds_dwordx4 v209, s[78:79] offset:1024
	global_load_lds_dwordx4 v208, s[80:81] offset:2048
	global_load_lds_dwordx4 v209, s[82:83] offset:3072
	v_add_u32_e32 v208, 0x80, v208
	v_add_u32_e32 v209, 0x80, v209
	ds_read_b128 v[132:135], v212 offset:32768
	ds_read_b128 v[136:139], v212 offset:36864
	ds_read_b128 v[140:143], v216 offset:32768
	ds_read_b128 v[144:147], v216 offset:36864
	ds_read_b128 v[148:151], v216 offset:49152
	ds_read_b128 v[158:161], v216 offset:53248
	s_waitcnt lgkmcnt(6)
	v_mfma_f32_32x32x16_bf16 v[4:19], v[162:165], v[172:175], v[4:19]
	v_mfma_f32_32x32x16_bf16 v[68:83], v[168:171], v[172:175], v[68:83]
	v_mfma_f32_32x32x16_bf16 v[20:35], v[162:165], v[176:179], v[20:35]
	v_mfma_f32_32x32x16_bf16 v[84:99], v[168:171], v[176:179], v[84:99]
	v_mfma_f32_32x32x16_bf16 v[36:51], v[162:165], v[180:183], v[36:51]
	v_mfma_f32_32x32x16_bf16 v[100:115], v[168:171], v[180:183], v[100:115]
	v_mfma_f32_32x32x16_bf16 v[52:67], v[162:165], v[184:187], v[52:67]
	v_mfma_f32_32x32x16_bf16 v[116:131], v[168:171], v[184:187], v[116:131]
	ds_read_b128 v[162:165], v213 offset:32768
	ds_read_b128 v[168:171], v213 offset:36864
	ds_read_b128 v[172:175], v217 offset:32768
	ds_read_b128 v[176:179], v217 offset:36864
	ds_read_b128 v[180:183], v217 offset:49152
	ds_read_b128 v[184:187], v217 offset:53248
	s_waitcnt lgkmcnt(6)
	v_mfma_f32_32x32x16_bf16 v[4:19], v[132:135], v[140:143], v[4:19]
	v_mfma_f32_32x32x16_bf16 v[68:83], v[136:139], v[140:143], v[68:83]
	v_mfma_f32_32x32x16_bf16 v[20:35], v[132:135], v[144:147], v[20:35]
	v_mfma_f32_32x32x16_bf16 v[84:99], v[136:139], v[144:147], v[84:99]
	v_mfma_f32_32x32x16_bf16 v[36:51], v[132:135], v[148:151], v[36:51]
	v_mfma_f32_32x32x16_bf16 v[100:115], v[136:139], v[148:151], v[100:115]
	v_mfma_f32_32x32x16_bf16 v[52:67], v[132:135], v[158:161], v[52:67]
	v_mfma_f32_32x32x16_bf16 v[116:131], v[136:139], v[158:161], v[116:131]
	s_waitcnt lgkmcnt(0)
	v_mfma_f32_32x32x16_bf16 v[4:19], v[162:165], v[172:175], v[4:19]
	v_mfma_f32_32x32x16_bf16 v[68:83], v[168:171], v[172:175], v[68:83]
	v_mfma_f32_32x32x16_bf16 v[20:35], v[162:165], v[176:179], v[20:35]
	v_mfma_f32_32x32x16_bf16 v[84:99], v[168:171], v[176:179], v[84:99]
	v_mfma_f32_32x32x16_bf16 v[36:51], v[162:165], v[180:183], v[36:51]
	v_mfma_f32_32x32x16_bf16 v[100:115], v[168:171], v[180:183], v[100:115]
	v_mfma_f32_32x32x16_bf16 v[52:67], v[162:165], v[184:187], v[52:67]
	v_mfma_f32_32x32x16_bf16 v[116:131], v[168:171], v[184:187], v[116:131]
	s_waitcnt vmcnt(0) lgkmcnt(0)
	s_barrier
	ds_read_b128 v[132:135], v210 offset:0
	ds_read_b128 v[136:139], v210 offset:4096
	ds_read_b128 v[140:143], v214 offset:0
	ds_read_b128 v[144:147], v214 offset:4096
	ds_read_b128 v[148:151], v214 offset:16384
	ds_read_b128 v[158:161], v214 offset:20480
	s_mov_b32 m0, s45
	s_nop 0
	global_load_lds_dwordx4 v208, s[68:69]
	global_load_lds_dwordx4 v209, s[70:71] offset:1024
	global_load_lds_dwordx4 v208, s[72:73] offset:2048
	global_load_lds_dwordx4 v209, s[74:75] offset:3072
	ds_read_b128 v[162:165], v211 offset:0
	ds_read_b128 v[168:171], v211 offset:4096
	ds_read_b128 v[172:175], v215 offset:0
	ds_read_b128 v[176:179], v215 offset:4096
	ds_read_b128 v[180:183], v215 offset:16384
	ds_read_b128 v[184:187], v215 offset:20480
	s_waitcnt lgkmcnt(6)
	v_mfma_f32_32x32x16_bf16 v[4:19], v[132:135], v[140:143], v[4:19]
	v_mfma_f32_32x32x16_bf16 v[68:83], v[136:139], v[140:143], v[68:83]
	v_mfma_f32_32x32x16_bf16 v[20:35], v[132:135], v[144:147], v[20:35]
	v_mfma_f32_32x32x16_bf16 v[84:99], v[136:139], v[144:147], v[84:99]
	v_mfma_f32_32x32x16_bf16 v[36:51], v[132:135], v[148:151], v[36:51]
	v_mfma_f32_32x32x16_bf16 v[100:115], v[136:139], v[148:151], v[100:115]
	v_mfma_f32_32x32x16_bf16 v[52:67], v[132:135], v[158:161], v[52:67]
	v_mfma_f32_32x32x16_bf16 v[116:131], v[136:139], v[158:161], v[116:131]
	s_mov_b32 m0, s47
	s_nop 0
	global_load_lds_dwordx4 v208, s[76:77]
	global_load_lds_dwordx4 v209, s[78:79] offset:1024
	global_load_lds_dwordx4 v208, s[80:81] offset:2048
	global_load_lds_dwordx4 v209, s[82:83] offset:3072
	v_add_u32_e32 v208, 0x80, v208
	v_add_u32_e32 v209, 0x80, v209
	ds_read_b128 v[132:135], v212 offset:0
	ds_read_b128 v[136:139], v212 offset:4096
	ds_read_b128 v[140:143], v216 offset:0
	ds_read_b128 v[144:147], v216 offset:4096
	ds_read_b128 v[148:151], v216 offset:16384
	ds_read_b128 v[158:161], v216 offset:20480
	s_waitcnt lgkmcnt(6)
; #define MFMA32(a, b, c) __builtin_amdgcn_mfma_f32_32x32x16_bf16((a), (b), (c), 0, 0, 0)
; template <bool SWAP, class Epi>
; DI void gemm_tile(const u16* __restrict__ A, int lda, const u16* __restrict__ Bw, int ldb, int K, char* lds, Epi epi) {
;     ...
;   auto compute = [&](int st) {
;     const char* as = lds + st * GEMM_STAGE;
;     const char* bs = as + 36864;
; #pragma unroll
;     for (int ks = 0; ks < 4; ++ks) {
;       bf16x8 af[2], bfr[2];
; #pragma unroll
;       for (int mi = 0; mi < 2; ++mi) af[mi] = *(const bf16x8*)(as + ((wm * 64 + mi * 32 + r) * 72 + ks * 16 + 8 * h) * 2);
; #pragma unroll
;       for (int ni = 0; ni < 2; ++ni) bfr[ni] = *(const bf16x8*)(bs + ((wn * 64 + ni * 32 + r) * 72 + ks * 16 + 8 * h) * 2);
; #pragma unroll
;       for (int mi = 0; mi < 2; ++mi)
; #pragma unroll
;         for (int ni = 0; ni < 2; ++ni) {
;           if (SWAP) acc[mi][ni] = MFMA32(bfr[ni], af[mi], acc[mi][ni]);
;           else acc[mi][ni] = MFMA32(af[mi], bfr[ni], acc[mi][ni]);
;         }
;     }
;   };
;   gload(0, ra0, rb0);
;   lstore(0, ra0, rb0);
;   gload(1, ra1, rb1);
;   __syncthreads();
;   for (int kt = 0; kt < nk; kt += 2) {
;     if (kt + 2 < nk) gload(kt + 2, ra0, rb0);
;     compute(0);
;     lstore(1, ra1, rb1);
;     __syncthreads();
;     if (kt + 3 < nk) gload(kt + 3, ra1, rb1);
;     compute(1);
;     if (kt + 2 < nk) lstore(0, ra0, rb0);
;     __syncthreads();
	v_mfma_f32_32x32x16_bf16 v[4:19], v[162:165], v[172:175], v[4:19]
	v_mfma_f32_32x32x16_bf16 v[68:83], v[168:171], v[172:175], v[68:83]
	v_mfma_f32_32x32x16_bf16 v[20:35], v[162:165], v[176:179], v[20:35]
	v_mfma_f32_32x32x16_bf16 v[84:99], v[168:171], v[176:179], v[84:99]
	v_mfma_f32_32x32x16_bf16 v[36:51], v[162:165], v[180:183], v[36:51]
	v_mfma_f32_32x32x16_bf16 v[100:115], v[168:171], v[180:183], v[100:115]
	v_mfma_f32_32x32x16_bf16 v[52:67], v[162:165], v[184:187], v[52:67]
	v_mfma_f32_32x32x16_bf16 v[116:131], v[168:171], v[184:187], v[116:131]
	ds_read_b128 v[162:165], v213 offset:0
	ds_read_b128 v[168:171], v213 offset:4096
	ds_read_b128 v[172:175], v217 offset:0
	ds_read_b128 v[176:179], v217 offset:4096
	ds_read_b128 v[180:183], v217 offset:16384
	ds_read_b128 v[184:187], v217 offset:20480
	s_waitcnt lgkmcnt(6)
	v_mfma_f32_32x32x16_bf16 v[4:19], v[132:135], v[140:143], v[4:19]
	v_mfma_f32_32x32x16_bf16 v[68:83], v[136:139], v[140:143], v[68:83]
	v_mfma_f32_32x32x16_bf16 v[20:35], v[132:135], v[144:147], v[20:35]
	v_mfma_f32_32x32x16_bf16 v[84:99], v[136:139], v[144:147], v[84:99]
	v_mfma_f32_32x32x16_bf16 v[36:51], v[132:135], v[148:151], v[36:51]
	v_mfma_f32_32x32x16_bf16 v[100:115], v[136:139], v[148:151], v[100:115]
	v_mfma_f32_32x32x16_bf16 v[52:67], v[132:135], v[158:161], v[52:67]
	v_mfma_f32_32x32x16_bf16 v[116:131], v[136:139], v[158:161], v[116:131]
	s_waitcnt lgkmcnt(0)
	v_mfma_f32_32x32x16_bf16 v[4:19], v[162:165], v[172:175], v[4:19]
	v_mfma_f32_32x32x16_bf16 v[68:83], v[168:171], v[172:175], v[68:83]
	v_mfma_f32_32x32x16_bf16 v[20:35], v[162:165], v[176:179], v[20:35]
	v_mfma_f32_32x32x16_bf16 v[84:99], v[168:171], v[176:179], v[84:99]
	v_mfma_f32_32x32x16_bf16 v[36:51], v[162:165], v[180:183], v[36:51]
	v_mfma_f32_32x32x16_bf16 v[100:115], v[168:171], v[180:183], v[100:115]
	v_mfma_f32_32x32x16_bf16 v[52:67], v[162:165], v[184:187], v[52:67]
	v_mfma_f32_32x32x16_bf16 v[116:131], v[168:171], v[184:187], v[116:131]
	s_waitcnt vmcnt(0) lgkmcnt(0)
	s_barrier
	ds_read_b128 v[132:135], v210 offset:32768
	ds_read_b128 v[136:139], v210 offset:36864
	ds_read_b128 v[140:143], v214 offset:32768
	ds_read_b128 v[144:147], v214 offset:36864
	ds_read_b128 v[148:151], v214 offset:49152
	ds_read_b128 v[158:161], v214 offset:53248
	s_mov_b32 m0, s44
	s_nop 0
	global_load_lds_dwordx4 v208, s[68:69]
	global_load_lds_dwordx4 v209, s[70:71] offset:1024
	global_load_lds_dwordx4 v208, s[72:73] offset:2048
	global_load_lds_dwordx4 v209, s[74:75] offset:3072
	ds_read_b128 v[162:165], v211 offset:32768
	ds_read_b128 v[168:171], v211 offset:36864
	ds_read_b128 v[172:175], v215 offset:32768
	ds_read_b128 v[176:179], v215 offset:36864
	ds_read_b128 v[180:183], v215 offset:49152
	ds_read_b128 v[184:187], v215 offset:53248
	s_waitcnt lgkmcnt(6)
	v_mfma_f32_32x32x16_bf16 v[4:19], v[132:135], v[140:143], v[4:19]
	v_mfma_f32_32x32x16_bf16 v[68:83], v[136:139], v[140:143], v[68:83]
	v_mfma_f32_32x32x16_bf16 v[20:35], v[132:135], v[144:147], v[20:35]
	v_mfma_f32_32x32x16_bf16 v[84:99], v[136:139], v[144:147], v[84:99]
	v_mfma_f32_32x32x16_bf16 v[36:51], v[132:135], v[148:151], v[36:51]
	v_mfma_f32_32x32x16_bf16 v[100:115], v[136:139], v[148:151], v[100:115]
	v_mfma_f32_32x32x16_bf16 v[52:67], v[132:135], v[158:161], v[52:67]
	v_mfma_f32_32x32x16_bf16 v[116:131], v[136:139], v[158:161], v[116:131]
	s_mov_b32 m0, s46
	s_nop 0
	global_load_lds_dwordx4 v208, s[76:77]
	global_load_lds_dwordx4 v209, s[78:79] offset:1024
	global_load_lds_dwordx4 v208, s[80:81] offset:2048
	global_load_lds_dwordx4 v209, s[82:83] offset:3072
	v_add_u32_e32 v208, 0x80, v208
	v_add_u32_e32 v209, 0x80, v209
	ds_read_b128 v[132:135], v212 offset:32768
	ds_read_b128 v[136:139], v212 offset:36864
	ds_read_b128 v[140:143], v216 offset:32768
	ds_read_b128 v[144:147], v216 offset:36864
	ds_read_b128 v[148:151], v216 offset:49152
	ds_read_b128 v[158:161], v216 offset:53248
	s_waitcnt lgkmcnt(6)
	v_mfma_f32_32x32x16_bf16 v[4:19], v[162:165], v[172:175], v[4:19]
	v_mfma_f32_32x32x16_bf16 v[68:83], v[168:171], v[172:175], v[68:83]
	v_mfma_f32_32x32x16_bf16 v[20:35], v[162:165], v[176:179], v[20:35]
	v_mfma_f32_32x32x16_bf16 v[84:99], v[168:171], v[176:179], v[84:99]
	v_mfma_f32_32x32x16_bf16 v[36:51], v[162:165], v[180:183], v[36:51]
	v_mfma_f32_32x32x16_bf16 v[100:115], v[168:171], v[180:183], v[100:115]
	v_mfma_f32_32x32x16_bf16 v[52:67], v[162:165], v[184:187], v[52:67]
	v_mfma_f32_32x32x16_bf16 v[116:131], v[168:171], v[184:187], v[116:131]
	ds_read_b128 v[162:165], v213 offset:32768
	ds_read_b128 v[168:171], v213 offset:36864
	ds_read_b128 v[172:175], v217 offset:32768
	ds_read_b128 v[176:179], v217 offset:36864
	ds_read_b128 v[180:183], v217 offset:49152
	ds_read_b128 v[184:187], v217 offset:53248
	s_waitcnt lgkmcnt(6)
	v_mfma_f32_32x32x16_bf16 v[4:19], v[132:135], v[140:143], v[4:19]
	v_mfma_f32_32x32x16_bf16 v[68:83], v[136:139], v[140:143], v[68:83]
	v_mfma_f32_32x32x16_bf16 v[20:35], v[132:135], v[144:147], v[20:35]
	v_mfma_f32_32x32x16_bf16 v[84:99], v[136:139], v[144:147], v[84:99]
	v_mfma_f32_32x32x16_bf16 v[36:51], v[132:135], v[148:151], v[36:51]
	v_mfma_f32_32x32x16_bf16 v[100:115], v[136:139], v[148:151], v[100:115]
	v_mfma_f32_32x32x16_bf16 v[52:67], v[132:135], v[158:161], v[52:67]
	v_mfma_f32_32x32x16_bf16 v[116:131], v[136:139], v[158:161], v[116:131]
	s_waitcnt lgkmcnt(0)
	v_mfma_f32_32x32x16_bf16 v[4:19], v[162:165], v[172:175], v[4:19]
	v_mfma_f32_32x32x16_bf16 v[68:83], v[168:171], v[172:175], v[68:83]
	v_mfma_f32_32x32x16_bf16 v[20:35], v[162:165], v[176:179], v[20:35]
	v_mfma_f32_32x32x16_bf16 v[84:99], v[168:171], v[176:179], v[84:99]
	v_mfma_f32_32x32x16_bf16 v[36:51], v[162:165], v[180:183], v[36:51]
	v_mfma_f32_32x32x16_bf16 v[100:115], v[168:171], v[180:183], v[100:115]
	v_mfma_f32_32x32x16_bf16 v[52:67], v[162:165], v[184:187], v[52:67]
	v_mfma_f32_32x32x16_bf16 v[116:131], v[168:171], v[184:187], v[116:131]
	s_waitcnt vmcnt(0) lgkmcnt(0)
	s_barrier
; #define MFMA32(a, b, c) __builtin_amdgcn_mfma_f32_32x32x16_bf16((a), (b), (c), 0, 0, 0)
; template <bool SWAP, class Epi>
; DI void gemm_tile(const u16* __restrict__ A, int lda, const u16* __restrict__ Bw, int ldb, int K, char* lds, Epi epi) {
;     ...
;   auto compute = [&](int st) {
;     const char* as = lds + st * GEMM_STAGE;
;     const char* bs = as + 36864;
; #pragma unroll
;     for (int ks = 0; ks < 4; ++ks) {
;       bf16x8 af[2], bfr[2];
; #pragma unroll
;       for (int mi = 0; mi < 2; ++mi) af[mi] = *(const bf16x8*)(as + ((wm * 64 + mi * 32 + r) * 72 + ks * 16 + 8 * h) * 2);
; #pragma unroll
;       for (int ni = 0; ni < 2; ++ni) bfr[ni] = *(const bf16x8*)(bs + ((wn * 64 + ni * 32 + r) * 72 + ks * 16 + 8 * h) * 2);
; #pragma unroll
;       for (int mi = 0; mi < 2; ++mi)
; #pragma unroll
;         for (int ni = 0; ni < 2; ++ni) {
;           if (SWAP) acc[mi][ni] = MFMA32(bfr[ni], af[mi], acc[mi][ni]);
;           else acc[mi][ni] = MFMA32(af[mi], bfr[ni], acc[mi][ni]);
;         }
;     }
;   };
;   gload(0, ra0, rb0);
;   lstore(0, ra0, rb0);
;   gload(1, ra1, rb1);
;   __syncthreads();
;   for (int kt = 0; kt < nk; kt += 2) {
;     if (kt + 2 < nk) gload(kt + 2, ra0, rb0);
;     compute(0);
;     lstore(1, ra1, rb1);
;     __syncthreads();
;     if (kt + 3 < nk) gload(kt + 3, ra1, rb1);
;     compute(1);
;     if (kt + 2 < nk) lstore(0, ra0, rb0);
;     __syncthreads();
	ds_read_b128 v[132:135], v210 offset:0
	ds_read_b128 v[136:139], v210 offset:4096
	ds_read_b128 v[140:143], v214 offset:0
	ds_read_b128 v[144:147], v214 offset:4096
	ds_read_b128 v[148:151], v214 offset:16384
	ds_read_b128 v[158:161], v214 offset:20480
	s_mov_b32 m0, s45
	s_nop 0
	global_load_lds_dwordx4 v208, s[68:69]
	global_load_lds_dwordx4 v209, s[70:71] offset:1024
	global_load_lds_dwordx4 v208, s[72:73] offset:2048
	global_load_lds_dwordx4 v209, s[74:75] offset:3072
	ds_read_b128 v[162:165], v211 offset:0
	ds_read_b128 v[168:171], v211 offset:4096
	ds_read_b128 v[172:175], v215 offset:0
	ds_read_b128 v[176:179], v215 offset:4096
	ds_read_b128 v[180:183], v215 offset:16384
	ds_read_b128 v[184:187], v215 offset:20480
	s_waitcnt lgkmcnt(6)
	v_mfma_f32_32x32x16_bf16 v[4:19], v[132:135], v[140:143], v[4:19]
	v_mfma_f32_32x32x16_bf16 v[68:83], v[136:139], v[140:143], v[68:83]
	v_mfma_f32_32x32x16_bf16 v[20:35], v[132:135], v[144:147], v[20:35]
	v_mfma_f32_32x32x16_bf16 v[84:99], v[136:139], v[144:147], v[84:99]
	v_mfma_f32_32x32x16_bf16 v[36:51], v[132:135], v[148:151], v[36:51]
	v_mfma_f32_32x32x16_bf16 v[100:115], v[136:139], v[148:151], v[100:115]
	v_mfma_f32_32x32x16_bf16 v[52:67], v[132:135], v[158:161], v[52:67]
	v_mfma_f32_32x32x16_bf16 v[116:131], v[136:139], v[158:161], v[116:131]
	s_mov_b32 m0, s47
	s_nop 0
	global_load_lds_dwordx4 v208, s[76:77]
	global_load_lds_dwordx4 v209, s[78:79] offset:1024
	global_load_lds_dwordx4 v208, s[80:81] offset:2048
	global_load_lds_dwordx4 v209, s[82:83] offset:3072
	v_add_u32_e32 v208, 0x80, v208
	v_add_u32_e32 v209, 0x80, v209
	ds_read_b128 v[132:135], v212 offset:0
	ds_read_b128 v[136:139], v212 offset:4096
	ds_read_b128 v[140:143], v216 offset:0
	ds_read_b128 v[144:147], v216 offset:4096
	ds_read_b128 v[148:151], v216 offset:16384
	ds_read_b128 v[158:161], v216 offset:20480
	s_waitcnt lgkmcnt(6)
	v_mfma_f32_32x32x16_bf16 v[4:19], v[162:165], v[172:175], v[4:19]
	v_mfma_f32_32x32x16_bf16 v[68:83], v[168:171], v[172:175], v[68:83]
	v_mfma_f32_32x32x16_bf16 v[20:35], v[162:165], v[176:179], v[20:35]
	v_mfma_f32_32x32x16_bf16 v[84:99], v[168:171], v[176:179], v[84:99]
	v_mfma_f32_32x32x16_bf16 v[36:51], v[162:165], v[180:183], v[36:51]
	v_mfma_f32_32x32x16_bf16 v[100:115], v[168:171], v[180:183], v[100:115]
	v_mfma_f32_32x32x16_bf16 v[52:67], v[162:165], v[184:187], v[52:67]
	v_mfma_f32_32x32x16_bf16 v[116:131], v[168:171], v[184:187], v[116:131]
	ds_read_b128 v[162:165], v213 offset:0
	ds_read_b128 v[168:171], v213 offset:4096
	ds_read_b128 v[172:175], v217 offset:0
	ds_read_b128 v[176:179], v217 offset:4096
	ds_read_b128 v[180:183], v217 offset:16384
	ds_read_b128 v[184:187], v217 offset:20480
	s_waitcnt lgkmcnt(6)
	v_mfma_f32_32x32x16_bf16 v[4:19], v[132:135], v[140:143], v[4:19]
	v_mfma_f32_32x32x16_bf16 v[68:83], v[136:139], v[140:143], v[68:83]
	v_mfma_f32_32x32x16_bf16 v[20:35], v[132:135], v[144:147], v[20:35]
	v_mfma_f32_32x32x16_bf16 v[84:99], v[136:139], v[144:147], v[84:99]
	v_mfma_f32_32x32x16_bf16 v[36:51], v[132:135], v[148:151], v[36:51]
	v_mfma_f32_32x32x16_bf16 v[100:115], v[136:139], v[148:151], v[100:115]
	v_mfma_f32_32x32x16_bf16 v[52:67], v[132:135], v[158:161], v[52:67]
	v_mfma_f32_32x32x16_bf16 v[116:131], v[136:139], v[158:161], v[116:131]
	s_waitcnt lgkmcnt(0)
	v_mfma_f32_32x32x16_bf16 v[4:19], v[162:165], v[172:175], v[4:19]
	v_mfma_f32_32x32x16_bf16 v[68:83], v[168:171], v[172:175], v[68:83]
	v_mfma_f32_32x32x16_bf16 v[20:35], v[162:165], v[176:179], v[20:35]
	v_mfma_f32_32x32x16_bf16 v[84:99], v[168:171], v[176:179], v[84:99]
	v_mfma_f32_32x32x16_bf16 v[36:51], v[162:165], v[180:183], v[36:51]
	v_mfma_f32_32x32x16_bf16 v[100:115], v[168:171], v[180:183], v[100:115]
	v_mfma_f32_32x32x16_bf16 v[52:67], v[162:165], v[184:187], v[52:67]
	v_mfma_f32_32x32x16_bf16 v[116:131], v[168:171], v[184:187], v[116:131]
	s_waitcnt vmcnt(0) lgkmcnt(0)
	s_barrier
	ds_read_b128 v[132:135], v210 offset:32768
	ds_read_b128 v[136:139], v210 offset:36864
	ds_read_b128 v[140:143], v214 offset:32768
	ds_read_b128 v[144:147], v214 offset:36864
	ds_read_b128 v[148:151], v214 offset:49152
	ds_read_b128 v[158:161], v214 offset:53248
	s_mov_b32 m0, s44
	s_nop 0
	global_load_lds_dwordx4 v208, s[68:69]
	global_load_lds_dwordx4 v209, s[70:71] offset:1024
	global_load_lds_dwordx4 v208, s[72:73] offset:2048
	global_load_lds_dwordx4 v209, s[74:75] offset:3072
	ds_read_b128 v[162:165], v211 offset:32768
	ds_read_b128 v[168:171], v211 offset:36864
	ds_read_b128 v[172:175], v215 offset:32768
	ds_read_b128 v[176:179], v215 offset:36864
	ds_read_b128 v[180:183], v215 offset:49152
	ds_read_b128 v[184:187], v215 offset:53248
	s_waitcnt lgkmcnt(6)
	v_mfma_f32_32x32x16_bf16 v[4:19], v[132:135], v[140:143], v[4:19]
	v_mfma_f32_32x32x16_bf16 v[68:83], v[136:139], v[140:143], v[68:83]
	v_mfma_f32_32x32x16_bf16 v[20:35], v[132:135], v[144:147], v[20:35]
	v_mfma_f32_32x32x16_bf16 v[84:99], v[136:139], v[144:147], v[84:99]
	v_mfma_f32_32x32x16_bf16 v[36:51], v[132:135], v[148:151], v[36:51]
	v_mfma_f32_32x32x16_bf16 v[100:115], v[136:139], v[148:151], v[100:115]
	v_mfma_f32_32x32x16_bf16 v[52:67], v[132:135], v[158:161], v[52:67]
	v_mfma_f32_32x32x16_bf16 v[116:131], v[136:139], v[158:161], v[116:131]
	s_mov_b32 m0, s46
	s_nop 0
	global_load_lds_dwordx4 v208, s[76:77]
	global_load_lds_dwordx4 v209, s[78:79] offset:1024
	global_load_lds_dwordx4 v208, s[80:81] offset:2048
	global_load_lds_dwordx4 v209, s[82:83] offset:3072
	v_add_u32_e32 v208, 0x80, v208
	v_add_u32_e32 v209, 0x80, v209
	ds_read_b128 v[132:135], v212 offset:32768
	ds_read_b128 v[136:139], v212 offset:36864
	ds_read_b128 v[140:143], v216 offset:32768
	ds_read_b128 v[144:147], v216 offset:36864
	ds_read_b128 v[148:151], v216 offset:49152
	ds_read_b128 v[158:161], v216 offset:53248
	s_waitcnt lgkmcnt(6)
; #define MFMA32(a, b, c) __builtin_amdgcn_mfma_f32_32x32x16_bf16((a), (b), (c), 0, 0, 0)
; template <bool SWAP, class Epi>
; DI void gemm_tile(const u16* __restrict__ A, int lda, const u16* __restrict__ Bw, int ldb, int K, char* lds, Epi epi) {
;     ...
;   auto compute = [&](int st) {
;     const char* as = lds + st * GEMM_STAGE;
;     const char* bs = as + 36864;
; #pragma unroll
;     for (int ks = 0; ks < 4; ++ks) {
;       bf16x8 af[2], bfr[2];
; #pragma unroll
;       for (int mi = 0; mi < 2; ++mi) af[mi] = *(const bf16x8*)(as + ((wm * 64 + mi * 32 + r) * 72 + ks * 16 + 8 * h) * 2);
; #pragma unroll
;       for (int ni = 0; ni < 2; ++ni) bfr[ni] = *(const bf16x8*)(bs + ((wn * 64 + ni * 32 + r) * 72 + ks * 16 + 8 * h) * 2);
; #pragma unroll
;       for (int mi = 0; mi < 2; ++mi)
; #pragma unroll
;         for (int ni = 0; ni < 2; ++ni) {
;           if (SWAP) acc[mi][ni] = MFMA32(bfr[ni], af[mi], acc[mi][ni]);
;           else acc[mi][ni] = MFMA32(af[mi], bfr[ni], acc[mi][ni]);
;         }
;     }
;   };
;   gload(0, ra0, rb0);
;   lstore(0, ra0, rb0);
;   gload(1, ra1, rb1);
;   __syncthreads();
;   for (int kt = 0; kt < nk; kt += 2) {
;     if (kt + 2 < nk) gload(kt + 2, ra0, rb0);
;     compute(0);
;     lstore(1, ra1, rb1);
;     __syncthreads();
;     if (kt + 3 < nk) gload(kt + 3, ra1, rb1);
;     compute(1);
;     if (kt + 2 < nk) lstore(0, ra0, rb0);
;     __syncthreads();
	v_mfma_f32_32x32x16_bf16 v[4:19], v[162:165], v[172:175], v[4:19]
	v_mfma_f32_32x32x16_bf16 v[68:83], v[168:171], v[172:175], v[68:83]
	v_mfma_f32_32x32x16_bf16 v[20:35], v[162:165], v[176:179], v[20:35]
	v_mfma_f32_32x32x16_bf16 v[84:99], v[168:171], v[176:179], v[84:99]
	v_mfma_f32_32x32x16_bf16 v[36:51], v[162:165], v[180:183], v[36:51]
	v_mfma_f32_32x32x16_bf16 v[100:115], v[168:171], v[180:183], v[100:115]
	v_mfma_f32_32x32x16_bf16 v[52:67], v[162:165], v[184:187], v[52:67]
	v_mfma_f32_32x32x16_bf16 v[116:131], v[168:171], v[184:187], v[116:131]
	ds_read_b128 v[162:165], v213 offset:32768
	ds_read_b128 v[168:171], v213 offset:36864
	ds_read_b128 v[172:175], v217 offset:32768
	ds_read_b128 v[176:179], v217 offset:36864
	ds_read_b128 v[180:183], v217 offset:49152
	ds_read_b128 v[184:187], v217 offset:53248
	s_waitcnt lgkmcnt(6)
	v_mfma_f32_32x32x16_bf16 v[4:19], v[132:135], v[140:143], v[4:19]
	v_mfma_f32_32x32x16_bf16 v[68:83], v[136:139], v[140:143], v[68:83]
	v_mfma_f32_32x32x16_bf16 v[20:35], v[132:135], v[144:147], v[20:35]
	v_mfma_f32_32x32x16_bf16 v[84:99], v[136:139], v[144:147], v[84:99]
	v_mfma_f32_32x32x16_bf16 v[36:51], v[132:135], v[148:151], v[36:51]
	v_mfma_f32_32x32x16_bf16 v[100:115], v[136:139], v[148:151], v[100:115]
	v_mfma_f32_32x32x16_bf16 v[52:67], v[132:135], v[158:161], v[52:67]
	v_mfma_f32_32x32x16_bf16 v[116:131], v[136:139], v[158:161], v[116:131]
	s_waitcnt lgkmcnt(0)
	v_mfma_f32_32x32x16_bf16 v[4:19], v[162:165], v[172:175], v[4:19]
	v_mfma_f32_32x32x16_bf16 v[68:83], v[168:171], v[172:175], v[68:83]
	v_mfma_f32_32x32x16_bf16 v[20:35], v[162:165], v[176:179], v[20:35]
	v_mfma_f32_32x32x16_bf16 v[84:99], v[168:171], v[176:179], v[84:99]
	v_mfma_f32_32x32x16_bf16 v[36:51], v[162:165], v[180:183], v[36:51]
	v_mfma_f32_32x32x16_bf16 v[100:115], v[168:171], v[180:183], v[100:115]
	v_mfma_f32_32x32x16_bf16 v[52:67], v[162:165], v[184:187], v[52:67]
	v_mfma_f32_32x32x16_bf16 v[116:131], v[168:171], v[184:187], v[116:131]
	s_waitcnt vmcnt(0) lgkmcnt(0)
	s_barrier
	ds_read_b128 v[132:135], v210 offset:0
	ds_read_b128 v[136:139], v210 offset:4096
	ds_read_b128 v[140:143], v214 offset:0
	ds_read_b128 v[144:147], v214 offset:4096
	ds_read_b128 v[148:151], v214 offset:16384
	ds_read_b128 v[158:161], v214 offset:20480
	s_mov_b32 m0, s45
	s_nop 0
	global_load_lds_dwordx4 v208, s[68:69]
	global_load_lds_dwordx4 v209, s[70:71] offset:1024
	global_load_lds_dwordx4 v208, s[72:73] offset:2048
	global_load_lds_dwordx4 v209, s[74:75] offset:3072
	ds_read_b128 v[162:165], v211 offset:0
	ds_read_b128 v[168:171], v211 offset:4096
	ds_read_b128 v[172:175], v215 offset:0
	ds_read_b128 v[176:179], v215 offset:4096
	ds_read_b128 v[180:183], v215 offset:16384
	ds_read_b128 v[184:187], v215 offset:20480
	s_waitcnt lgkmcnt(6)
	v_mfma_f32_32x32x16_bf16 v[4:19], v[132:135], v[140:143], v[4:19]
	v_mfma_f32_32x32x16_bf16 v[68:83], v[136:139], v[140:143], v[68:83]
	v_mfma_f32_32x32x16_bf16 v[20:35], v[132:135], v[144:147], v[20:35]
	v_mfma_f32_32x32x16_bf16 v[84:99], v[136:139], v[144:147], v[84:99]
	v_mfma_f32_32x32x16_bf16 v[36:51], v[132:135], v[148:151], v[36:51]
	v_mfma_f32_32x32x16_bf16 v[100:115], v[136:139], v[148:151], v[100:115]
	v_mfma_f32_32x32x16_bf16 v[52:67], v[132:135], v[158:161], v[52:67]
	v_mfma_f32_32x32x16_bf16 v[116:131], v[136:139], v[158:161], v[116:131]
	s_mov_b32 m0, s47
	s_nop 0
	global_load_lds_dwordx4 v208, s[76:77]
	global_load_lds_dwordx4 v209, s[78:79] offset:1024
	global_load_lds_dwordx4 v208, s[80:81] offset:2048
	global_load_lds_dwordx4 v209, s[82:83] offset:3072
	v_add_u32_e32 v208, 0x80, v208
	v_add_u32_e32 v209, 0x80, v209
	ds_read_b128 v[132:135], v212 offset:0
	ds_read_b128 v[136:139], v212 offset:4096
	ds_read_b128 v[140:143], v216 offset:0
	ds_read_b128 v[144:147], v216 offset:4096
	ds_read_b128 v[148:151], v216 offset:16384
	ds_read_b128 v[158:161], v216 offset:20480
	s_waitcnt lgkmcnt(6)
	v_mfma_f32_32x32x16_bf16 v[4:19], v[162:165], v[172:175], v[4:19]
	v_mfma_f32_32x32x16_bf16 v[68:83], v[168:171], v[172:175], v[68:83]
	v_mfma_f32_32x32x16_bf16 v[20:35], v[162:165], v[176:179], v[20:35]
	v_mfma_f32_32x32x16_bf16 v[84:99], v[168:171], v[176:179], v[84:99]
	v_mfma_f32_32x32x16_bf16 v[36:51], v[162:165], v[180:183], v[36:51]
	v_mfma_f32_32x32x16_bf16 v[100:115], v[168:171], v[180:183], v[100:115]
	v_mfma_f32_32x32x16_bf16 v[52:67], v[162:165], v[184:187], v[52:67]
	v_mfma_f32_32x32x16_bf16 v[116:131], v[168:171], v[184:187], v[116:131]
	ds_read_b128 v[162:165], v213 offset:0
	ds_read_b128 v[168:171], v213 offset:4096
	ds_read_b128 v[172:175], v217 offset:0
	ds_read_b128 v[176:179], v217 offset:4096
	ds_read_b128 v[180:183], v217 offset:16384
	ds_read_b128 v[184:187], v217 offset:20480
	s_waitcnt lgkmcnt(6)
	v_mfma_f32_32x32x16_bf16 v[4:19], v[132:135], v[140:143], v[4:19]
	v_mfma_f32_32x32x16_bf16 v[68:83], v[136:139], v[140:143], v[68:83]
	v_mfma_f32_32x32x16_bf16 v[20:35], v[132:135], v[144:147], v[20:35]
	v_mfma_f32_32x32x16_bf16 v[84:99], v[136:139], v[144:147], v[84:99]
	v_mfma_f32_32x32x16_bf16 v[36:51], v[132:135], v[148:151], v[36:51]
	v_mfma_f32_32x32x16_bf16 v[100:115], v[136:139], v[148:151], v[100:115]
	v_mfma_f32_32x32x16_bf16 v[52:67], v[132:135], v[158:161], v[52:67]
	v_mfma_f32_32x32x16_bf16 v[116:131], v[136:139], v[158:161], v[116:131]
	s_waitcnt lgkmcnt(0)
	v_mfma_f32_32x32x16_bf16 v[4:19], v[162:165], v[172:175], v[4:19]
	v_mfma_f32_32x32x16_bf16 v[68:83], v[168:171], v[172:175], v[68:83]
	v_mfma_f32_32x32x16_bf16 v[20:35], v[162:165], v[176:179], v[20:35]
	v_mfma_f32_32x32x16_bf16 v[84:99], v[168:171], v[176:179], v[84:99]
	v_mfma_f32_32x32x16_bf16 v[36:51], v[162:165], v[180:183], v[36:51]
	v_mfma_f32_32x32x16_bf16 v[100:115], v[168:171], v[180:183], v[100:115]
	v_mfma_f32_32x32x16_bf16 v[52:67], v[162:165], v[184:187], v[52:67]
	v_mfma_f32_32x32x16_bf16 v[116:131], v[168:171], v[184:187], v[116:131]
	s_waitcnt vmcnt(0) lgkmcnt(0)
	s_barrier
; #define MFMA32(a, b, c) __builtin_amdgcn_mfma_f32_32x32x16_bf16((a), (b), (c), 0, 0, 0)
; template <bool SWAP, class Epi>
; DI void gemm_tile(const u16* __restrict__ A, int lda, const u16* __restrict__ Bw, int ldb, int K, char* lds, Epi epi) {
;     ...
;   auto compute = [&](int st) {
;     const char* as = lds + st * GEMM_STAGE;
;     const char* bs = as + 36864;
; #pragma unroll
;     for (int ks = 0; ks < 4; ++ks) {
;       bf16x8 af[2], bfr[2];
; #pragma unroll
;       for (int mi = 0; mi < 2; ++mi) af[mi] = *(const bf16x8*)(as + ((wm * 64 + mi * 32 + r) * 72 + ks * 16 + 8 * h) * 2);
; #pragma unroll
;       for (int ni = 0; ni < 2; ++ni) bfr[ni] = *(const bf16x8*)(bs + ((wn * 64 + ni * 32 + r) * 72 + ks * 16 + 8 * h) * 2);
; #pragma unroll
;       for (int mi = 0; mi < 2; ++mi)
; #pragma unroll
;         for (int ni = 0; ni < 2; ++ni) {
;           if (SWAP) acc[mi][ni] = MFMA32(bfr[ni], af[mi], acc[mi][ni]);
;           else acc[mi][ni] = MFMA32(af[mi], bfr[ni], acc[mi][ni]);
;         }
;     }
;   };
;   gload(0, ra0, rb0);
;   lstore(0, ra0, rb0);
;   gload(1, ra1, rb1);
;   __syncthreads();
;   for (int kt = 0; kt < nk; kt += 2) {
;     if (kt + 2 < nk) gload(kt + 2, ra0, rb0);
;     compute(0);
;     lstore(1, ra1, rb1);
;     __syncthreads();
;     if (kt + 3 < nk) gload(kt + 3, ra1, rb1);
;     compute(1);
;     if (kt + 2 < nk) lstore(0, ra0, rb0);
;     __syncthreads();
	ds_read_b128 v[132:135], v210 offset:32768
	ds_read_b128 v[136:139], v210 offset:36864
	ds_read_b128 v[140:143], v214 offset:32768
	ds_read_b128 v[144:147], v214 offset:36864
	ds_read_b128 v[148:151], v214 offset:49152
	ds_read_b128 v[158:161], v214 offset:53248
	s_mov_b32 m0, s44
	s_nop 0
	global_load_lds_dwordx4 v208, s[68:69]
	global_load_lds_dwordx4 v209, s[70:71] offset:1024
	global_load_lds_dwordx4 v208, s[72:73] offset:2048
	global_load_lds_dwordx4 v209, s[74:75] offset:3072
	ds_read_b128 v[162:165], v211 offset:32768
	ds_read_b128 v[168:171], v211 offset:36864
	ds_read_b128 v[172:175], v215 offset:32768
	ds_read_b128 v[176:179], v215 offset:36864
	ds_read_b128 v[180:183], v215 offset:49152
	ds_read_b128 v[184:187], v215 offset:53248
	s_waitcnt lgkmcnt(6)
	v_mfma_f32_32x32x16_bf16 v[4:19], v[132:135], v[140:143], v[4:19]
	v_mfma_f32_32x32x16_bf16 v[68:83], v[136:139], v[140:143], v[68:83]
	v_mfma_f32_32x32x16_bf16 v[20:35], v[132:135], v[144:147], v[20:35]
	v_mfma_f32_32x32x16_bf16 v[84:99], v[136:139], v[144:147], v[84:99]
	v_mfma_f32_32x32x16_bf16 v[36:51], v[132:135], v[148:151], v[36:51]
	v_mfma_f32_32x32x16_bf16 v[100:115], v[136:139], v[148:151], v[100:115]
	v_mfma_f32_32x32x16_bf16 v[52:67], v[132:135], v[158:161], v[52:67]
	v_mfma_f32_32x32x16_bf16 v[116:131], v[136:139], v[158:161], v[116:131]
	s_mov_b32 m0, s46
	s_nop 0
	global_load_lds_dwordx4 v208, s[76:77]
	global_load_lds_dwordx4 v209, s[78:79] offset:1024
	global_load_lds_dwordx4 v208, s[80:81] offset:2048
	global_load_lds_dwordx4 v209, s[82:83] offset:3072
	v_add_u32_e32 v208, 0x80, v208
	v_add_u32_e32 v209, 0x80, v209
	ds_read_b128 v[132:135], v212 offset:32768
	ds_read_b128 v[136:139], v212 offset:36864
	ds_read_b128 v[140:143], v216 offset:32768
	ds_read_b128 v[144:147], v216 offset:36864
	ds_read_b128 v[148:151], v216 offset:49152
	ds_read_b128 v[158:161], v216 offset:53248
	s_waitcnt lgkmcnt(6)
	v_mfma_f32_32x32x16_bf16 v[4:19], v[162:165], v[172:175], v[4:19]
	v_mfma_f32_32x32x16_bf16 v[68:83], v[168:171], v[172:175], v[68:83]
	v_mfma_f32_32x32x16_bf16 v[20:35], v[162:165], v[176:179], v[20:35]
	v_mfma_f32_32x32x16_bf16 v[84:99], v[168:171], v[176:179], v[84:99]
	v_mfma_f32_32x32x16_bf16 v[36:51], v[162:165], v[180:183], v[36:51]
	v_mfma_f32_32x32x16_bf16 v[100:115], v[168:171], v[180:183], v[100:115]
	v_mfma_f32_32x32x16_bf16 v[52:67], v[162:165], v[184:187], v[52:67]
	v_mfma_f32_32x32x16_bf16 v[116:131], v[168:171], v[184:187], v[116:131]
	ds_read_b128 v[162:165], v213 offset:32768
	ds_read_b128 v[168:171], v213 offset:36864
	ds_read_b128 v[172:175], v217 offset:32768
	ds_read_b128 v[176:179], v217 offset:36864
	ds_read_b128 v[180:183], v217 offset:49152
	ds_read_b128 v[184:187], v217 offset:53248
	s_waitcnt lgkmcnt(6)
	v_mfma_f32_32x32x16_bf16 v[4:19], v[132:135], v[140:143], v[4:19]
	v_mfma_f32_32x32x16_bf16 v[68:83], v[136:139], v[140:143], v[68:83]
	v_mfma_f32_32x32x16_bf16 v[20:35], v[132:135], v[144:147], v[20:35]
	v_mfma_f32_32x32x16_bf16 v[84:99], v[136:139], v[144:147], v[84:99]
	v_mfma_f32_32x32x16_bf16 v[36:51], v[132:135], v[148:151], v[36:51]
	v_mfma_f32_32x32x16_bf16 v[100:115], v[136:139], v[148:151], v[100:115]
	v_mfma_f32_32x32x16_bf16 v[52:67], v[132:135], v[158:161], v[52:67]
	v_mfma_f32_32x32x16_bf16 v[116:131], v[136:139], v[158:161], v[116:131]
	s_waitcnt lgkmcnt(0)
	v_mfma_f32_32x32x16_bf16 v[4:19], v[162:165], v[172:175], v[4:19]
	v_mfma_f32_32x32x16_bf16 v[68:83], v[168:171], v[172:175], v[68:83]
	v_mfma_f32_32x32x16_bf16 v[20:35], v[162:165], v[176:179], v[20:35]
	v_mfma_f32_32x32x16_bf16 v[84:99], v[168:171], v[176:179], v[84:99]
	v_mfma_f32_32x32x16_bf16 v[36:51], v[162:165], v[180:183], v[36:51]
	v_mfma_f32_32x32x16_bf16 v[100:115], v[168:171], v[180:183], v[100:115]
	v_mfma_f32_32x32x16_bf16 v[52:67], v[162:165], v[184:187], v[52:67]
	v_mfma_f32_32x32x16_bf16 v[116:131], v[168:171], v[184:187], v[116:131]
	s_waitcnt vmcnt(0) lgkmcnt(0)
	s_barrier
	ds_read_b128 v[132:135], v210 offset:0
	ds_read_b128 v[136:139], v210 offset:4096
	ds_read_b128 v[140:143], v214 offset:0
	ds_read_b128 v[144:147], v214 offset:4096
	ds_read_b128 v[148:151], v214 offset:16384
	ds_read_b128 v[158:161], v214 offset:20480
	s_mov_b32 m0, s45
	s_nop 0
	global_load_lds_dwordx4 v208, s[68:69]
	global_load_lds_dwordx4 v209, s[70:71] offset:1024
	global_load_lds_dwordx4 v208, s[72:73] offset:2048
	global_load_lds_dwordx4 v209, s[74:75] offset:3072
	ds_read_b128 v[162:165], v211 offset:0
	ds_read_b128 v[168:171], v211 offset:4096
	ds_read_b128 v[172:175], v215 offset:0
	ds_read_b128 v[176:179], v215 offset:4096
	ds_read_b128 v[180:183], v215 offset:16384
	ds_read_b128 v[184:187], v215 offset:20480
	s_waitcnt lgkmcnt(6)
	v_mfma_f32_32x32x16_bf16 v[4:19], v[132:135], v[140:143], v[4:19]
	v_mfma_f32_32x32x16_bf16 v[68:83], v[136:139], v[140:143], v[68:83]
	v_mfma_f32_32x32x16_bf16 v[20:35], v[132:135], v[144:147], v[20:35]
	v_mfma_f32_32x32x16_bf16 v[84:99], v[136:139], v[144:147], v[84:99]
	v_mfma_f32_32x32x16_bf16 v[36:51], v[132:135], v[148:151], v[36:51]
	v_mfma_f32_32x32x16_bf16 v[100:115], v[136:139], v[148:151], v[100:115]
	v_mfma_f32_32x32x16_bf16 v[52:67], v[132:135], v[158:161], v[52:67]
	v_mfma_f32_32x32x16_bf16 v[116:131], v[136:139], v[158:161], v[116:131]
	s_mov_b32 m0, s47
	s_nop 0
	global_load_lds_dwordx4 v208, s[76:77]
	global_load_lds_dwordx4 v209, s[78:79] offset:1024
	global_load_lds_dwordx4 v208, s[80:81] offset:2048
	global_load_lds_dwordx4 v209, s[82:83] offset:3072
	v_add_u32_e32 v208, 0x80, v208
	v_add_u32_e32 v209, 0x80, v209
	ds_read_b128 v[132:135], v212 offset:0
	ds_read_b128 v[136:139], v212 offset:4096
	ds_read_b128 v[140:143], v216 offset:0
	ds_read_b128 v[144:147], v216 offset:4096
	ds_read_b128 v[148:151], v216 offset:16384
	ds_read_b128 v[158:161], v216 offset:20480
	s_waitcnt lgkmcnt(6)
; #define MFMA32(a, b, c) __builtin_amdgcn_mfma_f32_32x32x16_bf16((a), (b), (c), 0, 0, 0)
; template <bool SWAP, class Epi>
; DI void gemm_tile(const u16* __restrict__ A, int lda, const u16* __restrict__ Bw, int ldb, int K, char* lds, Epi epi) {
;     ...
;   auto compute = [&](int st) {
;     const char* as = lds + st * GEMM_STAGE;
;     const char* bs = as + 36864;
; #pragma unroll
;     for (int ks = 0; ks < 4; ++ks) {
;       bf16x8 af[2], bfr[2];
; #pragma unroll
;       for (int mi = 0; mi < 2; ++mi) af[mi] = *(const bf16x8*)(as + ((wm * 64 + mi * 32 + r) * 72 + ks * 16 + 8 * h) * 2);
; #pragma unroll
;       for (int ni = 0; ni < 2; ++ni) bfr[ni] = *(const bf16x8*)(bs + ((wn * 64 + ni * 32 + r) * 72 + ks * 16 + 8 * h) * 2);
; #pragma unroll
;       for (int mi = 0; mi < 2; ++mi)
; #pragma unroll
;         for (int ni = 0; ni < 2; ++ni) {
;           if (SWAP) acc[mi][ni] = MFMA32(bfr[ni], af[mi], acc[mi][ni]);
;           else acc[mi][ni] = MFMA32(af[mi], bfr[ni], acc[mi][ni]);
;         }
;     }
;   };
;   gload(0, ra0, rb0);
;   lstore(0, ra0, rb0);
;   gload(1, ra1, rb1);
;   __syncthreads();
;   for (int kt = 0; kt < nk; kt += 2) {
;     if (kt + 2 < nk) gload(kt + 2, ra0, rb0);
;     compute(0);
;     lstore(1, ra1, rb1);
;     __syncthreads();
;     if (kt + 3 < nk) gload(kt + 3, ra1, rb1);
;     compute(1);
;     if (kt + 2 < nk) lstore(0, ra0, rb0);
;     __syncthreads();
	v_mfma_f32_32x32x16_bf16 v[4:19], v[162:165], v[172:175], v[4:19]
	v_mfma_f32_32x32x16_bf16 v[68:83], v[168:171], v[172:175], v[68:83]
	v_mfma_f32_32x32x16_bf16 v[20:35], v[162:165], v[176:179], v[20:35]
	v_mfma_f32_32x32x16_bf16 v[84:99], v[168:171], v[176:179], v[84:99]
	v_mfma_f32_32x32x16_bf16 v[36:51], v[162:165], v[180:183], v[36:51]
	v_mfma_f32_32x32x16_bf16 v[100:115], v[168:171], v[180:183], v[100:115]
	v_mfma_f32_32x32x16_bf16 v[52:67], v[162:165], v[184:187], v[52:67]
	v_mfma_f32_32x32x16_bf16 v[116:131], v[168:171], v[184:187], v[116:131]
	ds_read_b128 v[162:165], v213 offset:0
	ds_read_b128 v[168:171], v213 offset:4096
	ds_read_b128 v[172:175], v217 offset:0
	ds_read_b128 v[176:179], v217 offset:4096
	ds_read_b128 v[180:183], v217 offset:16384
	ds_read_b128 v[184:187], v217 offset:20480
	s_waitcnt lgkmcnt(6)
	v_mfma_f32_32x32x16_bf16 v[4:19], v[132:135], v[140:143], v[4:19]
	v_mfma_f32_32x32x16_bf16 v[68:83], v[136:139], v[140:143], v[68:83]
	v_mfma_f32_32x32x16_bf16 v[20:35], v[132:135], v[144:147], v[20:35]
	v_mfma_f32_32x32x16_bf16 v[84:99], v[136:139], v[144:147], v[84:99]
	v_mfma_f32_32x32x16_bf16 v[36:51], v[132:135], v[148:151], v[36:51]
	v_mfma_f32_32x32x16_bf16 v[100:115], v[136:139], v[148:151], v[100:115]
	v_mfma_f32_32x32x16_bf16 v[52:67], v[132:135], v[158:161], v[52:67]
	v_mfma_f32_32x32x16_bf16 v[116:131], v[136:139], v[158:161], v[116:131]
	s_waitcnt lgkmcnt(0)
	v_mfma_f32_32x32x16_bf16 v[4:19], v[162:165], v[172:175], v[4:19]
	v_mfma_f32_32x32x16_bf16 v[68:83], v[168:171], v[172:175], v[68:83]
	v_mfma_f32_32x32x16_bf16 v[20:35], v[162:165], v[176:179], v[20:35]
	v_mfma_f32_32x32x16_bf16 v[84:99], v[168:171], v[176:179], v[84:99]
	v_mfma_f32_32x32x16_bf16 v[36:51], v[162:165], v[180:183], v[36:51]
	v_mfma_f32_32x32x16_bf16 v[100:115], v[168:171], v[180:183], v[100:115]
	v_mfma_f32_32x32x16_bf16 v[52:67], v[162:165], v[184:187], v[52:67]
	v_mfma_f32_32x32x16_bf16 v[116:131], v[168:171], v[184:187], v[116:131]
	s_waitcnt vmcnt(0) lgkmcnt(0)
	s_barrier
	ds_read_b128 v[132:135], v210 offset:32768
	ds_read_b128 v[136:139], v210 offset:36864
	ds_read_b128 v[140:143], v214 offset:32768
	ds_read_b128 v[144:147], v214 offset:36864
	ds_read_b128 v[148:151], v214 offset:49152
	ds_read_b128 v[158:161], v214 offset:53248
	s_mov_b32 m0, s44
	s_nop 0
	global_load_lds_dwordx4 v208, s[68:69]
	global_load_lds_dwordx4 v209, s[70:71] offset:1024
	global_load_lds_dwordx4 v208, s[72:73] offset:2048
	global_load_lds_dwordx4 v209, s[74:75] offset:3072
	ds_read_b128 v[162:165], v211 offset:32768
	ds_read_b128 v[168:171], v211 offset:36864
	ds_read_b128 v[172:175], v215 offset:32768
	ds_read_b128 v[176:179], v215 offset:36864
	ds_read_b128 v[180:183], v215 offset:49152
	ds_read_b128 v[184:187], v215 offset:53248
	s_waitcnt lgkmcnt(6)
	v_mfma_f32_32x32x16_bf16 v[4:19], v[132:135], v[140:143], v[4:19]
	v_mfma_f32_32x32x16_bf16 v[68:83], v[136:139], v[140:143], v[68:83]
	v_mfma_f32_32x32x16_bf16 v[20:35], v[132:135], v[144:147], v[20:35]
	v_mfma_f32_32x32x16_bf16 v[84:99], v[136:139], v[144:147], v[84:99]
	v_mfma_f32_32x32x16_bf16 v[36:51], v[132:135], v[148:151], v[36:51]
	v_mfma_f32_32x32x16_bf16 v[100:115], v[136:139], v[148:151], v[100:115]
	v_mfma_f32_32x32x16_bf16 v[52:67], v[132:135], v[158:161], v[52:67]
	v_mfma_f32_32x32x16_bf16 v[116:131], v[136:139], v[158:161], v[116:131]
	s_mov_b32 m0, s46
	s_nop 0
	global_load_lds_dwordx4 v208, s[76:77]
	global_load_lds_dwordx4 v209, s[78:79] offset:1024
	global_load_lds_dwordx4 v208, s[80:81] offset:2048
	global_load_lds_dwordx4 v209, s[82:83] offset:3072
	v_add_u32_e32 v208, 0x80, v208
	v_add_u32_e32 v209, 0x80, v209
	ds_read_b128 v[132:135], v212 offset:32768
	ds_read_b128 v[136:139], v212 offset:36864
	ds_read_b128 v[140:143], v216 offset:32768
	ds_read_b128 v[144:147], v216 offset:36864
	ds_read_b128 v[148:151], v216 offset:49152
	ds_read_b128 v[158:161], v216 offset:53248
	s_waitcnt lgkmcnt(6)
	v_mfma_f32_32x32x16_bf16 v[4:19], v[162:165], v[172:175], v[4:19]
	v_mfma_f32_32x32x16_bf16 v[68:83], v[168:171], v[172:175], v[68:83]
	v_mfma_f32_32x32x16_bf16 v[20:35], v[162:165], v[176:179], v[20:35]
	v_mfma_f32_32x32x16_bf16 v[84:99], v[168:171], v[176:179], v[84:99]
	v_mfma_f32_32x32x16_bf16 v[36:51], v[162:165], v[180:183], v[36:51]
	v_mfma_f32_32x32x16_bf16 v[100:115], v[168:171], v[180:183], v[100:115]
	v_mfma_f32_32x32x16_bf16 v[52:67], v[162:165], v[184:187], v[52:67]
	v_mfma_f32_32x32x16_bf16 v[116:131], v[168:171], v[184:187], v[116:131]
	ds_read_b128 v[162:165], v213 offset:32768
	ds_read_b128 v[168:171], v213 offset:36864
	ds_read_b128 v[172:175], v217 offset:32768
	ds_read_b128 v[176:179], v217 offset:36864
	ds_read_b128 v[180:183], v217 offset:49152
	ds_read_b128 v[184:187], v217 offset:53248
	s_waitcnt lgkmcnt(6)
	v_mfma_f32_32x32x16_bf16 v[4:19], v[132:135], v[140:143], v[4:19]
	v_mfma_f32_32x32x16_bf16 v[68:83], v[136:139], v[140:143], v[68:83]
	v_mfma_f32_32x32x16_bf16 v[20:35], v[132:135], v[144:147], v[20:35]
	v_mfma_f32_32x32x16_bf16 v[84:99], v[136:139], v[144:147], v[84:99]
	v_mfma_f32_32x32x16_bf16 v[36:51], v[132:135], v[148:151], v[36:51]
	v_mfma_f32_32x32x16_bf16 v[100:115], v[136:139], v[148:151], v[100:115]
	v_mfma_f32_32x32x16_bf16 v[52:67], v[132:135], v[158:161], v[52:67]
	v_mfma_f32_32x32x16_bf16 v[116:131], v[136:139], v[158:161], v[116:131]
	s_waitcnt lgkmcnt(0)
	v_mfma_f32_32x32x16_bf16 v[4:19], v[162:165], v[172:175], v[4:19]
	v_mfma_f32_32x32x16_bf16 v[68:83], v[168:171], v[172:175], v[68:83]
	v_mfma_f32_32x32x16_bf16 v[20:35], v[162:165], v[176:179], v[20:35]
	v_mfma_f32_32x32x16_bf16 v[84:99], v[168:171], v[176:179], v[84:99]
	v_mfma_f32_32x32x16_bf16 v[36:51], v[162:165], v[180:183], v[36:51]
	v_mfma_f32_32x32x16_bf16 v[100:115], v[168:171], v[180:183], v[100:115]
	v_mfma_f32_32x32x16_bf16 v[52:67], v[162:165], v[184:187], v[52:67]
	v_mfma_f32_32x32x16_bf16 v[116:131], v[168:171], v[184:187], v[116:131]
	s_waitcnt vmcnt(0) lgkmcnt(0)
	s_barrier
; #define MFMA32(a, b, c) __builtin_amdgcn_mfma_f32_32x32x16_bf16((a), (b), (c), 0, 0, 0)
; template <bool SWAP, class Epi>
; DI void gemm_tile(const u16* __restrict__ A, int lda, const u16* __restrict__ Bw, int ldb, int K, char* lds, Epi epi) {
;     ...
;   auto compute = [&](int st) {
;     const char* as = lds + st * GEMM_STAGE;
;     const char* bs = as + 36864;
; #pragma unroll
;     for (int ks = 0; ks < 4; ++ks) {
;       bf16x8 af[2], bfr[2];
; #pragma unroll
;       for (int mi = 0; mi < 2; ++mi) af[mi] = *(const bf16x8*)(as + ((wm * 64 + mi * 32 + r) * 72 + ks * 16 + 8 * h) * 2);
; #pragma unroll
;       for (int ni = 0; ni < 2; ++ni) bfr[ni] = *(const bf16x8*)(bs + ((wn * 64 + ni * 32 + r) * 72 + ks * 16 + 8 * h) * 2);
; #pragma unroll
;       for (int mi = 0; mi < 2; ++mi)
; #pragma unroll
;         for (int ni = 0; ni < 2; ++ni) {
;           if (SWAP) acc[mi][ni] = MFMA32(bfr[ni], af[mi], acc[mi][ni]);
;           else acc[mi][ni] = MFMA32(af[mi], bfr[ni], acc[mi][ni]);
;         }
;     }
;   };
;   gload(0, ra0, rb0);
;   lstore(0, ra0, rb0);
;   gload(1, ra1, rb1);
;   __syncthreads();
;   for (int kt = 0; kt < nk; kt += 2) {
;     if (kt + 2 < nk) gload(kt + 2, ra0, rb0);
;     compute(0);
;     lstore(1, ra1, rb1);
;     __syncthreads();
;     if (kt + 3 < nk) gload(kt + 3, ra1, rb1);
;     compute(1);
;     if (kt + 2 < nk) lstore(0, ra0, rb0);
;     __syncthreads();
	ds_read_b128 v[132:135], v210 offset:0
	ds_read_b128 v[136:139], v210 offset:4096
	ds_read_b128 v[140:143], v214 offset:0
	ds_read_b128 v[144:147], v214 offset:4096
	ds_read_b128 v[148:151], v214 offset:16384
	ds_read_b128 v[158:161], v214 offset:20480
	s_mov_b32 m0, s45
	s_nop 0
	global_load_lds_dwordx4 v208, s[68:69]
	global_load_lds_dwordx4 v209, s[70:71] offset:1024
	global_load_lds_dwordx4 v208, s[72:73] offset:2048
	global_load_lds_dwordx4 v209, s[74:75] offset:3072
	ds_read_b128 v[162:165], v211 offset:0
	ds_read_b128 v[168:171], v211 offset:4096
	ds_read_b128 v[172:175], v215 offset:0
	ds_read_b128 v[176:179], v215 offset:4096
	ds_read_b128 v[180:183], v215 offset:16384
	ds_read_b128 v[184:187], v215 offset:20480
	s_waitcnt lgkmcnt(6)
	v_mfma_f32_32x32x16_bf16 v[4:19], v[132:135], v[140:143], v[4:19]
	v_mfma_f32_32x32x16_bf16 v[68:83], v[136:139], v[140:143], v[68:83]
	v_mfma_f32_32x32x16_bf16 v[20:35], v[132:135], v[144:147], v[20:35]
	v_mfma_f32_32x32x16_bf16 v[84:99], v[136:139], v[144:147], v[84:99]
	v_mfma_f32_32x32x16_bf16 v[36:51], v[132:135], v[148:151], v[36:51]
	v_mfma_f32_32x32x16_bf16 v[100:115], v[136:139], v[148:151], v[100:115]
	v_mfma_f32_32x32x16_bf16 v[52:67], v[132:135], v[158:161], v[52:67]
	v_mfma_f32_32x32x16_bf16 v[116:131], v[136:139], v[158:161], v[116:131]
	s_mov_b32 m0, s47
	s_nop 0
	global_load_lds_dwordx4 v208, s[76:77]
	global_load_lds_dwordx4 v209, s[78:79] offset:1024
	global_load_lds_dwordx4 v208, s[80:81] offset:2048
	global_load_lds_dwordx4 v209, s[82:83] offset:3072
	v_add_u32_e32 v208, 0x80, v208
	v_add_u32_e32 v209, 0x80, v209
	ds_read_b128 v[132:135], v212 offset:0
	ds_read_b128 v[136:139], v212 offset:4096
	ds_read_b128 v[140:143], v216 offset:0
	ds_read_b128 v[144:147], v216 offset:4096
	ds_read_b128 v[148:151], v216 offset:16384
	ds_read_b128 v[158:161], v216 offset:20480
	s_waitcnt lgkmcnt(6)
	v_mfma_f32_32x32x16_bf16 v[4:19], v[162:165], v[172:175], v[4:19]
	v_mfma_f32_32x32x16_bf16 v[68:83], v[168:171], v[172:175], v[68:83]
	v_mfma_f32_32x32x16_bf16 v[20:35], v[162:165], v[176:179], v[20:35]
	v_mfma_f32_32x32x16_bf16 v[84:99], v[168:171], v[176:179], v[84:99]
	v_mfma_f32_32x32x16_bf16 v[36:51], v[162:165], v[180:183], v[36:51]
	v_mfma_f32_32x32x16_bf16 v[100:115], v[168:171], v[180:183], v[100:115]
	v_mfma_f32_32x32x16_bf16 v[52:67], v[162:165], v[184:187], v[52:67]
	v_mfma_f32_32x32x16_bf16 v[116:131], v[168:171], v[184:187], v[116:131]
	ds_read_b128 v[162:165], v213 offset:0
	ds_read_b128 v[168:171], v213 offset:4096
	ds_read_b128 v[172:175], v217 offset:0
	ds_read_b128 v[176:179], v217 offset:4096
	ds_read_b128 v[180:183], v217 offset:16384
	ds_read_b128 v[184:187], v217 offset:20480
	s_waitcnt lgkmcnt(6)
	v_mfma_f32_32x32x16_bf16 v[4:19], v[132:135], v[140:143], v[4:19]
	v_mfma_f32_32x32x16_bf16 v[68:83], v[136:139], v[140:143], v[68:83]
	v_mfma_f32_32x32x16_bf16 v[20:35], v[132:135], v[144:147], v[20:35]
	v_mfma_f32_32x32x16_bf16 v[84:99], v[136:139], v[144:147], v[84:99]
	v_mfma_f32_32x32x16_bf16 v[36:51], v[132:135], v[148:151], v[36:51]
	v_mfma_f32_32x32x16_bf16 v[100:115], v[136:139], v[148:151], v[100:115]
	v_mfma_f32_32x32x16_bf16 v[52:67], v[132:135], v[158:161], v[52:67]
	v_mfma_f32_32x32x16_bf16 v[116:131], v[136:139], v[158:161], v[116:131]
	s_waitcnt lgkmcnt(0)
	v_mfma_f32_32x32x16_bf16 v[4:19], v[162:165], v[172:175], v[4:19]
	v_mfma_f32_32x32x16_bf16 v[68:83], v[168:171], v[172:175], v[68:83]
	v_mfma_f32_32x32x16_bf16 v[20:35], v[162:165], v[176:179], v[20:35]
	v_mfma_f32_32x32x16_bf16 v[84:99], v[168:171], v[176:179], v[84:99]
	v_mfma_f32_32x32x16_bf16 v[36:51], v[162:165], v[180:183], v[36:51]
	v_mfma_f32_32x32x16_bf16 v[100:115], v[168:171], v[180:183], v[100:115]
	v_mfma_f32_32x32x16_bf16 v[52:67], v[162:165], v[184:187], v[52:67]
	v_mfma_f32_32x32x16_bf16 v[116:131], v[168:171], v[184:187], v[116:131]
	s_waitcnt vmcnt(0) lgkmcnt(0)
	s_barrier
	ds_read_b128 v[132:135], v210 offset:32768
	ds_read_b128 v[136:139], v210 offset:36864
	ds_read_b128 v[140:143], v214 offset:32768
	ds_read_b128 v[144:147], v214 offset:36864
	ds_read_b128 v[148:151], v214 offset:49152
	ds_read_b128 v[158:161], v214 offset:53248
	s_mov_b32 m0, s44
	s_nop 0
	global_load_lds_dwordx4 v208, s[68:69]
	global_load_lds_dwordx4 v209, s[70:71] offset:1024
	global_load_lds_dwordx4 v208, s[72:73] offset:2048
	global_load_lds_dwordx4 v209, s[74:75] offset:3072
	ds_read_b128 v[162:165], v211 offset:32768
	ds_read_b128 v[168:171], v211 offset:36864
	ds_read_b128 v[172:175], v215 offset:32768
	ds_read_b128 v[176:179], v215 offset:36864
	ds_read_b128 v[180:183], v215 offset:49152
	ds_read_b128 v[184:187], v215 offset:53248
	s_waitcnt lgkmcnt(6)
	v_mfma_f32_32x32x16_bf16 v[4:19], v[132:135], v[140:143], v[4:19]
	v_mfma_f32_32x32x16_bf16 v[68:83], v[136:139], v[140:143], v[68:83]
	v_mfma_f32_32x32x16_bf16 v[20:35], v[132:135], v[144:147], v[20:35]
	v_mfma_f32_32x32x16_bf16 v[84:99], v[136:139], v[144:147], v[84:99]
	v_mfma_f32_32x32x16_bf16 v[36:51], v[132:135], v[148:151], v[36:51]
	v_mfma_f32_32x32x16_bf16 v[100:115], v[136:139], v[148:151], v[100:115]
	v_mfma_f32_32x32x16_bf16 v[52:67], v[132:135], v[158:161], v[52:67]
	v_mfma_f32_32x32x16_bf16 v[116:131], v[136:139], v[158:161], v[116:131]
	s_mov_b32 m0, s46
	s_nop 0
	global_load_lds_dwordx4 v208, s[76:77]
	global_load_lds_dwordx4 v209, s[78:79] offset:1024
	global_load_lds_dwordx4 v208, s[80:81] offset:2048
	global_load_lds_dwordx4 v209, s[82:83] offset:3072
	v_add_u32_e32 v208, 0x80, v208
	v_add_u32_e32 v209, 0x80, v209
	ds_read_b128 v[132:135], v212 offset:32768
	ds_read_b128 v[136:139], v212 offset:36864
	ds_read_b128 v[140:143], v216 offset:32768
	ds_read_b128 v[144:147], v216 offset:36864
	ds_read_b128 v[148:151], v216 offset:49152
	ds_read_b128 v[158:161], v216 offset:53248
	s_waitcnt lgkmcnt(6)
; #define MFMA32(a, b, c) __builtin_amdgcn_mfma_f32_32x32x16_bf16((a), (b), (c), 0, 0, 0)
; template <bool SWAP, class Epi>
; DI void gemm_tile(const u16* __restrict__ A, int lda, const u16* __restrict__ Bw, int ldb, int K, char* lds, Epi epi) {
;     ...
;   auto compute = [&](int st) {
;     const char* as = lds + st * GEMM_STAGE;
;     const char* bs = as + 36864;
; #pragma unroll
;     for (int ks = 0; ks < 4; ++ks) {
;       bf16x8 af[2], bfr[2];
; #pragma unroll
;       for (int mi = 0; mi < 2; ++mi) af[mi] = *(const bf16x8*)(as + ((wm * 64 + mi * 32 + r) * 72 + ks * 16 + 8 * h) * 2);
; #pragma unroll
;       for (int ni = 0; ni < 2; ++ni) bfr[ni] = *(const bf16x8*)(bs + ((wn * 64 + ni * 32 + r) * 72 + ks * 16 + 8 * h) * 2);
; #pragma unroll
;       for (int mi = 0; mi < 2; ++mi)
; #pragma unroll
;         for (int ni = 0; ni < 2; ++ni) {
;           if (SWAP) acc[mi][ni] = MFMA32(bfr[ni], af[mi], acc[mi][ni]);
;           else acc[mi][ni] = MFMA32(af[mi], bfr[ni], acc[mi][ni]);
;         }
;     }
;   };
;   gload(0, ra0, rb0);
;   lstore(0, ra0, rb0);
;   gload(1, ra1, rb1);
;   __syncthreads();
;   for (int kt = 0; kt < nk; kt += 2) {
;     if (kt + 2 < nk) gload(kt + 2, ra0, rb0);
;     compute(0);
;     lstore(1, ra1, rb1);
;     __syncthreads();
;     if (kt + 3 < nk) gload(kt + 3, ra1, rb1);
;     compute(1);
;     if (kt + 2 < nk) lstore(0, ra0, rb0);
;     __syncthreads();
	v_mfma_f32_32x32x16_bf16 v[4:19], v[162:165], v[172:175], v[4:19]
	v_mfma_f32_32x32x16_bf16 v[68:83], v[168:171], v[172:175], v[68:83]
	v_mfma_f32_32x32x16_bf16 v[20:35], v[162:165], v[176:179], v[20:35]
	v_mfma_f32_32x32x16_bf16 v[84:99], v[168:171], v[176:179], v[84:99]
	v_mfma_f32_32x32x16_bf16 v[36:51], v[162:165], v[180:183], v[36:51]
	v_mfma_f32_32x32x16_bf16 v[100:115], v[168:171], v[180:183], v[100:115]
	v_mfma_f32_32x32x16_bf16 v[52:67], v[162:165], v[184:187], v[52:67]
	v_mfma_f32_32x32x16_bf16 v[116:131], v[168:171], v[184:187], v[116:131]
	ds_read_b128 v[162:165], v213 offset:32768
	ds_read_b128 v[168:171], v213 offset:36864
	ds_read_b128 v[172:175], v217 offset:32768
	ds_read_b128 v[176:179], v217 offset:36864
	ds_read_b128 v[180:183], v217 offset:49152
	ds_read_b128 v[184:187], v217 offset:53248
	s_waitcnt lgkmcnt(6)
	v_mfma_f32_32x32x16_bf16 v[4:19], v[132:135], v[140:143], v[4:19]
	v_mfma_f32_32x32x16_bf16 v[68:83], v[136:139], v[140:143], v[68:83]
	v_mfma_f32_32x32x16_bf16 v[20:35], v[132:135], v[144:147], v[20:35]
	v_mfma_f32_32x32x16_bf16 v[84:99], v[136:139], v[144:147], v[84:99]
	v_mfma_f32_32x32x16_bf16 v[36:51], v[132:135], v[148:151], v[36:51]
	v_mfma_f32_32x32x16_bf16 v[100:115], v[136:139], v[148:151], v[100:115]
	v_mfma_f32_32x32x16_bf16 v[52:67], v[132:135], v[158:161], v[52:67]
	v_mfma_f32_32x32x16_bf16 v[116:131], v[136:139], v[158:161], v[116:131]
	s_waitcnt lgkmcnt(0)
	v_mfma_f32_32x32x16_bf16 v[4:19], v[162:165], v[172:175], v[4:19]
	v_mfma_f32_32x32x16_bf16 v[68:83], v[168:171], v[172:175], v[68:83]
	v_mfma_f32_32x32x16_bf16 v[20:35], v[162:165], v[176:179], v[20:35]
	v_mfma_f32_32x32x16_bf16 v[84:99], v[168:171], v[176:179], v[84:99]
	v_mfma_f32_32x32x16_bf16 v[36:51], v[162:165], v[180:183], v[36:51]
	v_mfma_f32_32x32x16_bf16 v[100:115], v[168:171], v[180:183], v[100:115]
	v_mfma_f32_32x32x16_bf16 v[52:67], v[162:165], v[184:187], v[52:67]
	v_mfma_f32_32x32x16_bf16 v[116:131], v[168:171], v[184:187], v[116:131]
	s_waitcnt vmcnt(0) lgkmcnt(0)
	s_barrier
	ds_read_b128 v[132:135], v210 offset:0
	ds_read_b128 v[136:139], v210 offset:4096
	ds_read_b128 v[140:143], v214 offset:0
	ds_read_b128 v[144:147], v214 offset:4096
	ds_read_b128 v[148:151], v214 offset:16384
	ds_read_b128 v[158:161], v214 offset:20480
	s_mov_b32 m0, s45
	s_nop 0
	global_load_lds_dwordx4 v208, s[68:69]
	global_load_lds_dwordx4 v209, s[70:71] offset:1024
	global_load_lds_dwordx4 v208, s[72:73] offset:2048
	global_load_lds_dwordx4 v209, s[74:75] offset:3072
	ds_read_b128 v[162:165], v211 offset:0
	ds_read_b128 v[168:171], v211 offset:4096
	ds_read_b128 v[172:175], v215 offset:0
	ds_read_b128 v[176:179], v215 offset:4096
	ds_read_b128 v[180:183], v215 offset:16384
	ds_read_b128 v[184:187], v215 offset:20480
	s_waitcnt lgkmcnt(6)
	v_mfma_f32_32x32x16_bf16 v[4:19], v[132:135], v[140:143], v[4:19]
	v_mfma_f32_32x32x16_bf16 v[68:83], v[136:139], v[140:143], v[68:83]
	v_mfma_f32_32x32x16_bf16 v[20:35], v[132:135], v[144:147], v[20:35]
	v_mfma_f32_32x32x16_bf16 v[84:99], v[136:139], v[144:147], v[84:99]
	v_mfma_f32_32x32x16_bf16 v[36:51], v[132:135], v[148:151], v[36:51]
	v_mfma_f32_32x32x16_bf16 v[100:115], v[136:139], v[148:151], v[100:115]
	v_mfma_f32_32x32x16_bf16 v[52:67], v[132:135], v[158:161], v[52:67]
	v_mfma_f32_32x32x16_bf16 v[116:131], v[136:139], v[158:161], v[116:131]
	s_mov_b32 m0, s47
	s_nop 0
	global_load_lds_dwordx4 v208, s[76:77]
	global_load_lds_dwordx4 v209, s[78:79] offset:1024
	global_load_lds_dwordx4 v208, s[80:81] offset:2048
	global_load_lds_dwordx4 v209, s[82:83] offset:3072
	v_add_u32_e32 v208, 0x80, v208
	v_add_u32_e32 v209, 0x80, v209
	ds_read_b128 v[132:135], v212 offset:0
	ds_read_b128 v[136:139], v212 offset:4096
	ds_read_b128 v[140:143], v216 offset:0
	ds_read_b128 v[144:147], v216 offset:4096
	ds_read_b128 v[148:151], v216 offset:16384
	ds_read_b128 v[158:161], v216 offset:20480
	s_waitcnt lgkmcnt(6)
	v_mfma_f32_32x32x16_bf16 v[4:19], v[162:165], v[172:175], v[4:19]
	v_mfma_f32_32x32x16_bf16 v[68:83], v[168:171], v[172:175], v[68:83]
	v_mfma_f32_32x32x16_bf16 v[20:35], v[162:165], v[176:179], v[20:35]
	v_mfma_f32_32x32x16_bf16 v[84:99], v[168:171], v[176:179], v[84:99]
	v_mfma_f32_32x32x16_bf16 v[36:51], v[162:165], v[180:183], v[36:51]
	v_mfma_f32_32x32x16_bf16 v[100:115], v[168:171], v[180:183], v[100:115]
	v_mfma_f32_32x32x16_bf16 v[52:67], v[162:165], v[184:187], v[52:67]
	v_mfma_f32_32x32x16_bf16 v[116:131], v[168:171], v[184:187], v[116:131]
	ds_read_b128 v[162:165], v213 offset:0
	ds_read_b128 v[168:171], v213 offset:4096
	ds_read_b128 v[172:175], v217 offset:0
	ds_read_b128 v[176:179], v217 offset:4096
	ds_read_b128 v[180:183], v217 offset:16384
	ds_read_b128 v[184:187], v217 offset:20480
	s_waitcnt lgkmcnt(6)
	v_mfma_f32_32x32x16_bf16 v[4:19], v[132:135], v[140:143], v[4:19]
	v_mfma_f32_32x32x16_bf16 v[68:83], v[136:139], v[140:143], v[68:83]
	v_mfma_f32_32x32x16_bf16 v[20:35], v[132:135], v[144:147], v[20:35]
	v_mfma_f32_32x32x16_bf16 v[84:99], v[136:139], v[144:147], v[84:99]
	v_mfma_f32_32x32x16_bf16 v[36:51], v[132:135], v[148:151], v[36:51]
	v_mfma_f32_32x32x16_bf16 v[100:115], v[136:139], v[148:151], v[100:115]
	v_mfma_f32_32x32x16_bf16 v[52:67], v[132:135], v[158:161], v[52:67]
	v_mfma_f32_32x32x16_bf16 v[116:131], v[136:139], v[158:161], v[116:131]
	s_waitcnt lgkmcnt(0)
	v_mfma_f32_32x32x16_bf16 v[4:19], v[162:165], v[172:175], v[4:19]
	v_mfma_f32_32x32x16_bf16 v[68:83], v[168:171], v[172:175], v[68:83]
	v_mfma_f32_32x32x16_bf16 v[20:35], v[162:165], v[176:179], v[20:35]
	v_mfma_f32_32x32x16_bf16 v[84:99], v[168:171], v[176:179], v[84:99]
	v_mfma_f32_32x32x16_bf16 v[36:51], v[162:165], v[180:183], v[36:51]
	v_mfma_f32_32x32x16_bf16 v[100:115], v[168:171], v[180:183], v[100:115]
	v_mfma_f32_32x32x16_bf16 v[52:67], v[162:165], v[184:187], v[52:67]
	v_mfma_f32_32x32x16_bf16 v[116:131], v[168:171], v[184:187], v[116:131]
	s_waitcnt vmcnt(0) lgkmcnt(0)
	s_barrier
; #define MFMA32(a, b, c) __builtin_amdgcn_mfma_f32_32x32x16_bf16((a), (b), (c), 0, 0, 0)
; template <bool SWAP, class Epi>
; DI void gemm_tile(const u16* __restrict__ A, int lda, const u16* __restrict__ Bw, int ldb, int K, char* lds, Epi epi) {
;     ...
;   auto compute = [&](int st) {
;     const char* as = lds + st * GEMM_STAGE;
;     const char* bs = as + 36864;
; #pragma unroll
;     for (int ks = 0; ks < 4; ++ks) {
;       bf16x8 af[2], bfr[2];
; #pragma unroll
;       for (int mi = 0; mi < 2; ++mi) af[mi] = *(const bf16x8*)(as + ((wm * 64 + mi * 32 + r) * 72 + ks * 16 + 8 * h) * 2);
; #pragma unroll
;       for (int ni = 0; ni < 2; ++ni) bfr[ni] = *(const bf16x8*)(bs + ((wn * 64 + ni * 32 + r) * 72 + ks * 16 + 8 * h) * 2);
; #pragma unroll
;       for (int mi = 0; mi < 2; ++mi)
; #pragma unroll
;         for (int ni = 0; ni < 2; ++ni) {
;           if (SWAP) acc[mi][ni] = MFMA32(bfr[ni], af[mi], acc[mi][ni]);
;           else acc[mi][ni] = MFMA32(af[mi], bfr[ni], acc[mi][ni]);
;         }
;     }
;   };
;   gload(0, ra0, rb0);
;   lstore(0, ra0, rb0);
;   gload(1, ra1, rb1);
;   __syncthreads();
;   for (int kt = 0; kt < nk; kt += 2) {
;     if (kt + 2 < nk) gload(kt + 2, ra0, rb0);
;     compute(0);
;     lstore(1, ra1, rb1);
;     __syncthreads();
;     if (kt + 3 < nk) gload(kt + 3, ra1, rb1);
;     compute(1);
;     if (kt + 2 < nk) lstore(0, ra0, rb0);
;     __syncthreads();
	ds_read_b128 v[132:135], v210 offset:32768
	ds_read_b128 v[136:139], v210 offset:36864
	ds_read_b128 v[140:143], v214 offset:32768
	ds_read_b128 v[144:147], v214 offset:36864
	ds_read_b128 v[148:151], v214 offset:49152
	ds_read_b128 v[158:161], v214 offset:53248
	s_mov_b32 m0, s44
	s_nop 0
	global_load_lds_dwordx4 v208, s[68:69]
	global_load_lds_dwordx4 v209, s[70:71] offset:1024
	global_load_lds_dwordx4 v208, s[72:73] offset:2048
	global_load_lds_dwordx4 v209, s[74:75] offset:3072
	ds_read_b128 v[162:165], v211 offset:32768
	ds_read_b128 v[168:171], v211 offset:36864
	ds_read_b128 v[172:175], v215 offset:32768
	ds_read_b128 v[176:179], v215 offset:36864
	ds_read_b128 v[180:183], v215 offset:49152
	ds_read_b128 v[184:187], v215 offset:53248
	s_waitcnt lgkmcnt(6)
	v_mfma_f32_32x32x16_bf16 v[4:19], v[132:135], v[140:143], v[4:19]
	v_mfma_f32_32x32x16_bf16 v[68:83], v[136:139], v[140:143], v[68:83]
	v_mfma_f32_32x32x16_bf16 v[20:35], v[132:135], v[144:147], v[20:35]
	v_mfma_f32_32x32x16_bf16 v[84:99], v[136:139], v[144:147], v[84:99]
	v_mfma_f32_32x32x16_bf16 v[36:51], v[132:135], v[148:151], v[36:51]
	v_mfma_f32_32x32x16_bf16 v[100:115], v[136:139], v[148:151], v[100:115]
	v_mfma_f32_32x32x16_bf16 v[52:67], v[132:135], v[158:161], v[52:67]
	v_mfma_f32_32x32x16_bf16 v[116:131], v[136:139], v[158:161], v[116:131]
	s_mov_b32 m0, s46
	s_nop 0
	global_load_lds_dwordx4 v208, s[76:77]
	global_load_lds_dwordx4 v209, s[78:79] offset:1024
	global_load_lds_dwordx4 v208, s[80:81] offset:2048
	global_load_lds_dwordx4 v209, s[82:83] offset:3072
	v_add_u32_e32 v208, 0x80, v208
	v_add_u32_e32 v209, 0x80, v209
	ds_read_b128 v[132:135], v212 offset:32768
	ds_read_b128 v[136:139], v212 offset:36864
	ds_read_b128 v[140:143], v216 offset:32768
	ds_read_b128 v[144:147], v216 offset:36864
	ds_read_b128 v[148:151], v216 offset:49152
	ds_read_b128 v[158:161], v216 offset:53248
	s_waitcnt lgkmcnt(6)
	v_mfma_f32_32x32x16_bf16 v[4:19], v[162:165], v[172:175], v[4:19]
	v_mfma_f32_32x32x16_bf16 v[68:83], v[168:171], v[172:175], v[68:83]
	v_mfma_f32_32x32x16_bf16 v[20:35], v[162:165], v[176:179], v[20:35]
	v_mfma_f32_32x32x16_bf16 v[84:99], v[168:171], v[176:179], v[84:99]
	v_mfma_f32_32x32x16_bf16 v[36:51], v[162:165], v[180:183], v[36:51]
	v_mfma_f32_32x32x16_bf16 v[100:115], v[168:171], v[180:183], v[100:115]
	v_mfma_f32_32x32x16_bf16 v[52:67], v[162:165], v[184:187], v[52:67]
	v_mfma_f32_32x32x16_bf16 v[116:131], v[168:171], v[184:187], v[116:131]
	ds_read_b128 v[162:165], v213 offset:32768
	ds_read_b128 v[168:171], v213 offset:36864
	ds_read_b128 v[172:175], v217 offset:32768
	ds_read_b128 v[176:179], v217 offset:36864
	ds_read_b128 v[180:183], v217 offset:49152
	ds_read_b128 v[184:187], v217 offset:53248
	s_waitcnt lgkmcnt(6)
	v_mfma_f32_32x32x16_bf16 v[4:19], v[132:135], v[140:143], v[4:19]
	v_mfma_f32_32x32x16_bf16 v[68:83], v[136:139], v[140:143], v[68:83]
	v_mfma_f32_32x32x16_bf16 v[20:35], v[132:135], v[144:147], v[20:35]
	v_mfma_f32_32x32x16_bf16 v[84:99], v[136:139], v[144:147], v[84:99]
	v_mfma_f32_32x32x16_bf16 v[36:51], v[132:135], v[148:151], v[36:51]
	v_mfma_f32_32x32x16_bf16 v[100:115], v[136:139], v[148:151], v[100:115]
	v_mfma_f32_32x32x16_bf16 v[52:67], v[132:135], v[158:161], v[52:67]
	v_mfma_f32_32x32x16_bf16 v[116:131], v[136:139], v[158:161], v[116:131]
	s_waitcnt lgkmcnt(0)
	v_mfma_f32_32x32x16_bf16 v[4:19], v[162:165], v[172:175], v[4:19]
	v_mfma_f32_32x32x16_bf16 v[68:83], v[168:171], v[172:175], v[68:83]
	v_mfma_f32_32x32x16_bf16 v[20:35], v[162:165], v[176:179], v[20:35]
	v_mfma_f32_32x32x16_bf16 v[84:99], v[168:171], v[176:179], v[84:99]
	v_mfma_f32_32x32x16_bf16 v[36:51], v[162:165], v[180:183], v[36:51]
	v_mfma_f32_32x32x16_bf16 v[100:115], v[168:171], v[180:183], v[100:115]
	v_mfma_f32_32x32x16_bf16 v[52:67], v[162:165], v[184:187], v[52:67]
	v_mfma_f32_32x32x16_bf16 v[116:131], v[168:171], v[184:187], v[116:131]
	s_waitcnt vmcnt(0) lgkmcnt(0)
	s_barrier
	ds_read_b128 v[132:135], v210 offset:0
	ds_read_b128 v[136:139], v210 offset:4096
	ds_read_b128 v[140:143], v214 offset:0
	ds_read_b128 v[144:147], v214 offset:4096
	ds_read_b128 v[148:151], v214 offset:16384
	ds_read_b128 v[158:161], v214 offset:20480
	s_mov_b32 m0, s45
	s_nop 0
	global_load_lds_dwordx4 v208, s[68:69]
	global_load_lds_dwordx4 v209, s[70:71] offset:1024
	global_load_lds_dwordx4 v208, s[72:73] offset:2048
	global_load_lds_dwordx4 v209, s[74:75] offset:3072
	ds_read_b128 v[162:165], v211 offset:0
	ds_read_b128 v[168:171], v211 offset:4096
	ds_read_b128 v[172:175], v215 offset:0
	ds_read_b128 v[176:179], v215 offset:4096
	ds_read_b128 v[180:183], v215 offset:16384
	ds_read_b128 v[184:187], v215 offset:20480
	s_waitcnt lgkmcnt(6)
	v_mfma_f32_32x32x16_bf16 v[4:19], v[132:135], v[140:143], v[4:19]
	v_mfma_f32_32x32x16_bf16 v[68:83], v[136:139], v[140:143], v[68:83]
	v_mfma_f32_32x32x16_bf16 v[20:35], v[132:135], v[144:147], v[20:35]
	v_mfma_f32_32x32x16_bf16 v[84:99], v[136:139], v[144:147], v[84:99]
	v_mfma_f32_32x32x16_bf16 v[36:51], v[132:135], v[148:151], v[36:51]
	v_mfma_f32_32x32x16_bf16 v[100:115], v[136:139], v[148:151], v[100:115]
	v_mfma_f32_32x32x16_bf16 v[52:67], v[132:135], v[158:161], v[52:67]
	v_mfma_f32_32x32x16_bf16 v[116:131], v[136:139], v[158:161], v[116:131]
	s_mov_b32 m0, s47
	s_nop 0
	global_load_lds_dwordx4 v208, s[76:77]
	global_load_lds_dwordx4 v209, s[78:79] offset:1024
	global_load_lds_dwordx4 v208, s[80:81] offset:2048
	global_load_lds_dwordx4 v209, s[82:83] offset:3072
	v_add_u32_e32 v208, 0x80, v208
	v_add_u32_e32 v209, 0x80, v209
	ds_read_b128 v[132:135], v212 offset:0
	ds_read_b128 v[136:139], v212 offset:4096
	ds_read_b128 v[140:143], v216 offset:0
	ds_read_b128 v[144:147], v216 offset:4096
	ds_read_b128 v[148:151], v216 offset:16384
	ds_read_b128 v[158:161], v216 offset:20480
	s_waitcnt lgkmcnt(6)
; template <bool SWAP, class Epi>
; DI void gemm_tile(const u16* __restrict__ A, int lda, const u16* __restrict__ Bw, int ldb, int K, char* lds, Epi epi) {
;     ...
;   for (int kt = 0; kt < nk; kt += 2) {
;     if (kt + 2 < nk) gload(kt + 2, ra0, rb0);
;     compute(0);
;     lstore(1, ra1, rb1);
;     __syncthreads();
;     if (kt + 3 < nk) gload(kt + 3, ra1, rb1);
;     compute(1);
;     if (kt + 2 < nk) lstore(0, ra0, rb0);
;     __syncthreads();
	v_mfma_f32_32x32x16_bf16 v[4:19], v[162:165], v[172:175], v[4:19]
	v_mfma_f32_32x32x16_bf16 v[68:83], v[168:171], v[172:175], v[68:83]
	v_mfma_f32_32x32x16_bf16 v[20:35], v[162:165], v[176:179], v[20:35]
	v_mfma_f32_32x32x16_bf16 v[84:99], v[168:171], v[176:179], v[84:99]
	v_mfma_f32_32x32x16_bf16 v[36:51], v[162:165], v[180:183], v[36:51]
	v_mfma_f32_32x32x16_bf16 v[100:115], v[168:171], v[180:183], v[100:115]
	v_mfma_f32_32x32x16_bf16 v[52:67], v[162:165], v[184:187], v[52:67]
	v_mfma_f32_32x32x16_bf16 v[116:131], v[168:171], v[184:187], v[116:131]
	ds_read_b128 v[162:165], v213 offset:0
	ds_read_b128 v[168:171], v213 offset:4096
	ds_read_b128 v[172:175], v217 offset:0
	ds_read_b128 v[176:179], v217 offset:4096
	ds_read_b128 v[180:183], v217 offset:16384
	ds_read_b128 v[184:187], v217 offset:20480
	s_waitcnt lgkmcnt(6)
	v_mfma_f32_32x32x16_bf16 v[4:19], v[132:135], v[140:143], v[4:19]
	v_mfma_f32_32x32x16_bf16 v[68:83], v[136:139], v[140:143], v[68:83]
	v_mfma_f32_32x32x16_bf16 v[20:35], v[132:135], v[144:147], v[20:35]
	v_mfma_f32_32x32x16_bf16 v[84:99], v[136:139], v[144:147], v[84:99]
	v_mfma_f32_32x32x16_bf16 v[36:51], v[132:135], v[148:151], v[36:51]
	v_mfma_f32_32x32x16_bf16 v[100:115], v[136:139], v[148:151], v[100:115]
	v_mfma_f32_32x32x16_bf16 v[52:67], v[132:135], v[158:161], v[52:67]
	v_mfma_f32_32x32x16_bf16 v[116:131], v[136:139], v[158:161], v[116:131]
	s_waitcnt lgkmcnt(0)
	v_mfma_f32_32x32x16_bf16 v[4:19], v[162:165], v[172:175], v[4:19]
	v_mfma_f32_32x32x16_bf16 v[68:83], v[168:171], v[172:175], v[68:83]
	v_mfma_f32_32x32x16_bf16 v[20:35], v[162:165], v[176:179], v[20:35]
	v_mfma_f32_32x32x16_bf16 v[84:99], v[168:171], v[176:179], v[84:99]
	v_mfma_f32_32x32x16_bf16 v[36:51], v[162:165], v[180:183], v[36:51]
	v_mfma_f32_32x32x16_bf16 v[100:115], v[168:171], v[180:183], v[100:115]
	v_mfma_f32_32x32x16_bf16 v[52:67], v[162:165], v[184:187], v[52:67]
	v_mfma_f32_32x32x16_bf16 v[116:131], v[168:171], v[184:187], v[116:131]
	s_waitcnt vmcnt(0) lgkmcnt(0)
	s_barrier
	ds_read_b128 v[132:135], v210 offset:32768
	ds_read_b128 v[136:139], v210 offset:36864
	ds_read_b128 v[140:143], v214 offset:32768
	ds_read_b128 v[144:147], v214 offset:36864
	ds_read_b128 v[148:151], v214 offset:49152
	ds_read_b128 v[158:161], v214 offset:53248
	ds_read_b128 v[162:165], v211 offset:32768
	ds_read_b128 v[168:171], v211 offset:36864
	ds_read_b128 v[172:175], v215 offset:32768
	ds_read_b128 v[176:179], v215 offset:36864
	ds_read_b128 v[180:183], v215 offset:49152
	ds_read_b128 v[184:187], v215 offset:53248
	s_waitcnt lgkmcnt(6)
	v_mfma_f32_32x32x16_bf16 v[4:19], v[132:135], v[140:143], v[4:19]
	v_mfma_f32_32x32x16_bf16 v[68:83], v[136:139], v[140:143], v[68:83]
	v_mfma_f32_32x32x16_bf16 v[20:35], v[132:135], v[144:147], v[20:35]
	v_mfma_f32_32x32x16_bf16 v[84:99], v[136:139], v[144:147], v[84:99]
	v_mfma_f32_32x32x16_bf16 v[36:51], v[132:135], v[148:151], v[36:51]
	v_mfma_f32_32x32x16_bf16 v[100:115], v[136:139], v[148:151], v[100:115]
	v_mfma_f32_32x32x16_bf16 v[52:67], v[132:135], v[158:161], v[52:67]
	v_mfma_f32_32x32x16_bf16 v[116:131], v[136:139], v[158:161], v[116:131]
	ds_read_b128 v[132:135], v212 offset:32768
	ds_read_b128 v[136:139], v212 offset:36864
	ds_read_b128 v[140:143], v216 offset:32768
	ds_read_b128 v[144:147], v216 offset:36864
	ds_read_b128 v[148:151], v216 offset:49152
	ds_read_b128 v[158:161], v216 offset:53248
	s_waitcnt lgkmcnt(6)
	v_mfma_f32_32x32x16_bf16 v[4:19], v[162:165], v[172:175], v[4:19]
	v_mfma_f32_32x32x16_bf16 v[68:83], v[168:171], v[172:175], v[68:83]
	v_mfma_f32_32x32x16_bf16 v[20:35], v[162:165], v[176:179], v[20:35]
	v_mfma_f32_32x32x16_bf16 v[84:99], v[168:171], v[176:179], v[84:99]
	v_mfma_f32_32x32x16_bf16 v[36:51], v[162:165], v[180:183], v[36:51]
	v_mfma_f32_32x32x16_bf16 v[100:115], v[168:171], v[180:183], v[100:115]
	v_mfma_f32_32x32x16_bf16 v[52:67], v[162:165], v[184:187], v[52:67]
	v_mfma_f32_32x32x16_bf16 v[116:131], v[168:171], v[184:187], v[116:131]
	ds_read_b128 v[162:165], v213 offset:32768
	ds_read_b128 v[168:171], v213 offset:36864
	ds_read_b128 v[172:175], v217 offset:32768
	ds_read_b128 v[176:179], v217 offset:36864
	ds_read_b128 v[180:183], v217 offset:49152
	ds_read_b128 v[184:187], v217 offset:53248
	s_waitcnt lgkmcnt(6)
	v_mfma_f32_32x32x16_bf16 v[4:19], v[132:135], v[140:143], v[4:19]
	v_mfma_f32_32x32x16_bf16 v[68:83], v[136:139], v[140:143], v[68:83]
	v_mfma_f32_32x32x16_bf16 v[20:35], v[132:135], v[144:147], v[20:35]
	v_mfma_f32_32x32x16_bf16 v[84:99], v[136:139], v[144:147], v[84:99]
	v_mfma_f32_32x32x16_bf16 v[36:51], v[132:135], v[148:151], v[36:51]
	v_mfma_f32_32x32x16_bf16 v[100:115], v[136:139], v[148:151], v[100:115]
	v_mfma_f32_32x32x16_bf16 v[52:67], v[132:135], v[158:161], v[52:67]
	v_mfma_f32_32x32x16_bf16 v[116:131], v[136:139], v[158:161], v[116:131]
	s_waitcnt lgkmcnt(0)
	v_mfma_f32_32x32x16_bf16 v[4:19], v[162:165], v[172:175], v[4:19]
	v_mfma_f32_32x32x16_bf16 v[68:83], v[168:171], v[172:175], v[68:83]
	v_mfma_f32_32x32x16_bf16 v[20:35], v[162:165], v[176:179], v[20:35]
	v_mfma_f32_32x32x16_bf16 v[84:99], v[168:171], v[176:179], v[84:99]
	v_mfma_f32_32x32x16_bf16 v[36:51], v[162:165], v[180:183], v[36:51]
	v_mfma_f32_32x32x16_bf16 v[100:115], v[168:171], v[180:183], v[100:115]
	v_mfma_f32_32x32x16_bf16 v[52:67], v[162:165], v[184:187], v[52:67]
	v_mfma_f32_32x32x16_bf16 v[116:131], v[168:171], v[184:187], v[116:131]
	s_waitcnt lgkmcnt(0)
	s_barrier
; DI unsigned pk2(float a, float b) { f32x2 v = {a, b}; return __builtin_bit_cast(unsigned, __builtin_convertvector(v, bf2_t)); }
; DI void store_transposed(u16* dst, const f32x16& a, int h, const float* rs  ) {
; #pragma unroll
;   for (int g = 0; g < 4; ++g) {
;     float s0 = 1.f, s1 = 1.f, s2 = 1.f, s3 = 1.f;
;     if (rs) { f32x4 sv = *(const f32x4*)(rs + 8 * g + 4 * h); s0 = sv[0]; s1 = sv[1]; s2 = sv[2]; s3 = sv[3]; }
;     u32x2 v = {pk2(a[4 * g] * s0, a[4 * g + 1] * s1), pk2(a[4 * g + 2] * s2, a[4 * g + 3] * s3)};
;     *(u32x2*)(dst + 8 * g + 4 * h) = v;
;   }
; DI void inproj_tile(const Params& p, int l, int mt, int nt, char* lds) {
;     ...
;   } else {
;     u16* vt; int nv, c0;
;     if (nt < 47) { vt = p.VtA; nv = 512; c0 = (nt - 43) * 128; } else { vt = p.VtD; nv = 128; c0 = 0; }
;     gemm_tile<false>(A, DM, Bw, DM, DM, lds, [&](int mi, int ni, const f32x16& a) {
;       const int b = m0 / PP, t0 = m0 - b * PP + wm * 64 + mi * 32;
;       const int col = c0 + wn * 64 + ni * 32 + r;
;       store_transposed(vt + ((size_t)b * nv + col) * PP + t0, a, h, nullptr);
;     });
	s_nop 7
	s_nop 7
	v_cvt_pk_bf16_f32 v224, v4, v5
	v_cvt_pk_bf16_f32 v225, v6, v7
	global_store_dwordx2 v218, v[224:225], s[8:9]
	v_cvt_pk_bf16_f32 v228, v8, v9
	v_cvt_pk_bf16_f32 v229, v10, v11
	global_store_dwordx2 v218, v[228:229], s[8:9] offset:16
	v_cvt_pk_bf16_f32 v224, v12, v13
	v_cvt_pk_bf16_f32 v225, v14, v15
	global_store_dwordx2 v218, v[224:225], s[8:9] offset:32
	v_cvt_pk_bf16_f32 v228, v16, v17
	v_cvt_pk_bf16_f32 v229, v18, v19
	global_store_dwordx2 v218, v[228:229], s[8:9] offset:48
	v_cvt_pk_bf16_f32 v224, v68, v69
	v_cvt_pk_bf16_f32 v225, v70, v71
	global_store_dwordx2 v218, v[224:225], s[8:9] offset:64
	v_cvt_pk_bf16_f32 v228, v72, v73
	v_cvt_pk_bf16_f32 v229, v74, v75
	global_store_dwordx2 v218, v[228:229], s[8:9] offset:80
	v_cvt_pk_bf16_f32 v224, v76, v77
	v_cvt_pk_bf16_f32 v225, v78, v79
	global_store_dwordx2 v218, v[224:225], s[8:9] offset:96
	v_cvt_pk_bf16_f32 v228, v80, v81
	v_cvt_pk_bf16_f32 v229, v82, v83
	global_store_dwordx2 v218, v[228:229], s[8:9] offset:112
	v_cvt_pk_bf16_f32 v224, v20, v21
	v_cvt_pk_bf16_f32 v225, v22, v23
	global_store_dwordx2 v219, v[224:225], s[8:9]
	v_cvt_pk_bf16_f32 v228, v24, v25
	v_cvt_pk_bf16_f32 v229, v26, v27
	global_store_dwordx2 v219, v[228:229], s[8:9] offset:16
	v_cvt_pk_bf16_f32 v224, v28, v29
	v_cvt_pk_bf16_f32 v225, v30, v31
	global_store_dwordx2 v219, v[224:225], s[8:9] offset:32
	v_cvt_pk_bf16_f32 v228, v32, v33
	v_cvt_pk_bf16_f32 v229, v34, v35
	global_store_dwordx2 v219, v[228:229], s[8:9] offset:48
	v_cvt_pk_bf16_f32 v224, v84, v85
	v_cvt_pk_bf16_f32 v225, v86, v87
	global_store_dwordx2 v219, v[224:225], s[8:9] offset:64
	v_cvt_pk_bf16_f32 v228, v88, v89
	v_cvt_pk_bf16_f32 v229, v90, v91
	global_store_dwordx2 v219, v[228:229], s[8:9] offset:80
	v_cvt_pk_bf16_f32 v224, v92, v93
	v_cvt_pk_bf16_f32 v225, v94, v95
	global_store_dwordx2 v219, v[224:225], s[8:9] offset:96
	v_cvt_pk_bf16_f32 v228, v96, v97
	v_cvt_pk_bf16_f32 v229, v98, v99
	global_store_dwordx2 v219, v[228:229], s[8:9] offset:112
	v_cvt_pk_bf16_f32 v224, v36, v37
	v_cvt_pk_bf16_f32 v225, v38, v39
	global_store_dwordx2 v220, v[224:225], s[8:9]
	v_cvt_pk_bf16_f32 v228, v40, v41
	v_cvt_pk_bf16_f32 v229, v42, v43
	global_store_dwordx2 v220, v[228:229], s[8:9] offset:16
	v_cvt_pk_bf16_f32 v224, v44, v45
	v_cvt_pk_bf16_f32 v225, v46, v47
	global_store_dwordx2 v220, v[224:225], s[8:9] offset:32
	v_cvt_pk_bf16_f32 v228, v48, v49
	v_cvt_pk_bf16_f32 v229, v50, v51
	global_store_dwordx2 v220, v[228:229], s[8:9] offset:48
	v_cvt_pk_bf16_f32 v224, v100, v101
	v_cvt_pk_bf16_f32 v225, v102, v103
	global_store_dwordx2 v220, v[224:225], s[8:9] offset:64
	v_cvt_pk_bf16_f32 v228, v104, v105
	v_cvt_pk_bf16_f32 v229, v106, v107
	global_store_dwordx2 v220, v[228:229], s[8:9] offset:80
	v_cvt_pk_bf16_f32 v224, v108, v109
	v_cvt_pk_bf16_f32 v225, v110, v111
	global_store_dwordx2 v220, v[224:225], s[8:9] offset:96
	v_cvt_pk_bf16_f32 v228, v112, v113
	v_cvt_pk_bf16_f32 v229, v114, v115
	global_store_dwordx2 v220, v[228:229], s[8:9] offset:112
	v_cvt_pk_bf16_f32 v224, v52, v53
	v_cvt_pk_bf16_f32 v225, v54, v55
	global_store_dwordx2 v221, v[224:225], s[8:9]
	v_cvt_pk_bf16_f32 v228, v56, v57
	v_cvt_pk_bf16_f32 v229, v58, v59
	global_store_dwordx2 v221, v[228:229], s[8:9] offset:16
	v_cvt_pk_bf16_f32 v224, v60, v61
	v_cvt_pk_bf16_f32 v225, v62, v63
	global_store_dwordx2 v221, v[224:225], s[8:9] offset:32
	v_cvt_pk_bf16_f32 v228, v64, v65
	v_cvt_pk_bf16_f32 v229, v66, v67
	global_store_dwordx2 v221, v[228:229], s[8:9] offset:48
	v_cvt_pk_bf16_f32 v224, v116, v117
	v_cvt_pk_bf16_f32 v225, v118, v119
	global_store_dwordx2 v221, v[224:225], s[8:9] offset:64
	v_cvt_pk_bf16_f32 v228, v120, v121
	v_cvt_pk_bf16_f32 v229, v122, v123
	global_store_dwordx2 v221, v[228:229], s[8:9] offset:80
	v_cvt_pk_bf16_f32 v224, v124, v125
	v_cvt_pk_bf16_f32 v225, v126, v127
	global_store_dwordx2 v221, v[224:225], s[8:9] offset:96
	v_cvt_pk_bf16_f32 v228, v128, v129
	v_cvt_pk_bf16_f32 v229, v130, v131
	global_store_dwordx2 v221, v[228:229], s[8:9] offset:112
.Lpp_next:
	s_addk_i32 s101, 0x20
	s_branch .Lpp_loop
.Lpp_done:
	v_readlane_b32 s25, v238, 16
	s_and_b32 s0, s25, 7
	s_lshr_b32 s25, s25, 3
	s_cmp_gt_u32 s0, 6
	s_cbranch_scc1 .Lsg_go
	s_cmp_lt_u32 s25, 6
	s_cbranch_scc1 .LBB0_370
	s_cmp_gt_u32 s25, 11
	s_cbranch_scc1 .LBB0_370

; DI void inproj_tile(const Params& p, int l, int mt, int nt, char* lds) {
;     ...
;   } else {
;     u16* vt; int nv, c0;
;     if (nt < 47) { vt = p.VtA; nv = 512; c0 = (nt - 43) * 128; } else { vt = p.VtD; nv = 128; c0 = 0; }
;     gemm_tile<false>(A, DM, Bw, DM, DM, lds, [&](int mi, int ni, const f32x16& a) {
;       const int b = m0 / PP, t0 = m0 - b * PP + wm * 64 + mi * 32;
;       const int col = c0 + wn * 64 + ni * 32 + r;
;       store_transposed(vt + ((size_t)b * nv + col) * PP + t0, a, h, nullptr);
;     });
; __global__ void __launch_bounds__(NTHREADS) mega(Params p) {
;     ...
;       for (int j = blockIdx.x; j < 66 * 48; j += gridDim.x) inproj_tile(p, l, j / 48, j % 48, lds);
.LBB0_323:
	s_mov_b32 s25, s101
	v_readlane_b32 s0, v238, 18
	s_add_i32 s25, s25, 32
	s_add_i32 s24, s24, s0
	s_add_i32 s23, s23, s22
	v_readlane_b32 s0, v238, 16
	s_and_b32 s0, s0, 7
	s_movk_i32 s1, 354
	s_cmp_lt_u32 s0, 7
	s_cselect_b32 s0, 12, s1
	s_cmp_ge_u32 s25, s0
	s_cbranch_scc1 .LBB0_370
.LBB0_324:
	s_mov_b32 s101, s25
	v_readlane_b32 s0, v238, 16
	s_and_b32 s0, s0, 7
	s_lshr_b32 s1, s25, 2
	s_and_b32 s2, s25, 3
	s_add_i32 s2, s2, 4
	s_cmp_lt_u32 s0, 7
	s_cbranch_scc0 .Lsg_7
	s_mul_i32 s1, s0, 6
	s_add_i32 s1, s1, s25
	s_add_i32 s1, s1, 18
	s_movk_i32 s2, 47
	s_branch .Lsg_map
.Lsg_7:
	s_cmpk_lt_u32 s25, 0x108
	s_cbranch_scc1 .Lsg_map
	s_sub_i32 s1, s25, 0x108
	s_movk_i32 s2, 42
	s_cmpk_lt_u32 s25, 0x14a
	s_cbranch_scc1 .Lsg_map
	s_sub_i32 s1, s25, 0x14a
	s_movk_i32 s2, 47
